# v16 with the weight-converter bf16 stores issued sc1 (write-through, line dropped from the XCD L2) instead of nt, to keep the converter's output out of the L2 the GEMM staging loads rely on
# speedup vs baseline: 1.0062x; 1.0062x over previous
; #define LAS __attribute__((address_space(3)))
; __device__ __forceinline__ unsigned cvt_pk_bf16(float lo, float hi) { unsigned r; asm volatile("v_cvt_pk_bf16_f32 %0, %1, %2" : "=v"(r) : "v"(lo), "v"(hi)); return r; }
; #define LDS_WAIT() asm volatile("s_waitcnt lgkmcnt(0)" ::: "memory")
; __device__ __forceinline__ unsigned cvt_pk_bf16(float lo, float hi) { unsigned r; asm volatile("v_cvt_pk_bf16_f32 %0, %1, %2" : "=v"(r) : "v"(lo), "v"(hi)); return r; }
; template <bool NT = true> __device__ __forceinline__ void tr_load(const TrDesc& d, f32x4 (&v)[8], int lane) {
;     const float* sp = d.src + (size_t)(lane >> 3) * d.ldn + 4 * (lane & 7);
; #pragma unroll
;     for (int i = 0; i < 8; ++i) v[i] = NT ? __builtin_nontemporal_load((const f32x4*)(sp + (size_t)(8 * i) * d.ldn)) : *(const f32x4*)(sp + (size_t)(8 * i) * d.ldn);
; }
; template <bool NT = true> __device__ __forceinline__ void tr_finish(const TrDesc& d, const f32x4 (&v)[8], LAS float* scr, int lane) {
;     const int c = lane & 7;
;     f32x4 g0 = {1.f, 1.f, 1.f, 1.f}, g1 = {1.f, 1.f, 1.f, 1.f};
;     if (d.gain) { g0 = *(const f32x4*)(d.gain + 8 * c); g1 = *(const f32x4*)(d.gain + 8 * c + 4); }
; #pragma unroll
;     for (int i = 0; i < 8; ++i) { LAS float* w = scr + (8 * i + (lane >> 3)) * 33 + 4 * c; w[0] = v[i].x; w[1] = v[i].y; w[2] = v[i].z; w[3] = v[i].w; }
;     LDS_WAIT(); asm volatile("" ::: "memory");
; #pragma unroll
;     for (int j = 0; j < 4; ++j) { const int n = (lane >> 3) + 8 * j; const LAS float* s = scr + (8 * c) * 33 + n;
;         u32x4 o; o.x = cvt_pk_bf16(s[0 * 33] * g0.x, s[1 * 33] * g0.y); o.y = cvt_pk_bf16(s[2 * 33] * g0.z, s[3 * 33] * g0.w); o.z = cvt_pk_bf16(s[4 * 33] * g1.x, s[5 * 33] * g1.y); o.w = cvt_pk_bf16(s[6 * 33] * g1.z, s[7 * 33] * g1.w);
;         if (NT) __builtin_nontemporal_store(o, (u32x4*)(d.dst + (size_t)n * d.K + 8 * c)); else *(u32x4*)(d.dst + (size_t)n * d.K + 8 * c) = o; }
.Lpz_run:
	s_cmp_eq_u32 s74, 0
	s_cbranch_scc1 .Lpz_ret
	v_mul_lo_u32 v229, v238, s78
	v_lshlrev_b32_e32 v229, 3, v229
	v_lshl_add_u32 v2, v239, 4, v229
	v_add_u32_e32 v120, s78, v2
	v_add_u32_e32 v121, s78, v120
	v_add_u32_e32 v126, s78, v121
	v_add_u32_e32 v144, s78, v126
	v_add_u32_e32 v145, s78, v144
	v_add_u32_e32 v147, s78, v145
	v_add_u32_e32 v165, s78, v147
	v_lshlrev_b32_e32 v230, 2, v239
	v_mul_lo_u32 v230, v230, s79
	v_lshl_add_u32 v214, v238, 4, v230
	v_add_u32_e32 v215, s79, v214
	v_add_u32_e32 v219, s79, v215
	v_add_u32_e32 v236, s79, v219
	s_cmp_eq_u32 s80, 0
	s_cbranch_scc1 .Lpz_nogain
	global_load_dwordx4 v[220:223], v237, s[76:77]
	global_load_dwordx4 v[224:227], v237, s[76:77] offset:16
	global_load_dwordx4 v[6:9], v2, s[60:61] offset:0 nt
	global_load_dwordx4 v[10:13], v120, s[60:61] offset:0 nt
	global_load_dwordx4 v[14:17], v121, s[60:61] offset:0 nt
	global_load_dwordx4 v[18:21], v126, s[60:61] offset:0 nt
	global_load_dwordx4 v[22:25], v144, s[60:61] offset:0 nt
	global_load_dwordx4 v[26:29], v145, s[60:61] offset:0 nt
	global_load_dwordx4 v[30:33], v147, s[60:61] offset:0 nt
	global_load_dwordx4 v[66:69], v165, s[60:61] offset:0 nt
	global_load_dwordx4 v[100:103], v2, s[60:61] offset:128 nt
	global_load_dwordx4 v[104:107], v120, s[60:61] offset:128 nt
	global_load_dwordx4 v[108:111], v121, s[60:61] offset:128 nt
	global_load_dwordx4 v[112:115], v126, s[60:61] offset:128 nt
	global_load_dwordx4 v[116:119], v144, s[60:61] offset:128 nt
	global_load_dwordx4 v[132:135], v145, s[60:61] offset:128 nt
	global_load_dwordx4 v[136:139], v147, s[60:61] offset:128 nt
	global_load_dwordx4 v[140:143], v165, s[60:61] offset:128 nt
	global_load_dwordx4 v[148:151], v2, s[60:61] offset:256 nt
	global_load_dwordx4 v[152:155], v120, s[60:61] offset:256 nt
	global_load_dwordx4 v[156:159], v121, s[60:61] offset:256 nt
	global_load_dwordx4 v[160:163], v126, s[60:61] offset:256 nt
	global_load_dwordx4 v[166:169], v144, s[60:61] offset:256 nt
	global_load_dwordx4 v[170:173], v145, s[60:61] offset:256 nt
	global_load_dwordx4 v[174:177], v147, s[60:61] offset:256 nt
	global_load_dwordx4 v[178:181], v165, s[60:61] offset:256 nt
	global_load_dwordx4 v[182:185], v2, s[60:61] offset:384 nt
	global_load_dwordx4 v[186:189], v120, s[60:61] offset:384 nt
	global_load_dwordx4 v[190:193], v121, s[60:61] offset:384 nt
	global_load_dwordx4 v[194:197], v126, s[60:61] offset:384 nt
	global_load_dwordx4 v[198:201], v144, s[60:61] offset:384 nt
	global_load_dwordx4 v[202:205], v145, s[60:61] offset:384 nt
	global_load_dwordx4 v[206:209], v147, s[60:61] offset:384 nt
	global_load_dwordx4 v[210:213], v165, s[60:61] offset:384 nt
	s_add_u32 s60, s60, s70
	s_addc_u32 s61, s61, s71
	s_cmp_eq_u32 s74, 1
	s_cbranch_scc1 .Lpz_g_last
	s_waitcnt vmcnt(24)
	v_mul_f32_e32 v6, v220, v6
	v_mul_f32_e32 v7, v220, v7
	v_mul_f32_e32 v8, v220, v8
	v_mul_f32_e32 v9, v220, v9
	v_mul_f32_e32 v10, v221, v10
	v_mul_f32_e32 v11, v221, v11
	v_mul_f32_e32 v12, v221, v12
	v_mul_f32_e32 v13, v221, v13
	v_mul_f32_e32 v14, v222, v14
	v_mul_f32_e32 v15, v222, v15
	v_mul_f32_e32 v16, v222, v16
	v_mul_f32_e32 v17, v222, v17
	v_mul_f32_e32 v18, v223, v18
	v_mul_f32_e32 v19, v223, v19
	v_mul_f32_e32 v20, v223, v20
	v_mul_f32_e32 v21, v223, v21
	v_mul_f32_e32 v22, v224, v22
	v_mul_f32_e32 v23, v224, v23
	v_mul_f32_e32 v24, v224, v24
	v_mul_f32_e32 v25, v224, v25
	v_mul_f32_e32 v26, v225, v26
	v_mul_f32_e32 v27, v225, v27
	v_mul_f32_e32 v28, v225, v28
	v_mul_f32_e32 v29, v225, v29
	v_mul_f32_e32 v30, v226, v30
	v_mul_f32_e32 v31, v226, v31
	v_mul_f32_e32 v32, v226, v32
	v_mul_f32_e32 v33, v226, v33
	v_mul_f32_e32 v66, v227, v66
	v_mul_f32_e32 v67, v227, v67
	v_mul_f32_e32 v68, v227, v68
	v_mul_f32_e32 v69, v227, v69
	v_cvt_pk_bf16_f32 v228, v6, v10
	v_cvt_pk_bf16_f32 v229, v14, v18
	v_cvt_pk_bf16_f32 v230, v22, v26
	v_cvt_pk_bf16_f32 v231, v30, v66
	global_store_dwordx4 v214, v[228:231], s[62:63] sc1
	v_cvt_pk_bf16_f32 v232, v7, v11
	v_cvt_pk_bf16_f32 v233, v15, v19
	v_cvt_pk_bf16_f32 v234, v23, v27
	v_cvt_pk_bf16_f32 v235, v31, v67
	global_store_dwordx4 v215, v[232:235], s[62:63] sc1
	v_cvt_pk_bf16_f32 v228, v8, v12
	v_cvt_pk_bf16_f32 v229, v16, v20
	v_cvt_pk_bf16_f32 v230, v24, v28
	v_cvt_pk_bf16_f32 v231, v32, v68
	global_store_dwordx4 v219, v[228:231], s[62:63] sc1
	v_cvt_pk_bf16_f32 v232, v9, v13
	v_cvt_pk_bf16_f32 v233, v17, v21
	v_cvt_pk_bf16_f32 v234, v25, v29
	v_cvt_pk_bf16_f32 v235, v33, v69
	global_store_dwordx4 v236, v[232:235], s[62:63] sc1
	global_load_dwordx4 v[6:9], v2, s[60:61] offset:0 nt
	global_load_dwordx4 v[10:13], v120, s[60:61] offset:0 nt
	global_load_dwordx4 v[14:17], v121, s[60:61] offset:0 nt
	global_load_dwordx4 v[18:21], v126, s[60:61] offset:0 nt
	global_load_dwordx4 v[22:25], v144, s[60:61] offset:0 nt
	global_load_dwordx4 v[26:29], v145, s[60:61] offset:0 nt
	global_load_dwordx4 v[30:33], v147, s[60:61] offset:0 nt
	global_load_dwordx4 v[66:69], v165, s[60:61] offset:0 nt
	s_add_u32 s62, s62, s72
	s_addc_u32 s63, s63, s73
	s_waitcnt vmcnt(28)
; #define LAS __attribute__((address_space(3)))
; __device__ __forceinline__ unsigned cvt_pk_bf16(float lo, float hi) { unsigned r; asm volatile("v_cvt_pk_bf16_f32 %0, %1, %2" : "=v"(r) : "v"(lo), "v"(hi)); return r; }
; #define LDS_WAIT() asm volatile("s_waitcnt lgkmcnt(0)" ::: "memory")
; __device__ __forceinline__ unsigned cvt_pk_bf16(float lo, float hi) { unsigned r; asm volatile("v_cvt_pk_bf16_f32 %0, %1, %2" : "=v"(r) : "v"(lo), "v"(hi)); return r; }
; template <bool NT = true> __device__ __forceinline__ void tr_finish(const TrDesc& d, const f32x4 (&v)[8], LAS float* scr, int lane) {
;     const int c = lane & 7;
;     f32x4 g0 = {1.f, 1.f, 1.f, 1.f}, g1 = {1.f, 1.f, 1.f, 1.f};
;     if (d.gain) { g0 = *(const f32x4*)(d.gain + 8 * c); g1 = *(const f32x4*)(d.gain + 8 * c + 4); }
; #pragma unroll
;     for (int i = 0; i < 8; ++i) { LAS float* w = scr + (8 * i + (lane >> 3)) * 33 + 4 * c; w[0] = v[i].x; w[1] = v[i].y; w[2] = v[i].z; w[3] = v[i].w; }
;     LDS_WAIT(); asm volatile("" ::: "memory");
; #pragma unroll
;     for (int j = 0; j < 4; ++j) { const int n = (lane >> 3) + 8 * j; const LAS float* s = scr + (8 * c) * 33 + n;
;         u32x4 o; o.x = cvt_pk_bf16(s[0 * 33] * g0.x, s[1 * 33] * g0.y); o.y = cvt_pk_bf16(s[2 * 33] * g0.z, s[3 * 33] * g0.w); o.z = cvt_pk_bf16(s[4 * 33] * g1.x, s[5 * 33] * g1.y); o.w = cvt_pk_bf16(s[6 * 33] * g1.z, s[7 * 33] * g1.w);
;         if (NT) __builtin_nontemporal_store(o, (u32x4*)(d.dst + (size_t)n * d.K + 8 * c)); else *(u32x4*)(d.dst + (size_t)n * d.K + 8 * c) = o; }
	v_mul_f32_e32 v100, v220, v100
	v_mul_f32_e32 v101, v220, v101
	v_mul_f32_e32 v102, v220, v102
	v_mul_f32_e32 v103, v220, v103
	v_mul_f32_e32 v104, v221, v104
	v_mul_f32_e32 v105, v221, v105
	v_mul_f32_e32 v106, v221, v106
	v_mul_f32_e32 v107, v221, v107
	v_mul_f32_e32 v108, v222, v108
	v_mul_f32_e32 v109, v222, v109
	v_mul_f32_e32 v110, v222, v110
	v_mul_f32_e32 v111, v222, v111
	v_mul_f32_e32 v112, v223, v112
	v_mul_f32_e32 v113, v223, v113
	v_mul_f32_e32 v114, v223, v114
	v_mul_f32_e32 v115, v223, v115
	v_mul_f32_e32 v116, v224, v116
	v_mul_f32_e32 v117, v224, v117
	v_mul_f32_e32 v118, v224, v118
	v_mul_f32_e32 v119, v224, v119
	v_mul_f32_e32 v132, v225, v132
	v_mul_f32_e32 v133, v225, v133
	v_mul_f32_e32 v134, v225, v134
	v_mul_f32_e32 v135, v225, v135
	v_mul_f32_e32 v136, v226, v136
	v_mul_f32_e32 v137, v226, v137
	v_mul_f32_e32 v138, v226, v138
	v_mul_f32_e32 v139, v226, v139
	v_mul_f32_e32 v140, v227, v140
	v_mul_f32_e32 v141, v227, v141
	v_mul_f32_e32 v142, v227, v142
	v_mul_f32_e32 v143, v227, v143
	v_cvt_pk_bf16_f32 v228, v100, v104
	v_cvt_pk_bf16_f32 v229, v108, v112
	v_cvt_pk_bf16_f32 v230, v116, v132
	v_cvt_pk_bf16_f32 v231, v136, v140
	global_store_dwordx4 v214, v[228:231], s[64:65] sc1
	v_cvt_pk_bf16_f32 v232, v101, v105
	v_cvt_pk_bf16_f32 v233, v109, v113
	v_cvt_pk_bf16_f32 v234, v117, v133
	v_cvt_pk_bf16_f32 v235, v137, v141
	global_store_dwordx4 v215, v[232:235], s[64:65] sc1
	v_cvt_pk_bf16_f32 v228, v102, v106
	v_cvt_pk_bf16_f32 v229, v110, v114
	v_cvt_pk_bf16_f32 v230, v118, v134
	v_cvt_pk_bf16_f32 v231, v138, v142
	global_store_dwordx4 v219, v[228:231], s[64:65] sc1
	v_cvt_pk_bf16_f32 v232, v103, v107
	v_cvt_pk_bf16_f32 v233, v111, v115
	v_cvt_pk_bf16_f32 v234, v119, v135
	v_cvt_pk_bf16_f32 v235, v139, v143
	global_store_dwordx4 v236, v[232:235], s[64:65] sc1
	global_load_dwordx4 v[100:103], v2, s[60:61] offset:128 nt
	global_load_dwordx4 v[104:107], v120, s[60:61] offset:128 nt
	global_load_dwordx4 v[108:111], v121, s[60:61] offset:128 nt
	global_load_dwordx4 v[112:115], v126, s[60:61] offset:128 nt
	global_load_dwordx4 v[116:119], v144, s[60:61] offset:128 nt
	global_load_dwordx4 v[132:135], v145, s[60:61] offset:128 nt
	global_load_dwordx4 v[136:139], v147, s[60:61] offset:128 nt
	global_load_dwordx4 v[140:143], v165, s[60:61] offset:128 nt
	s_add_u32 s64, s64, s72
	s_addc_u32 s65, s65, s73
	s_waitcnt vmcnt(32)
	v_mul_f32_e32 v148, v220, v148
	v_mul_f32_e32 v149, v220, v149
	v_mul_f32_e32 v150, v220, v150
	v_mul_f32_e32 v151, v220, v151
	v_mul_f32_e32 v152, v221, v152
	v_mul_f32_e32 v153, v221, v153
	v_mul_f32_e32 v154, v221, v154
	v_mul_f32_e32 v155, v221, v155
	v_mul_f32_e32 v156, v222, v156
	v_mul_f32_e32 v157, v222, v157
	v_mul_f32_e32 v158, v222, v158
	v_mul_f32_e32 v159, v222, v159
	v_mul_f32_e32 v160, v223, v160
	v_mul_f32_e32 v161, v223, v161
	v_mul_f32_e32 v162, v223, v162
	v_mul_f32_e32 v163, v223, v163
	v_mul_f32_e32 v166, v224, v166
	v_mul_f32_e32 v167, v224, v167
	v_mul_f32_e32 v168, v224, v168
	v_mul_f32_e32 v169, v224, v169
	v_mul_f32_e32 v170, v225, v170
	v_mul_f32_e32 v171, v225, v171
	v_mul_f32_e32 v172, v225, v172
	v_mul_f32_e32 v173, v225, v173
	v_mul_f32_e32 v174, v226, v174
	v_mul_f32_e32 v175, v226, v175
	v_mul_f32_e32 v176, v226, v176
	v_mul_f32_e32 v177, v226, v177
	v_mul_f32_e32 v178, v227, v178
	v_mul_f32_e32 v179, v227, v179
	v_mul_f32_e32 v180, v227, v180
	v_mul_f32_e32 v181, v227, v181
	v_cvt_pk_bf16_f32 v228, v148, v152
	v_cvt_pk_bf16_f32 v229, v156, v160
	v_cvt_pk_bf16_f32 v230, v166, v170
	v_cvt_pk_bf16_f32 v231, v174, v178
	global_store_dwordx4 v214, v[228:231], s[66:67] sc1
	v_cvt_pk_bf16_f32 v232, v149, v153
	v_cvt_pk_bf16_f32 v233, v157, v161
	v_cvt_pk_bf16_f32 v234, v167, v171
	v_cvt_pk_bf16_f32 v235, v175, v179
	global_store_dwordx4 v215, v[232:235], s[66:67] sc1
	v_cvt_pk_bf16_f32 v228, v150, v154
	v_cvt_pk_bf16_f32 v229, v158, v162
	v_cvt_pk_bf16_f32 v230, v168, v172
	v_cvt_pk_bf16_f32 v231, v176, v180
	global_store_dwordx4 v219, v[228:231], s[66:67] sc1
	v_cvt_pk_bf16_f32 v232, v151, v155
	v_cvt_pk_bf16_f32 v233, v159, v163
	v_cvt_pk_bf16_f32 v234, v169, v173
	v_cvt_pk_bf16_f32 v235, v177, v181
	global_store_dwordx4 v236, v[232:235], s[66:67] sc1
	global_load_dwordx4 v[148:151], v2, s[60:61] offset:256 nt
	global_load_dwordx4 v[152:155], v120, s[60:61] offset:256 nt
	global_load_dwordx4 v[156:159], v121, s[60:61] offset:256 nt
	global_load_dwordx4 v[160:163], v126, s[60:61] offset:256 nt
	global_load_dwordx4 v[166:169], v144, s[60:61] offset:256 nt
	global_load_dwordx4 v[170:173], v145, s[60:61] offset:256 nt
	global_load_dwordx4 v[174:177], v147, s[60:61] offset:256 nt
	global_load_dwordx4 v[178:181], v165, s[60:61] offset:256 nt
	s_add_u32 s66, s66, s72
	s_addc_u32 s67, s67, s73
	s_waitcnt vmcnt(36)
; #define LAS __attribute__((address_space(3)))
; __device__ __forceinline__ unsigned cvt_pk_bf16(float lo, float hi) { unsigned r; asm volatile("v_cvt_pk_bf16_f32 %0, %1, %2" : "=v"(r) : "v"(lo), "v"(hi)); return r; }
; #define LDS_WAIT() asm volatile("s_waitcnt lgkmcnt(0)" ::: "memory")
; __device__ __forceinline__ unsigned cvt_pk_bf16(float lo, float hi) { unsigned r; asm volatile("v_cvt_pk_bf16_f32 %0, %1, %2" : "=v"(r) : "v"(lo), "v"(hi)); return r; }
; template <bool NT = true> __device__ __forceinline__ void tr_finish(const TrDesc& d, const f32x4 (&v)[8], LAS float* scr, int lane) {
;     const int c = lane & 7;
;     f32x4 g0 = {1.f, 1.f, 1.f, 1.f}, g1 = {1.f, 1.f, 1.f, 1.f};
;     if (d.gain) { g0 = *(const f32x4*)(d.gain + 8 * c); g1 = *(const f32x4*)(d.gain + 8 * c + 4); }
; #pragma unroll
;     for (int i = 0; i < 8; ++i) { LAS float* w = scr + (8 * i + (lane >> 3)) * 33 + 4 * c; w[0] = v[i].x; w[1] = v[i].y; w[2] = v[i].z; w[3] = v[i].w; }
;     LDS_WAIT(); asm volatile("" ::: "memory");
; #pragma unroll
;     for (int j = 0; j < 4; ++j) { const int n = (lane >> 3) + 8 * j; const LAS float* s = scr + (8 * c) * 33 + n;
;         u32x4 o; o.x = cvt_pk_bf16(s[0 * 33] * g0.x, s[1 * 33] * g0.y); o.y = cvt_pk_bf16(s[2 * 33] * g0.z, s[3 * 33] * g0.w); o.z = cvt_pk_bf16(s[4 * 33] * g1.x, s[5 * 33] * g1.y); o.w = cvt_pk_bf16(s[6 * 33] * g1.z, s[7 * 33] * g1.w);
;         if (NT) __builtin_nontemporal_store(o, (u32x4*)(d.dst + (size_t)n * d.K + 8 * c)); else *(u32x4*)(d.dst + (size_t)n * d.K + 8 * c) = o; }
	v_mul_f32_e32 v182, v220, v182
	v_mul_f32_e32 v183, v220, v183
	v_mul_f32_e32 v184, v220, v184
	v_mul_f32_e32 v185, v220, v185
	v_mul_f32_e32 v186, v221, v186
	v_mul_f32_e32 v187, v221, v187
	v_mul_f32_e32 v188, v221, v188
	v_mul_f32_e32 v189, v221, v189
	v_mul_f32_e32 v190, v222, v190
	v_mul_f32_e32 v191, v222, v191
	v_mul_f32_e32 v192, v222, v192
	v_mul_f32_e32 v193, v222, v193
	v_mul_f32_e32 v194, v223, v194
	v_mul_f32_e32 v195, v223, v195
	v_mul_f32_e32 v196, v223, v196
	v_mul_f32_e32 v197, v223, v197
	v_mul_f32_e32 v198, v224, v198
	v_mul_f32_e32 v199, v224, v199
	v_mul_f32_e32 v200, v224, v200
	v_mul_f32_e32 v201, v224, v201
	v_mul_f32_e32 v202, v225, v202
	v_mul_f32_e32 v203, v225, v203
	v_mul_f32_e32 v204, v225, v204
	v_mul_f32_e32 v205, v225, v205
	v_mul_f32_e32 v206, v226, v206
	v_mul_f32_e32 v207, v226, v207
	v_mul_f32_e32 v208, v226, v208
	v_mul_f32_e32 v209, v226, v209
	v_mul_f32_e32 v210, v227, v210
	v_mul_f32_e32 v211, v227, v211
	v_mul_f32_e32 v212, v227, v212
	v_mul_f32_e32 v213, v227, v213
	v_cvt_pk_bf16_f32 v228, v182, v186
	v_cvt_pk_bf16_f32 v229, v190, v194
	v_cvt_pk_bf16_f32 v230, v198, v202
	v_cvt_pk_bf16_f32 v231, v206, v210
	global_store_dwordx4 v214, v[228:231], s[68:69] sc1
	v_cvt_pk_bf16_f32 v232, v183, v187
	v_cvt_pk_bf16_f32 v233, v191, v195
	v_cvt_pk_bf16_f32 v234, v199, v203
	v_cvt_pk_bf16_f32 v235, v207, v211
	global_store_dwordx4 v215, v[232:235], s[68:69] sc1
	v_cvt_pk_bf16_f32 v228, v184, v188
	v_cvt_pk_bf16_f32 v229, v192, v196
	v_cvt_pk_bf16_f32 v230, v200, v204
	v_cvt_pk_bf16_f32 v231, v208, v212
	global_store_dwordx4 v219, v[228:231], s[68:69] sc1
	v_cvt_pk_bf16_f32 v232, v185, v189
	v_cvt_pk_bf16_f32 v233, v193, v197
	v_cvt_pk_bf16_f32 v234, v201, v205
	v_cvt_pk_bf16_f32 v235, v209, v213
	global_store_dwordx4 v236, v[232:235], s[68:69] sc1
	global_load_dwordx4 v[182:185], v2, s[60:61] offset:384 nt
	global_load_dwordx4 v[186:189], v120, s[60:61] offset:384 nt
	global_load_dwordx4 v[190:193], v121, s[60:61] offset:384 nt
	global_load_dwordx4 v[194:197], v126, s[60:61] offset:384 nt
	global_load_dwordx4 v[198:201], v144, s[60:61] offset:384 nt
	global_load_dwordx4 v[202:205], v145, s[60:61] offset:384 nt
	global_load_dwordx4 v[206:209], v147, s[60:61] offset:384 nt
	global_load_dwordx4 v[210:213], v165, s[60:61] offset:384 nt
	s_add_u32 s68, s68, s72
	s_addc_u32 s69, s69, s73
	s_add_u32 s60, s60, s70
	s_addc_u32 s61, s61, s71
	s_sub_i32 s74, s74, 1
	s_cmp_eq_u32 s74, 1
	s_cbranch_scc1 .Lpz_g_last
.Lpz_g_steady:
	s_waitcnt vmcnt(36)
	v_mul_f32_e32 v6, v220, v6
	v_mul_f32_e32 v7, v220, v7
	v_mul_f32_e32 v8, v220, v8
	v_mul_f32_e32 v9, v220, v9
	v_mul_f32_e32 v10, v221, v10
	v_mul_f32_e32 v11, v221, v11
	v_mul_f32_e32 v12, v221, v12
	v_mul_f32_e32 v13, v221, v13
	v_mul_f32_e32 v14, v222, v14
	v_mul_f32_e32 v15, v222, v15
	v_mul_f32_e32 v16, v222, v16
	v_mul_f32_e32 v17, v222, v17
	v_mul_f32_e32 v18, v223, v18
	v_mul_f32_e32 v19, v223, v19
	v_mul_f32_e32 v20, v223, v20
	v_mul_f32_e32 v21, v223, v21
	v_mul_f32_e32 v22, v224, v22
	v_mul_f32_e32 v23, v224, v23
	v_mul_f32_e32 v24, v224, v24
	v_mul_f32_e32 v25, v224, v25
	v_mul_f32_e32 v26, v225, v26
	v_mul_f32_e32 v27, v225, v27
	v_mul_f32_e32 v28, v225, v28
	v_mul_f32_e32 v29, v225, v29
	v_mul_f32_e32 v30, v226, v30
	v_mul_f32_e32 v31, v226, v31
	v_mul_f32_e32 v32, v226, v32
	v_mul_f32_e32 v33, v226, v33
	v_mul_f32_e32 v66, v227, v66
	v_mul_f32_e32 v67, v227, v67
	v_mul_f32_e32 v68, v227, v68
	v_mul_f32_e32 v69, v227, v69
	v_cvt_pk_bf16_f32 v228, v6, v10
	v_cvt_pk_bf16_f32 v229, v14, v18
	v_cvt_pk_bf16_f32 v230, v22, v26
	v_cvt_pk_bf16_f32 v231, v30, v66
	global_store_dwordx4 v214, v[228:231], s[62:63] sc1
	v_cvt_pk_bf16_f32 v232, v7, v11
	v_cvt_pk_bf16_f32 v233, v15, v19
	v_cvt_pk_bf16_f32 v234, v23, v27
	v_cvt_pk_bf16_f32 v235, v31, v67
	global_store_dwordx4 v215, v[232:235], s[62:63] sc1
	v_cvt_pk_bf16_f32 v228, v8, v12
	v_cvt_pk_bf16_f32 v229, v16, v20
	v_cvt_pk_bf16_f32 v230, v24, v28
	v_cvt_pk_bf16_f32 v231, v32, v68
	global_store_dwordx4 v219, v[228:231], s[62:63] sc1
	v_cvt_pk_bf16_f32 v232, v9, v13
	v_cvt_pk_bf16_f32 v233, v17, v21
	v_cvt_pk_bf16_f32 v234, v25, v29
	v_cvt_pk_bf16_f32 v235, v33, v69
	global_store_dwordx4 v236, v[232:235], s[62:63] sc1
	global_load_dwordx4 v[6:9], v2, s[60:61] offset:0 nt
	global_load_dwordx4 v[10:13], v120, s[60:61] offset:0 nt
	global_load_dwordx4 v[14:17], v121, s[60:61] offset:0 nt
	global_load_dwordx4 v[18:21], v126, s[60:61] offset:0 nt
	global_load_dwordx4 v[22:25], v144, s[60:61] offset:0 nt
	global_load_dwordx4 v[26:29], v145, s[60:61] offset:0 nt
	global_load_dwordx4 v[30:33], v147, s[60:61] offset:0 nt
	global_load_dwordx4 v[66:69], v165, s[60:61] offset:0 nt
	s_add_u32 s62, s62, s72
	s_addc_u32 s63, s63, s73
	s_waitcnt vmcnt(36)
; #define LAS __attribute__((address_space(3)))
; __device__ __forceinline__ unsigned cvt_pk_bf16(float lo, float hi) { unsigned r; asm volatile("v_cvt_pk_bf16_f32 %0, %1, %2" : "=v"(r) : "v"(lo), "v"(hi)); return r; }
; #define LDS_WAIT() asm volatile("s_waitcnt lgkmcnt(0)" ::: "memory")
; __device__ __forceinline__ unsigned cvt_pk_bf16(float lo, float hi) { unsigned r; asm volatile("v_cvt_pk_bf16_f32 %0, %1, %2" : "=v"(r) : "v"(lo), "v"(hi)); return r; }
; template <bool NT = true> __device__ __forceinline__ void tr_finish(const TrDesc& d, const f32x4 (&v)[8], LAS float* scr, int lane) {
;     const int c = lane & 7;
;     f32x4 g0 = {1.f, 1.f, 1.f, 1.f}, g1 = {1.f, 1.f, 1.f, 1.f};
;     if (d.gain) { g0 = *(const f32x4*)(d.gain + 8 * c); g1 = *(const f32x4*)(d.gain + 8 * c + 4); }
; #pragma unroll
;     for (int i = 0; i < 8; ++i) { LAS float* w = scr + (8 * i + (lane >> 3)) * 33 + 4 * c; w[0] = v[i].x; w[1] = v[i].y; w[2] = v[i].z; w[3] = v[i].w; }
;     LDS_WAIT(); asm volatile("" ::: "memory");
; #pragma unroll
;     for (int j = 0; j < 4; ++j) { const int n = (lane >> 3) + 8 * j; const LAS float* s = scr + (8 * c) * 33 + n;
;         u32x4 o; o.x = cvt_pk_bf16(s[0 * 33] * g0.x, s[1 * 33] * g0.y); o.y = cvt_pk_bf16(s[2 * 33] * g0.z, s[3 * 33] * g0.w); o.z = cvt_pk_bf16(s[4 * 33] * g1.x, s[5 * 33] * g1.y); o.w = cvt_pk_bf16(s[6 * 33] * g1.z, s[7 * 33] * g1.w);
;         if (NT) __builtin_nontemporal_store(o, (u32x4*)(d.dst + (size_t)n * d.K + 8 * c)); else *(u32x4*)(d.dst + (size_t)n * d.K + 8 * c) = o; }
	v_mul_f32_e32 v100, v220, v100
	v_mul_f32_e32 v101, v220, v101
	v_mul_f32_e32 v102, v220, v102
	v_mul_f32_e32 v103, v220, v103
	v_mul_f32_e32 v104, v221, v104
	v_mul_f32_e32 v105, v221, v105
	v_mul_f32_e32 v106, v221, v106
	v_mul_f32_e32 v107, v221, v107
	v_mul_f32_e32 v108, v222, v108
	v_mul_f32_e32 v109, v222, v109
	v_mul_f32_e32 v110, v222, v110
	v_mul_f32_e32 v111, v222, v111
	v_mul_f32_e32 v112, v223, v112
	v_mul_f32_e32 v113, v223, v113
	v_mul_f32_e32 v114, v223, v114
	v_mul_f32_e32 v115, v223, v115
	v_mul_f32_e32 v116, v224, v116
	v_mul_f32_e32 v117, v224, v117
	v_mul_f32_e32 v118, v224, v118
	v_mul_f32_e32 v119, v224, v119
	v_mul_f32_e32 v132, v225, v132
	v_mul_f32_e32 v133, v225, v133
	v_mul_f32_e32 v134, v225, v134
	v_mul_f32_e32 v135, v225, v135
	v_mul_f32_e32 v136, v226, v136
	v_mul_f32_e32 v137, v226, v137
	v_mul_f32_e32 v138, v226, v138
	v_mul_f32_e32 v139, v226, v139
	v_mul_f32_e32 v140, v227, v140
	v_mul_f32_e32 v141, v227, v141
	v_mul_f32_e32 v142, v227, v142
	v_mul_f32_e32 v143, v227, v143
	v_cvt_pk_bf16_f32 v228, v100, v104
	v_cvt_pk_bf16_f32 v229, v108, v112
	v_cvt_pk_bf16_f32 v230, v116, v132
	v_cvt_pk_bf16_f32 v231, v136, v140
	global_store_dwordx4 v214, v[228:231], s[64:65] sc1
	v_cvt_pk_bf16_f32 v232, v101, v105
	v_cvt_pk_bf16_f32 v233, v109, v113
	v_cvt_pk_bf16_f32 v234, v117, v133
	v_cvt_pk_bf16_f32 v235, v137, v141
	global_store_dwordx4 v215, v[232:235], s[64:65] sc1
	v_cvt_pk_bf16_f32 v228, v102, v106
	v_cvt_pk_bf16_f32 v229, v110, v114
	v_cvt_pk_bf16_f32 v230, v118, v134
	v_cvt_pk_bf16_f32 v231, v138, v142
	global_store_dwordx4 v219, v[228:231], s[64:65] sc1
	v_cvt_pk_bf16_f32 v232, v103, v107
	v_cvt_pk_bf16_f32 v233, v111, v115
	v_cvt_pk_bf16_f32 v234, v119, v135
	v_cvt_pk_bf16_f32 v235, v139, v143
	global_store_dwordx4 v236, v[232:235], s[64:65] sc1
	global_load_dwordx4 v[100:103], v2, s[60:61] offset:128 nt
	global_load_dwordx4 v[104:107], v120, s[60:61] offset:128 nt
	global_load_dwordx4 v[108:111], v121, s[60:61] offset:128 nt
	global_load_dwordx4 v[112:115], v126, s[60:61] offset:128 nt
	global_load_dwordx4 v[116:119], v144, s[60:61] offset:128 nt
	global_load_dwordx4 v[132:135], v145, s[60:61] offset:128 nt
	global_load_dwordx4 v[136:139], v147, s[60:61] offset:128 nt
	global_load_dwordx4 v[140:143], v165, s[60:61] offset:128 nt
	s_add_u32 s64, s64, s72
	s_addc_u32 s65, s65, s73
	s_waitcnt vmcnt(36)
	v_mul_f32_e32 v148, v220, v148
	v_mul_f32_e32 v149, v220, v149
	v_mul_f32_e32 v150, v220, v150
	v_mul_f32_e32 v151, v220, v151
	v_mul_f32_e32 v152, v221, v152
	v_mul_f32_e32 v153, v221, v153
	v_mul_f32_e32 v154, v221, v154
	v_mul_f32_e32 v155, v221, v155
	v_mul_f32_e32 v156, v222, v156
	v_mul_f32_e32 v157, v222, v157
	v_mul_f32_e32 v158, v222, v158
	v_mul_f32_e32 v159, v222, v159
	v_mul_f32_e32 v160, v223, v160
	v_mul_f32_e32 v161, v223, v161
	v_mul_f32_e32 v162, v223, v162
	v_mul_f32_e32 v163, v223, v163
	v_mul_f32_e32 v166, v224, v166
	v_mul_f32_e32 v167, v224, v167
	v_mul_f32_e32 v168, v224, v168
	v_mul_f32_e32 v169, v224, v169
	v_mul_f32_e32 v170, v225, v170
	v_mul_f32_e32 v171, v225, v171
	v_mul_f32_e32 v172, v225, v172
	v_mul_f32_e32 v173, v225, v173
	v_mul_f32_e32 v174, v226, v174
	v_mul_f32_e32 v175, v226, v175
	v_mul_f32_e32 v176, v226, v176
	v_mul_f32_e32 v177, v226, v177
	v_mul_f32_e32 v178, v227, v178
	v_mul_f32_e32 v179, v227, v179
	v_mul_f32_e32 v180, v227, v180
	v_mul_f32_e32 v181, v227, v181
	v_cvt_pk_bf16_f32 v228, v148, v152
	v_cvt_pk_bf16_f32 v229, v156, v160
	v_cvt_pk_bf16_f32 v230, v166, v170
	v_cvt_pk_bf16_f32 v231, v174, v178
	global_store_dwordx4 v214, v[228:231], s[66:67] sc1
	v_cvt_pk_bf16_f32 v232, v149, v153
	v_cvt_pk_bf16_f32 v233, v157, v161
	v_cvt_pk_bf16_f32 v234, v167, v171
	v_cvt_pk_bf16_f32 v235, v175, v179
	global_store_dwordx4 v215, v[232:235], s[66:67] sc1
	v_cvt_pk_bf16_f32 v228, v150, v154
	v_cvt_pk_bf16_f32 v229, v158, v162
	v_cvt_pk_bf16_f32 v230, v168, v172
	v_cvt_pk_bf16_f32 v231, v176, v180
	global_store_dwordx4 v219, v[228:231], s[66:67] sc1
	v_cvt_pk_bf16_f32 v232, v151, v155
	v_cvt_pk_bf16_f32 v233, v159, v163
	v_cvt_pk_bf16_f32 v234, v169, v173
	v_cvt_pk_bf16_f32 v235, v177, v181
	global_store_dwordx4 v236, v[232:235], s[66:67] sc1
	global_load_dwordx4 v[148:151], v2, s[60:61] offset:256 nt
	global_load_dwordx4 v[152:155], v120, s[60:61] offset:256 nt
	global_load_dwordx4 v[156:159], v121, s[60:61] offset:256 nt
	global_load_dwordx4 v[160:163], v126, s[60:61] offset:256 nt
	global_load_dwordx4 v[166:169], v144, s[60:61] offset:256 nt
	global_load_dwordx4 v[170:173], v145, s[60:61] offset:256 nt
	global_load_dwordx4 v[174:177], v147, s[60:61] offset:256 nt
	global_load_dwordx4 v[178:181], v165, s[60:61] offset:256 nt
	s_add_u32 s66, s66, s72
	s_addc_u32 s67, s67, s73
	s_waitcnt vmcnt(36)
; #define LAS __attribute__((address_space(3)))
; __device__ __forceinline__ unsigned cvt_pk_bf16(float lo, float hi) { unsigned r; asm volatile("v_cvt_pk_bf16_f32 %0, %1, %2" : "=v"(r) : "v"(lo), "v"(hi)); return r; }
; #define LDS_WAIT() asm volatile("s_waitcnt lgkmcnt(0)" ::: "memory")
; __device__ __forceinline__ unsigned cvt_pk_bf16(float lo, float hi) { unsigned r; asm volatile("v_cvt_pk_bf16_f32 %0, %1, %2" : "=v"(r) : "v"(lo), "v"(hi)); return r; }
; template <bool NT = true> __device__ __forceinline__ void tr_finish(const TrDesc& d, const f32x4 (&v)[8], LAS float* scr, int lane) {
;     const int c = lane & 7;
;     f32x4 g0 = {1.f, 1.f, 1.f, 1.f}, g1 = {1.f, 1.f, 1.f, 1.f};
;     if (d.gain) { g0 = *(const f32x4*)(d.gain + 8 * c); g1 = *(const f32x4*)(d.gain + 8 * c + 4); }
; #pragma unroll
;     for (int i = 0; i < 8; ++i) { LAS float* w = scr + (8 * i + (lane >> 3)) * 33 + 4 * c; w[0] = v[i].x; w[1] = v[i].y; w[2] = v[i].z; w[3] = v[i].w; }
;     LDS_WAIT(); asm volatile("" ::: "memory");
; #pragma unroll
;     for (int j = 0; j < 4; ++j) { const int n = (lane >> 3) + 8 * j; const LAS float* s = scr + (8 * c) * 33 + n;
;         u32x4 o; o.x = cvt_pk_bf16(s[0 * 33] * g0.x, s[1 * 33] * g0.y); o.y = cvt_pk_bf16(s[2 * 33] * g0.z, s[3 * 33] * g0.w); o.z = cvt_pk_bf16(s[4 * 33] * g1.x, s[5 * 33] * g1.y); o.w = cvt_pk_bf16(s[6 * 33] * g1.z, s[7 * 33] * g1.w);
;         if (NT) __builtin_nontemporal_store(o, (u32x4*)(d.dst + (size_t)n * d.K + 8 * c)); else *(u32x4*)(d.dst + (size_t)n * d.K + 8 * c) = o; }
	v_mul_f32_e32 v182, v220, v182
	v_mul_f32_e32 v183, v220, v183
	v_mul_f32_e32 v184, v220, v184
	v_mul_f32_e32 v185, v220, v185
	v_mul_f32_e32 v186, v221, v186
	v_mul_f32_e32 v187, v221, v187
	v_mul_f32_e32 v188, v221, v188
	v_mul_f32_e32 v189, v221, v189
	v_mul_f32_e32 v190, v222, v190
	v_mul_f32_e32 v191, v222, v191
	v_mul_f32_e32 v192, v222, v192
	v_mul_f32_e32 v193, v222, v193
	v_mul_f32_e32 v194, v223, v194
	v_mul_f32_e32 v195, v223, v195
	v_mul_f32_e32 v196, v223, v196
	v_mul_f32_e32 v197, v223, v197
	v_mul_f32_e32 v198, v224, v198
	v_mul_f32_e32 v199, v224, v199
	v_mul_f32_e32 v200, v224, v200
	v_mul_f32_e32 v201, v224, v201
	v_mul_f32_e32 v202, v225, v202
	v_mul_f32_e32 v203, v225, v203
	v_mul_f32_e32 v204, v225, v204
	v_mul_f32_e32 v205, v225, v205
	v_mul_f32_e32 v206, v226, v206
	v_mul_f32_e32 v207, v226, v207
	v_mul_f32_e32 v208, v226, v208
	v_mul_f32_e32 v209, v226, v209
	v_mul_f32_e32 v210, v227, v210
	v_mul_f32_e32 v211, v227, v211
	v_mul_f32_e32 v212, v227, v212
	v_mul_f32_e32 v213, v227, v213
	v_cvt_pk_bf16_f32 v228, v182, v186
	v_cvt_pk_bf16_f32 v229, v190, v194
	v_cvt_pk_bf16_f32 v230, v198, v202
	v_cvt_pk_bf16_f32 v231, v206, v210
	global_store_dwordx4 v214, v[228:231], s[68:69] sc1
	v_cvt_pk_bf16_f32 v232, v183, v187
	v_cvt_pk_bf16_f32 v233, v191, v195
	v_cvt_pk_bf16_f32 v234, v199, v203
	v_cvt_pk_bf16_f32 v235, v207, v211
	global_store_dwordx4 v215, v[232:235], s[68:69] sc1
	v_cvt_pk_bf16_f32 v228, v184, v188
	v_cvt_pk_bf16_f32 v229, v192, v196
	v_cvt_pk_bf16_f32 v230, v200, v204
	v_cvt_pk_bf16_f32 v231, v208, v212
	global_store_dwordx4 v219, v[228:231], s[68:69] sc1
	v_cvt_pk_bf16_f32 v232, v185, v189
	v_cvt_pk_bf16_f32 v233, v193, v197
	v_cvt_pk_bf16_f32 v234, v201, v205
	v_cvt_pk_bf16_f32 v235, v209, v213
	global_store_dwordx4 v236, v[232:235], s[68:69] sc1
	global_load_dwordx4 v[182:185], v2, s[60:61] offset:384 nt
	global_load_dwordx4 v[186:189], v120, s[60:61] offset:384 nt
	global_load_dwordx4 v[190:193], v121, s[60:61] offset:384 nt
	global_load_dwordx4 v[194:197], v126, s[60:61] offset:384 nt
	global_load_dwordx4 v[198:201], v144, s[60:61] offset:384 nt
	global_load_dwordx4 v[202:205], v145, s[60:61] offset:384 nt
	global_load_dwordx4 v[206:209], v147, s[60:61] offset:384 nt
	global_load_dwordx4 v[210:213], v165, s[60:61] offset:384 nt
	s_add_u32 s68, s68, s72
	s_addc_u32 s69, s69, s73
	s_add_u32 s60, s60, s70
	s_addc_u32 s61, s61, s71
	s_sub_i32 s74, s74, 1
	s_cmp_eq_u32 s74, 1
	s_cbranch_scc0 .Lpz_g_steady
.Lpz_g_last:
	s_waitcnt vmcnt(24)
	v_mul_f32_e32 v6, v220, v6
	v_mul_f32_e32 v7, v220, v7
	v_mul_f32_e32 v8, v220, v8
	v_mul_f32_e32 v9, v220, v9
	v_mul_f32_e32 v10, v221, v10
	v_mul_f32_e32 v11, v221, v11
	v_mul_f32_e32 v12, v221, v12
	v_mul_f32_e32 v13, v221, v13
	v_mul_f32_e32 v14, v222, v14
	v_mul_f32_e32 v15, v222, v15
	v_mul_f32_e32 v16, v222, v16
	v_mul_f32_e32 v17, v222, v17
	v_mul_f32_e32 v18, v223, v18
	v_mul_f32_e32 v19, v223, v19
	v_mul_f32_e32 v20, v223, v20
	v_mul_f32_e32 v21, v223, v21
	v_mul_f32_e32 v22, v224, v22
	v_mul_f32_e32 v23, v224, v23
	v_mul_f32_e32 v24, v224, v24
	v_mul_f32_e32 v25, v224, v25
	v_mul_f32_e32 v26, v225, v26
	v_mul_f32_e32 v27, v225, v27
	v_mul_f32_e32 v28, v225, v28
	v_mul_f32_e32 v29, v225, v29
	v_mul_f32_e32 v30, v226, v30
	v_mul_f32_e32 v31, v226, v31
	v_mul_f32_e32 v32, v226, v32
	v_mul_f32_e32 v33, v226, v33
	v_mul_f32_e32 v66, v227, v66
	v_mul_f32_e32 v67, v227, v67
	v_mul_f32_e32 v68, v227, v68
	v_mul_f32_e32 v69, v227, v69
	v_cvt_pk_bf16_f32 v228, v6, v10
	v_cvt_pk_bf16_f32 v229, v14, v18
	v_cvt_pk_bf16_f32 v230, v22, v26
	v_cvt_pk_bf16_f32 v231, v30, v66
	global_store_dwordx4 v214, v[228:231], s[62:63] sc1
	v_cvt_pk_bf16_f32 v232, v7, v11
	v_cvt_pk_bf16_f32 v233, v15, v19
	v_cvt_pk_bf16_f32 v234, v23, v27
	v_cvt_pk_bf16_f32 v235, v31, v67
	global_store_dwordx4 v215, v[232:235], s[62:63] sc1
	v_cvt_pk_bf16_f32 v228, v8, v12
	v_cvt_pk_bf16_f32 v229, v16, v20
	v_cvt_pk_bf16_f32 v230, v24, v28
	v_cvt_pk_bf16_f32 v231, v32, v68
	global_store_dwordx4 v219, v[228:231], s[62:63] sc1
	v_cvt_pk_bf16_f32 v232, v9, v13
	v_cvt_pk_bf16_f32 v233, v17, v21
	v_cvt_pk_bf16_f32 v234, v25, v29
	v_cvt_pk_bf16_f32 v235, v33, v69
	global_store_dwordx4 v236, v[232:235], s[62:63] sc1
	s_waitcnt vmcnt(20)
	v_mul_f32_e32 v100, v220, v100
	v_mul_f32_e32 v101, v220, v101
	v_mul_f32_e32 v102, v220, v102
	v_mul_f32_e32 v103, v220, v103
	v_mul_f32_e32 v104, v221, v104
	v_mul_f32_e32 v105, v221, v105
	v_mul_f32_e32 v106, v221, v106
	v_mul_f32_e32 v107, v221, v107
	v_mul_f32_e32 v108, v222, v108
	v_mul_f32_e32 v109, v222, v109
	v_mul_f32_e32 v110, v222, v110
	v_mul_f32_e32 v111, v222, v111
	v_mul_f32_e32 v112, v223, v112
	v_mul_f32_e32 v113, v223, v113
	v_mul_f32_e32 v114, v223, v114
	v_mul_f32_e32 v115, v223, v115
	v_mul_f32_e32 v116, v224, v116
	v_mul_f32_e32 v117, v224, v117
	v_mul_f32_e32 v118, v224, v118
	v_mul_f32_e32 v119, v224, v119
	v_mul_f32_e32 v132, v225, v132
	v_mul_f32_e32 v133, v225, v133
	v_mul_f32_e32 v134, v225, v134
	v_mul_f32_e32 v135, v225, v135
	v_mul_f32_e32 v136, v226, v136
	v_mul_f32_e32 v137, v226, v137
	v_mul_f32_e32 v138, v226, v138
	v_mul_f32_e32 v139, v226, v139
	v_mul_f32_e32 v140, v227, v140
	v_mul_f32_e32 v141, v227, v141
	v_mul_f32_e32 v142, v227, v142
	v_mul_f32_e32 v143, v227, v143
	v_cvt_pk_bf16_f32 v228, v100, v104
	v_cvt_pk_bf16_f32 v229, v108, v112
	v_cvt_pk_bf16_f32 v230, v116, v132
	v_cvt_pk_bf16_f32 v231, v136, v140
	global_store_dwordx4 v214, v[228:231], s[64:65] sc1
	v_cvt_pk_bf16_f32 v232, v101, v105
	v_cvt_pk_bf16_f32 v233, v109, v113
	v_cvt_pk_bf16_f32 v234, v117, v133
	v_cvt_pk_bf16_f32 v235, v137, v141
	global_store_dwordx4 v215, v[232:235], s[64:65] sc1
	v_cvt_pk_bf16_f32 v228, v102, v106
	v_cvt_pk_bf16_f32 v229, v110, v114
	v_cvt_pk_bf16_f32 v230, v118, v134
	v_cvt_pk_bf16_f32 v231, v138, v142
	global_store_dwordx4 v219, v[228:231], s[64:65] sc1
	v_cvt_pk_bf16_f32 v232, v103, v107
	v_cvt_pk_bf16_f32 v233, v111, v115
	v_cvt_pk_bf16_f32 v234, v119, v135
	v_cvt_pk_bf16_f32 v235, v139, v143
	global_store_dwordx4 v236, v[232:235], s[64:65] sc1
	s_waitcnt vmcnt(16)
; #define LAS __attribute__((address_space(3)))
; __device__ __forceinline__ unsigned cvt_pk_bf16(float lo, float hi) { unsigned r; asm volatile("v_cvt_pk_bf16_f32 %0, %1, %2" : "=v"(r) : "v"(lo), "v"(hi)); return r; }
; #define LDS_WAIT() asm volatile("s_waitcnt lgkmcnt(0)" ::: "memory")
; __device__ __forceinline__ unsigned cvt_pk_bf16(float lo, float hi) { unsigned r; asm volatile("v_cvt_pk_bf16_f32 %0, %1, %2" : "=v"(r) : "v"(lo), "v"(hi)); return r; }
; template <bool NT = true> __device__ __forceinline__ void tr_finish(const TrDesc& d, const f32x4 (&v)[8], LAS float* scr, int lane) {
;     const int c = lane & 7;
;     f32x4 g0 = {1.f, 1.f, 1.f, 1.f}, g1 = {1.f, 1.f, 1.f, 1.f};
;     if (d.gain) { g0 = *(const f32x4*)(d.gain + 8 * c); g1 = *(const f32x4*)(d.gain + 8 * c + 4); }
; #pragma unroll
;     for (int i = 0; i < 8; ++i) { LAS float* w = scr + (8 * i + (lane >> 3)) * 33 + 4 * c; w[0] = v[i].x; w[1] = v[i].y; w[2] = v[i].z; w[3] = v[i].w; }
;     LDS_WAIT(); asm volatile("" ::: "memory");
; #pragma unroll
;     for (int j = 0; j < 4; ++j) { const int n = (lane >> 3) + 8 * j; const LAS float* s = scr + (8 * c) * 33 + n;
;         u32x4 o; o.x = cvt_pk_bf16(s[0 * 33] * g0.x, s[1 * 33] * g0.y); o.y = cvt_pk_bf16(s[2 * 33] * g0.z, s[3 * 33] * g0.w); o.z = cvt_pk_bf16(s[4 * 33] * g1.x, s[5 * 33] * g1.y); o.w = cvt_pk_bf16(s[6 * 33] * g1.z, s[7 * 33] * g1.w);
;         if (NT) __builtin_nontemporal_store(o, (u32x4*)(d.dst + (size_t)n * d.K + 8 * c)); else *(u32x4*)(d.dst + (size_t)n * d.K + 8 * c) = o; }
	v_mul_f32_e32 v148, v220, v148
	v_mul_f32_e32 v149, v220, v149
	v_mul_f32_e32 v150, v220, v150
	v_mul_f32_e32 v151, v220, v151
	v_mul_f32_e32 v152, v221, v152
	v_mul_f32_e32 v153, v221, v153
	v_mul_f32_e32 v154, v221, v154
	v_mul_f32_e32 v155, v221, v155
	v_mul_f32_e32 v156, v222, v156
	v_mul_f32_e32 v157, v222, v157
	v_mul_f32_e32 v158, v222, v158
	v_mul_f32_e32 v159, v222, v159
	v_mul_f32_e32 v160, v223, v160
	v_mul_f32_e32 v161, v223, v161
	v_mul_f32_e32 v162, v223, v162
	v_mul_f32_e32 v163, v223, v163
	v_mul_f32_e32 v166, v224, v166
	v_mul_f32_e32 v167, v224, v167
	v_mul_f32_e32 v168, v224, v168
	v_mul_f32_e32 v169, v224, v169
	v_mul_f32_e32 v170, v225, v170
	v_mul_f32_e32 v171, v225, v171
	v_mul_f32_e32 v172, v225, v172
	v_mul_f32_e32 v173, v225, v173
	v_mul_f32_e32 v174, v226, v174
	v_mul_f32_e32 v175, v226, v175
	v_mul_f32_e32 v176, v226, v176
	v_mul_f32_e32 v177, v226, v177
	v_mul_f32_e32 v178, v227, v178
	v_mul_f32_e32 v179, v227, v179
	v_mul_f32_e32 v180, v227, v180
	v_mul_f32_e32 v181, v227, v181
	v_cvt_pk_bf16_f32 v228, v148, v152
	v_cvt_pk_bf16_f32 v229, v156, v160
	v_cvt_pk_bf16_f32 v230, v166, v170
	v_cvt_pk_bf16_f32 v231, v174, v178
	global_store_dwordx4 v214, v[228:231], s[66:67] sc1
	v_cvt_pk_bf16_f32 v232, v149, v153
	v_cvt_pk_bf16_f32 v233, v157, v161
	v_cvt_pk_bf16_f32 v234, v167, v171
	v_cvt_pk_bf16_f32 v235, v175, v179
	global_store_dwordx4 v215, v[232:235], s[66:67] sc1
	v_cvt_pk_bf16_f32 v228, v150, v154
	v_cvt_pk_bf16_f32 v229, v158, v162
	v_cvt_pk_bf16_f32 v230, v168, v172
	v_cvt_pk_bf16_f32 v231, v176, v180
	global_store_dwordx4 v219, v[228:231], s[66:67] sc1
	v_cvt_pk_bf16_f32 v232, v151, v155
	v_cvt_pk_bf16_f32 v233, v159, v163
	v_cvt_pk_bf16_f32 v234, v169, v173
	v_cvt_pk_bf16_f32 v235, v177, v181
	global_store_dwordx4 v236, v[232:235], s[66:67] sc1
	s_waitcnt vmcnt(12)
	v_mul_f32_e32 v182, v220, v182
	v_mul_f32_e32 v183, v220, v183
	v_mul_f32_e32 v184, v220, v184
	v_mul_f32_e32 v185, v220, v185
	v_mul_f32_e32 v186, v221, v186
	v_mul_f32_e32 v187, v221, v187
	v_mul_f32_e32 v188, v221, v188
	v_mul_f32_e32 v189, v221, v189
	v_mul_f32_e32 v190, v222, v190
	v_mul_f32_e32 v191, v222, v191
	v_mul_f32_e32 v192, v222, v192
	v_mul_f32_e32 v193, v222, v193
	v_mul_f32_e32 v194, v223, v194
	v_mul_f32_e32 v195, v223, v195
	v_mul_f32_e32 v196, v223, v196
	v_mul_f32_e32 v197, v223, v197
	v_mul_f32_e32 v198, v224, v198
	v_mul_f32_e32 v199, v224, v199
	v_mul_f32_e32 v200, v224, v200
	v_mul_f32_e32 v201, v224, v201
	v_mul_f32_e32 v202, v225, v202
	v_mul_f32_e32 v203, v225, v203
	v_mul_f32_e32 v204, v225, v204
	v_mul_f32_e32 v205, v225, v205
	v_mul_f32_e32 v206, v226, v206
	v_mul_f32_e32 v207, v226, v207
	v_mul_f32_e32 v208, v226, v208
	v_mul_f32_e32 v209, v226, v209
	v_mul_f32_e32 v210, v227, v210
	v_mul_f32_e32 v211, v227, v211
	v_mul_f32_e32 v212, v227, v212
	v_mul_f32_e32 v213, v227, v213
	v_cvt_pk_bf16_f32 v228, v182, v186
	v_cvt_pk_bf16_f32 v229, v190, v194
	v_cvt_pk_bf16_f32 v230, v198, v202
	v_cvt_pk_bf16_f32 v231, v206, v210
	global_store_dwordx4 v214, v[228:231], s[68:69] sc1
	v_cvt_pk_bf16_f32 v232, v183, v187
	v_cvt_pk_bf16_f32 v233, v191, v195
	v_cvt_pk_bf16_f32 v234, v199, v203
	v_cvt_pk_bf16_f32 v235, v207, v211
	global_store_dwordx4 v215, v[232:235], s[68:69] sc1
	v_cvt_pk_bf16_f32 v228, v184, v188
	v_cvt_pk_bf16_f32 v229, v192, v196
	v_cvt_pk_bf16_f32 v230, v200, v204
	v_cvt_pk_bf16_f32 v231, v208, v212
	global_store_dwordx4 v219, v[228:231], s[68:69] sc1
	v_cvt_pk_bf16_f32 v232, v185, v189
	v_cvt_pk_bf16_f32 v233, v193, v197
	v_cvt_pk_bf16_f32 v234, v201, v205
	v_cvt_pk_bf16_f32 v235, v209, v213
	global_store_dwordx4 v236, v[232:235], s[68:69] sc1
	s_branch .Lpz_ret
.Lpz_nogain:
	global_load_dwordx4 v[6:9], v2, s[60:61] offset:0 nt
	global_load_dwordx4 v[10:13], v120, s[60:61] offset:0 nt
	global_load_dwordx4 v[14:17], v121, s[60:61] offset:0 nt
	global_load_dwordx4 v[18:21], v126, s[60:61] offset:0 nt
	global_load_dwordx4 v[22:25], v144, s[60:61] offset:0 nt
	global_load_dwordx4 v[26:29], v145, s[60:61] offset:0 nt
	global_load_dwordx4 v[30:33], v147, s[60:61] offset:0 nt
	global_load_dwordx4 v[66:69], v165, s[60:61] offset:0 nt
	global_load_dwordx4 v[100:103], v2, s[60:61] offset:128 nt
	global_load_dwordx4 v[104:107], v120, s[60:61] offset:128 nt
	global_load_dwordx4 v[108:111], v121, s[60:61] offset:128 nt
	global_load_dwordx4 v[112:115], v126, s[60:61] offset:128 nt
	global_load_dwordx4 v[116:119], v144, s[60:61] offset:128 nt
	global_load_dwordx4 v[132:135], v145, s[60:61] offset:128 nt
	global_load_dwordx4 v[136:139], v147, s[60:61] offset:128 nt
	global_load_dwordx4 v[140:143], v165, s[60:61] offset:128 nt
	global_load_dwordx4 v[148:151], v2, s[60:61] offset:256 nt
	global_load_dwordx4 v[152:155], v120, s[60:61] offset:256 nt
	global_load_dwordx4 v[156:159], v121, s[60:61] offset:256 nt
	global_load_dwordx4 v[160:163], v126, s[60:61] offset:256 nt
	global_load_dwordx4 v[166:169], v144, s[60:61] offset:256 nt
	global_load_dwordx4 v[170:173], v145, s[60:61] offset:256 nt
	global_load_dwordx4 v[174:177], v147, s[60:61] offset:256 nt
	global_load_dwordx4 v[178:181], v165, s[60:61] offset:256 nt
	global_load_dwordx4 v[182:185], v2, s[60:61] offset:384 nt
	global_load_dwordx4 v[186:189], v120, s[60:61] offset:384 nt
	global_load_dwordx4 v[190:193], v121, s[60:61] offset:384 nt
	global_load_dwordx4 v[194:197], v126, s[60:61] offset:384 nt
	global_load_dwordx4 v[198:201], v144, s[60:61] offset:384 nt
	global_load_dwordx4 v[202:205], v145, s[60:61] offset:384 nt
	global_load_dwordx4 v[206:209], v147, s[60:61] offset:384 nt
	global_load_dwordx4 v[210:213], v165, s[60:61] offset:384 nt
	s_add_u32 s60, s60, s70
	s_addc_u32 s61, s61, s71
	s_cmp_eq_u32 s74, 1
	s_cbranch_scc1 .Lpz_n_last
; #define LAS __attribute__((address_space(3)))
; __device__ __forceinline__ unsigned cvt_pk_bf16(float lo, float hi) { unsigned r; asm volatile("v_cvt_pk_bf16_f32 %0, %1, %2" : "=v"(r) : "v"(lo), "v"(hi)); return r; }
; #define LDS_WAIT() asm volatile("s_waitcnt lgkmcnt(0)" ::: "memory")
; __device__ __forceinline__ unsigned cvt_pk_bf16(float lo, float hi) { unsigned r; asm volatile("v_cvt_pk_bf16_f32 %0, %1, %2" : "=v"(r) : "v"(lo), "v"(hi)); return r; }
; template <bool NT = true> __device__ __forceinline__ void tr_finish(const TrDesc& d, const f32x4 (&v)[8], LAS float* scr, int lane) {
;     const int c = lane & 7;
;     f32x4 g0 = {1.f, 1.f, 1.f, 1.f}, g1 = {1.f, 1.f, 1.f, 1.f};
;     if (d.gain) { g0 = *(const f32x4*)(d.gain + 8 * c); g1 = *(const f32x4*)(d.gain + 8 * c + 4); }
; #pragma unroll
;     for (int i = 0; i < 8; ++i) { LAS float* w = scr + (8 * i + (lane >> 3)) * 33 + 4 * c; w[0] = v[i].x; w[1] = v[i].y; w[2] = v[i].z; w[3] = v[i].w; }
;     LDS_WAIT(); asm volatile("" ::: "memory");
; #pragma unroll
;     for (int j = 0; j < 4; ++j) { const int n = (lane >> 3) + 8 * j; const LAS float* s = scr + (8 * c) * 33 + n;
;         u32x4 o; o.x = cvt_pk_bf16(s[0 * 33] * g0.x, s[1 * 33] * g0.y); o.y = cvt_pk_bf16(s[2 * 33] * g0.z, s[3 * 33] * g0.w); o.z = cvt_pk_bf16(s[4 * 33] * g1.x, s[5 * 33] * g1.y); o.w = cvt_pk_bf16(s[6 * 33] * g1.z, s[7 * 33] * g1.w);
;         if (NT) __builtin_nontemporal_store(o, (u32x4*)(d.dst + (size_t)n * d.K + 8 * c)); else *(u32x4*)(d.dst + (size_t)n * d.K + 8 * c) = o; }
	s_waitcnt vmcnt(24)
	v_cvt_pk_bf16_f32 v228, v6, v10
	v_cvt_pk_bf16_f32 v229, v14, v18
	v_cvt_pk_bf16_f32 v230, v22, v26
	v_cvt_pk_bf16_f32 v231, v30, v66
	global_store_dwordx4 v214, v[228:231], s[62:63] sc1
	v_cvt_pk_bf16_f32 v232, v7, v11
	v_cvt_pk_bf16_f32 v233, v15, v19
	v_cvt_pk_bf16_f32 v234, v23, v27
	v_cvt_pk_bf16_f32 v235, v31, v67
	global_store_dwordx4 v215, v[232:235], s[62:63] sc1
	v_cvt_pk_bf16_f32 v228, v8, v12
	v_cvt_pk_bf16_f32 v229, v16, v20
	v_cvt_pk_bf16_f32 v230, v24, v28
	v_cvt_pk_bf16_f32 v231, v32, v68
	global_store_dwordx4 v219, v[228:231], s[62:63] sc1
	v_cvt_pk_bf16_f32 v232, v9, v13
	v_cvt_pk_bf16_f32 v233, v17, v21
	v_cvt_pk_bf16_f32 v234, v25, v29
	v_cvt_pk_bf16_f32 v235, v33, v69
	global_store_dwordx4 v236, v[232:235], s[62:63] sc1
	global_load_dwordx4 v[6:9], v2, s[60:61] offset:0 nt
	global_load_dwordx4 v[10:13], v120, s[60:61] offset:0 nt
	global_load_dwordx4 v[14:17], v121, s[60:61] offset:0 nt
	global_load_dwordx4 v[18:21], v126, s[60:61] offset:0 nt
	global_load_dwordx4 v[22:25], v144, s[60:61] offset:0 nt
	global_load_dwordx4 v[26:29], v145, s[60:61] offset:0 nt
	global_load_dwordx4 v[30:33], v147, s[60:61] offset:0 nt
	global_load_dwordx4 v[66:69], v165, s[60:61] offset:0 nt
	s_add_u32 s62, s62, s72
	s_addc_u32 s63, s63, s73
	s_waitcnt vmcnt(28)
	v_cvt_pk_bf16_f32 v228, v100, v104
	v_cvt_pk_bf16_f32 v229, v108, v112
	v_cvt_pk_bf16_f32 v230, v116, v132
	v_cvt_pk_bf16_f32 v231, v136, v140
	global_store_dwordx4 v214, v[228:231], s[64:65] sc1
	v_cvt_pk_bf16_f32 v232, v101, v105
	v_cvt_pk_bf16_f32 v233, v109, v113
	v_cvt_pk_bf16_f32 v234, v117, v133
	v_cvt_pk_bf16_f32 v235, v137, v141
	global_store_dwordx4 v215, v[232:235], s[64:65] sc1
	v_cvt_pk_bf16_f32 v228, v102, v106
	v_cvt_pk_bf16_f32 v229, v110, v114
	v_cvt_pk_bf16_f32 v230, v118, v134
	v_cvt_pk_bf16_f32 v231, v138, v142
	global_store_dwordx4 v219, v[228:231], s[64:65] sc1
	v_cvt_pk_bf16_f32 v232, v103, v107
	v_cvt_pk_bf16_f32 v233, v111, v115
	v_cvt_pk_bf16_f32 v234, v119, v135
	v_cvt_pk_bf16_f32 v235, v139, v143
	global_store_dwordx4 v236, v[232:235], s[64:65] sc1
	global_load_dwordx4 v[100:103], v2, s[60:61] offset:128 nt
	global_load_dwordx4 v[104:107], v120, s[60:61] offset:128 nt
	global_load_dwordx4 v[108:111], v121, s[60:61] offset:128 nt
	global_load_dwordx4 v[112:115], v126, s[60:61] offset:128 nt
	global_load_dwordx4 v[116:119], v144, s[60:61] offset:128 nt
	global_load_dwordx4 v[132:135], v145, s[60:61] offset:128 nt
	global_load_dwordx4 v[136:139], v147, s[60:61] offset:128 nt
	global_load_dwordx4 v[140:143], v165, s[60:61] offset:128 nt
	s_add_u32 s64, s64, s72
	s_addc_u32 s65, s65, s73
	s_waitcnt vmcnt(32)
	v_cvt_pk_bf16_f32 v228, v148, v152
	v_cvt_pk_bf16_f32 v229, v156, v160
	v_cvt_pk_bf16_f32 v230, v166, v170
	v_cvt_pk_bf16_f32 v231, v174, v178
	global_store_dwordx4 v214, v[228:231], s[66:67] sc1
	v_cvt_pk_bf16_f32 v232, v149, v153
	v_cvt_pk_bf16_f32 v233, v157, v161
	v_cvt_pk_bf16_f32 v234, v167, v171
	v_cvt_pk_bf16_f32 v235, v175, v179
	global_store_dwordx4 v215, v[232:235], s[66:67] sc1
	v_cvt_pk_bf16_f32 v228, v150, v154
	v_cvt_pk_bf16_f32 v229, v158, v162
	v_cvt_pk_bf16_f32 v230, v168, v172
	v_cvt_pk_bf16_f32 v231, v176, v180
	global_store_dwordx4 v219, v[228:231], s[66:67] sc1
	v_cvt_pk_bf16_f32 v232, v151, v155
	v_cvt_pk_bf16_f32 v233, v159, v163
	v_cvt_pk_bf16_f32 v234, v169, v173
	v_cvt_pk_bf16_f32 v235, v177, v181
	global_store_dwordx4 v236, v[232:235], s[66:67] sc1
	global_load_dwordx4 v[148:151], v2, s[60:61] offset:256 nt
	global_load_dwordx4 v[152:155], v120, s[60:61] offset:256 nt
	global_load_dwordx4 v[156:159], v121, s[60:61] offset:256 nt
	global_load_dwordx4 v[160:163], v126, s[60:61] offset:256 nt
	global_load_dwordx4 v[166:169], v144, s[60:61] offset:256 nt
	global_load_dwordx4 v[170:173], v145, s[60:61] offset:256 nt
	global_load_dwordx4 v[174:177], v147, s[60:61] offset:256 nt
	global_load_dwordx4 v[178:181], v165, s[60:61] offset:256 nt
	s_add_u32 s66, s66, s72
	s_addc_u32 s67, s67, s73
	s_waitcnt vmcnt(36)
	v_cvt_pk_bf16_f32 v228, v182, v186
	v_cvt_pk_bf16_f32 v229, v190, v194
	v_cvt_pk_bf16_f32 v230, v198, v202
	v_cvt_pk_bf16_f32 v231, v206, v210
	global_store_dwordx4 v214, v[228:231], s[68:69] sc1
	v_cvt_pk_bf16_f32 v232, v183, v187
	v_cvt_pk_bf16_f32 v233, v191, v195
	v_cvt_pk_bf16_f32 v234, v199, v203
	v_cvt_pk_bf16_f32 v235, v207, v211
	global_store_dwordx4 v215, v[232:235], s[68:69] sc1
	v_cvt_pk_bf16_f32 v228, v184, v188
	v_cvt_pk_bf16_f32 v229, v192, v196
	v_cvt_pk_bf16_f32 v230, v200, v204
	v_cvt_pk_bf16_f32 v231, v208, v212
	global_store_dwordx4 v219, v[228:231], s[68:69] sc1
	v_cvt_pk_bf16_f32 v232, v185, v189
	v_cvt_pk_bf16_f32 v233, v193, v197
	v_cvt_pk_bf16_f32 v234, v201, v205
	v_cvt_pk_bf16_f32 v235, v209, v213
	global_store_dwordx4 v236, v[232:235], s[68:69] sc1
	global_load_dwordx4 v[182:185], v2, s[60:61] offset:384 nt
	global_load_dwordx4 v[186:189], v120, s[60:61] offset:384 nt
	global_load_dwordx4 v[190:193], v121, s[60:61] offset:384 nt
	global_load_dwordx4 v[194:197], v126, s[60:61] offset:384 nt
	global_load_dwordx4 v[198:201], v144, s[60:61] offset:384 nt
	global_load_dwordx4 v[202:205], v145, s[60:61] offset:384 nt
	global_load_dwordx4 v[206:209], v147, s[60:61] offset:384 nt
	global_load_dwordx4 v[210:213], v165, s[60:61] offset:384 nt
	s_add_u32 s68, s68, s72
	s_addc_u32 s69, s69, s73
	s_add_u32 s60, s60, s70
	s_addc_u32 s61, s61, s71
	s_sub_i32 s74, s74, 1
	s_cmp_eq_u32 s74, 1
	s_cbranch_scc1 .Lpz_n_last
; #define LAS __attribute__((address_space(3)))
; __device__ __forceinline__ unsigned cvt_pk_bf16(float lo, float hi) { unsigned r; asm volatile("v_cvt_pk_bf16_f32 %0, %1, %2" : "=v"(r) : "v"(lo), "v"(hi)); return r; }
; #define LDS_WAIT() asm volatile("s_waitcnt lgkmcnt(0)" ::: "memory")
; __device__ __forceinline__ unsigned cvt_pk_bf16(float lo, float hi) { unsigned r; asm volatile("v_cvt_pk_bf16_f32 %0, %1, %2" : "=v"(r) : "v"(lo), "v"(hi)); return r; }
; template <bool NT = true> __device__ __forceinline__ void tr_finish(const TrDesc& d, const f32x4 (&v)[8], LAS float* scr, int lane) {
;     const int c = lane & 7;
;     f32x4 g0 = {1.f, 1.f, 1.f, 1.f}, g1 = {1.f, 1.f, 1.f, 1.f};
;     if (d.gain) { g0 = *(const f32x4*)(d.gain + 8 * c); g1 = *(const f32x4*)(d.gain + 8 * c + 4); }
; #pragma unroll
;     for (int i = 0; i < 8; ++i) { LAS float* w = scr + (8 * i + (lane >> 3)) * 33 + 4 * c; w[0] = v[i].x; w[1] = v[i].y; w[2] = v[i].z; w[3] = v[i].w; }
;     LDS_WAIT(); asm volatile("" ::: "memory");
; #pragma unroll
;     for (int j = 0; j < 4; ++j) { const int n = (lane >> 3) + 8 * j; const LAS float* s = scr + (8 * c) * 33 + n;
;         u32x4 o; o.x = cvt_pk_bf16(s[0 * 33] * g0.x, s[1 * 33] * g0.y); o.y = cvt_pk_bf16(s[2 * 33] * g0.z, s[3 * 33] * g0.w); o.z = cvt_pk_bf16(s[4 * 33] * g1.x, s[5 * 33] * g1.y); o.w = cvt_pk_bf16(s[6 * 33] * g1.z, s[7 * 33] * g1.w);
;         if (NT) __builtin_nontemporal_store(o, (u32x4*)(d.dst + (size_t)n * d.K + 8 * c)); else *(u32x4*)(d.dst + (size_t)n * d.K + 8 * c) = o; }
.Lpz_n_steady:
	s_waitcnt vmcnt(36)
	v_cvt_pk_bf16_f32 v228, v6, v10
	v_cvt_pk_bf16_f32 v229, v14, v18
	v_cvt_pk_bf16_f32 v230, v22, v26
	v_cvt_pk_bf16_f32 v231, v30, v66
	global_store_dwordx4 v214, v[228:231], s[62:63] sc1
	v_cvt_pk_bf16_f32 v232, v7, v11
	v_cvt_pk_bf16_f32 v233, v15, v19
	v_cvt_pk_bf16_f32 v234, v23, v27
	v_cvt_pk_bf16_f32 v235, v31, v67
	global_store_dwordx4 v215, v[232:235], s[62:63] sc1
	v_cvt_pk_bf16_f32 v228, v8, v12
	v_cvt_pk_bf16_f32 v229, v16, v20
	v_cvt_pk_bf16_f32 v230, v24, v28
	v_cvt_pk_bf16_f32 v231, v32, v68
	global_store_dwordx4 v219, v[228:231], s[62:63] sc1
	v_cvt_pk_bf16_f32 v232, v9, v13
	v_cvt_pk_bf16_f32 v233, v17, v21
	v_cvt_pk_bf16_f32 v234, v25, v29
	v_cvt_pk_bf16_f32 v235, v33, v69
	global_store_dwordx4 v236, v[232:235], s[62:63] sc1
	global_load_dwordx4 v[6:9], v2, s[60:61] offset:0 nt
	global_load_dwordx4 v[10:13], v120, s[60:61] offset:0 nt
	global_load_dwordx4 v[14:17], v121, s[60:61] offset:0 nt
	global_load_dwordx4 v[18:21], v126, s[60:61] offset:0 nt
	global_load_dwordx4 v[22:25], v144, s[60:61] offset:0 nt
	global_load_dwordx4 v[26:29], v145, s[60:61] offset:0 nt
	global_load_dwordx4 v[30:33], v147, s[60:61] offset:0 nt
	global_load_dwordx4 v[66:69], v165, s[60:61] offset:0 nt
	s_add_u32 s62, s62, s72
	s_addc_u32 s63, s63, s73
	s_waitcnt vmcnt(36)
	v_cvt_pk_bf16_f32 v228, v100, v104
	v_cvt_pk_bf16_f32 v229, v108, v112
	v_cvt_pk_bf16_f32 v230, v116, v132
	v_cvt_pk_bf16_f32 v231, v136, v140
	global_store_dwordx4 v214, v[228:231], s[64:65] sc1
	v_cvt_pk_bf16_f32 v232, v101, v105
	v_cvt_pk_bf16_f32 v233, v109, v113
	v_cvt_pk_bf16_f32 v234, v117, v133
	v_cvt_pk_bf16_f32 v235, v137, v141
	global_store_dwordx4 v215, v[232:235], s[64:65] sc1
	v_cvt_pk_bf16_f32 v228, v102, v106
	v_cvt_pk_bf16_f32 v229, v110, v114
	v_cvt_pk_bf16_f32 v230, v118, v134
	v_cvt_pk_bf16_f32 v231, v138, v142
	global_store_dwordx4 v219, v[228:231], s[64:65] sc1
	v_cvt_pk_bf16_f32 v232, v103, v107
	v_cvt_pk_bf16_f32 v233, v111, v115
	v_cvt_pk_bf16_f32 v234, v119, v135
	v_cvt_pk_bf16_f32 v235, v139, v143
	global_store_dwordx4 v236, v[232:235], s[64:65] sc1
	global_load_dwordx4 v[100:103], v2, s[60:61] offset:128 nt
	global_load_dwordx4 v[104:107], v120, s[60:61] offset:128 nt
	global_load_dwordx4 v[108:111], v121, s[60:61] offset:128 nt
	global_load_dwordx4 v[112:115], v126, s[60:61] offset:128 nt
	global_load_dwordx4 v[116:119], v144, s[60:61] offset:128 nt
	global_load_dwordx4 v[132:135], v145, s[60:61] offset:128 nt
	global_load_dwordx4 v[136:139], v147, s[60:61] offset:128 nt
	global_load_dwordx4 v[140:143], v165, s[60:61] offset:128 nt
	s_add_u32 s64, s64, s72
	s_addc_u32 s65, s65, s73
	s_waitcnt vmcnt(36)
	v_cvt_pk_bf16_f32 v228, v148, v152
	v_cvt_pk_bf16_f32 v229, v156, v160
	v_cvt_pk_bf16_f32 v230, v166, v170
	v_cvt_pk_bf16_f32 v231, v174, v178
	global_store_dwordx4 v214, v[228:231], s[66:67] sc1
	v_cvt_pk_bf16_f32 v232, v149, v153
	v_cvt_pk_bf16_f32 v233, v157, v161
	v_cvt_pk_bf16_f32 v234, v167, v171
	v_cvt_pk_bf16_f32 v235, v175, v179
	global_store_dwordx4 v215, v[232:235], s[66:67] sc1
	v_cvt_pk_bf16_f32 v228, v150, v154
	v_cvt_pk_bf16_f32 v229, v158, v162
	v_cvt_pk_bf16_f32 v230, v168, v172
	v_cvt_pk_bf16_f32 v231, v176, v180
	global_store_dwordx4 v219, v[228:231], s[66:67] sc1
	v_cvt_pk_bf16_f32 v232, v151, v155
	v_cvt_pk_bf16_f32 v233, v159, v163
	v_cvt_pk_bf16_f32 v234, v169, v173
	v_cvt_pk_bf16_f32 v235, v177, v181
	global_store_dwordx4 v236, v[232:235], s[66:67] sc1
	global_load_dwordx4 v[148:151], v2, s[60:61] offset:256 nt
	global_load_dwordx4 v[152:155], v120, s[60:61] offset:256 nt
	global_load_dwordx4 v[156:159], v121, s[60:61] offset:256 nt
	global_load_dwordx4 v[160:163], v126, s[60:61] offset:256 nt
	global_load_dwordx4 v[166:169], v144, s[60:61] offset:256 nt
	global_load_dwordx4 v[170:173], v145, s[60:61] offset:256 nt
	global_load_dwordx4 v[174:177], v147, s[60:61] offset:256 nt
	global_load_dwordx4 v[178:181], v165, s[60:61] offset:256 nt
	s_add_u32 s66, s66, s72
	s_addc_u32 s67, s67, s73
	s_waitcnt vmcnt(36)
	v_cvt_pk_bf16_f32 v228, v182, v186
	v_cvt_pk_bf16_f32 v229, v190, v194
	v_cvt_pk_bf16_f32 v230, v198, v202
	v_cvt_pk_bf16_f32 v231, v206, v210
	global_store_dwordx4 v214, v[228:231], s[68:69] sc1
	v_cvt_pk_bf16_f32 v232, v183, v187
	v_cvt_pk_bf16_f32 v233, v191, v195
	v_cvt_pk_bf16_f32 v234, v199, v203
	v_cvt_pk_bf16_f32 v235, v207, v211
	global_store_dwordx4 v215, v[232:235], s[68:69] sc1
	v_cvt_pk_bf16_f32 v228, v184, v188
	v_cvt_pk_bf16_f32 v229, v192, v196
	v_cvt_pk_bf16_f32 v230, v200, v204
	v_cvt_pk_bf16_f32 v231, v208, v212
	global_store_dwordx4 v219, v[228:231], s[68:69] sc1
	v_cvt_pk_bf16_f32 v232, v185, v189
	v_cvt_pk_bf16_f32 v233, v193, v197
	v_cvt_pk_bf16_f32 v234, v201, v205
	v_cvt_pk_bf16_f32 v235, v209, v213
	global_store_dwordx4 v236, v[232:235], s[68:69] sc1
	global_load_dwordx4 v[182:185], v2, s[60:61] offset:384 nt
	global_load_dwordx4 v[186:189], v120, s[60:61] offset:384 nt
	global_load_dwordx4 v[190:193], v121, s[60:61] offset:384 nt
	global_load_dwordx4 v[194:197], v126, s[60:61] offset:384 nt
	global_load_dwordx4 v[198:201], v144, s[60:61] offset:384 nt
	global_load_dwordx4 v[202:205], v145, s[60:61] offset:384 nt
	global_load_dwordx4 v[206:209], v147, s[60:61] offset:384 nt
	global_load_dwordx4 v[210:213], v165, s[60:61] offset:384 nt
	s_add_u32 s68, s68, s72
	s_addc_u32 s69, s69, s73
	s_add_u32 s60, s60, s70
	s_addc_u32 s61, s61, s71
	s_sub_i32 s74, s74, 1
	s_cmp_eq_u32 s74, 1
	s_cbranch_scc0 .Lpz_n_steady
; #define LAS __attribute__((address_space(3)))
; __device__ __forceinline__ unsigned cvt_pk_bf16(float lo, float hi) { unsigned r; asm volatile("v_cvt_pk_bf16_f32 %0, %1, %2" : "=v"(r) : "v"(lo), "v"(hi)); return r; }
; #define LDS_WAIT() asm volatile("s_waitcnt lgkmcnt(0)" ::: "memory")
; __device__ __forceinline__ unsigned cvt_pk_bf16(float lo, float hi) { unsigned r; asm volatile("v_cvt_pk_bf16_f32 %0, %1, %2" : "=v"(r) : "v"(lo), "v"(hi)); return r; }
; template <bool NT = true> __device__ __forceinline__ void tr_finish(const TrDesc& d, const f32x4 (&v)[8], LAS float* scr, int lane) {
;     const int c = lane & 7;
;     f32x4 g0 = {1.f, 1.f, 1.f, 1.f}, g1 = {1.f, 1.f, 1.f, 1.f};
;     if (d.gain) { g0 = *(const f32x4*)(d.gain + 8 * c); g1 = *(const f32x4*)(d.gain + 8 * c + 4); }
; #pragma unroll
;     for (int i = 0; i < 8; ++i) { LAS float* w = scr + (8 * i + (lane >> 3)) * 33 + 4 * c; w[0] = v[i].x; w[1] = v[i].y; w[2] = v[i].z; w[3] = v[i].w; }
;     LDS_WAIT(); asm volatile("" ::: "memory");
; #pragma unroll
;     for (int j = 0; j < 4; ++j) { const int n = (lane >> 3) + 8 * j; const LAS float* s = scr + (8 * c) * 33 + n;
;         u32x4 o; o.x = cvt_pk_bf16(s[0 * 33] * g0.x, s[1 * 33] * g0.y); o.y = cvt_pk_bf16(s[2 * 33] * g0.z, s[3 * 33] * g0.w); o.z = cvt_pk_bf16(s[4 * 33] * g1.x, s[5 * 33] * g1.y); o.w = cvt_pk_bf16(s[6 * 33] * g1.z, s[7 * 33] * g1.w);
;         if (NT) __builtin_nontemporal_store(o, (u32x4*)(d.dst + (size_t)n * d.K + 8 * c)); else *(u32x4*)(d.dst + (size_t)n * d.K + 8 * c) = o; }
.Lpz_n_last:
	s_waitcnt vmcnt(24)
	v_cvt_pk_bf16_f32 v228, v6, v10
	v_cvt_pk_bf16_f32 v229, v14, v18
	v_cvt_pk_bf16_f32 v230, v22, v26
	v_cvt_pk_bf16_f32 v231, v30, v66
	global_store_dwordx4 v214, v[228:231], s[62:63] sc1
	v_cvt_pk_bf16_f32 v232, v7, v11
	v_cvt_pk_bf16_f32 v233, v15, v19
	v_cvt_pk_bf16_f32 v234, v23, v27
	v_cvt_pk_bf16_f32 v235, v31, v67
	global_store_dwordx4 v215, v[232:235], s[62:63] sc1
	v_cvt_pk_bf16_f32 v228, v8, v12
	v_cvt_pk_bf16_f32 v229, v16, v20
	v_cvt_pk_bf16_f32 v230, v24, v28
	v_cvt_pk_bf16_f32 v231, v32, v68
	global_store_dwordx4 v219, v[228:231], s[62:63] sc1
	v_cvt_pk_bf16_f32 v232, v9, v13
	v_cvt_pk_bf16_f32 v233, v17, v21
	v_cvt_pk_bf16_f32 v234, v25, v29
	v_cvt_pk_bf16_f32 v235, v33, v69
	global_store_dwordx4 v236, v[232:235], s[62:63] sc1
	s_waitcnt vmcnt(20)
	v_cvt_pk_bf16_f32 v228, v100, v104
	v_cvt_pk_bf16_f32 v229, v108, v112
	v_cvt_pk_bf16_f32 v230, v116, v132
	v_cvt_pk_bf16_f32 v231, v136, v140
	global_store_dwordx4 v214, v[228:231], s[64:65] sc1
	v_cvt_pk_bf16_f32 v232, v101, v105
	v_cvt_pk_bf16_f32 v233, v109, v113
	v_cvt_pk_bf16_f32 v234, v117, v133
	v_cvt_pk_bf16_f32 v235, v137, v141
	global_store_dwordx4 v215, v[232:235], s[64:65] sc1
	v_cvt_pk_bf16_f32 v228, v102, v106
	v_cvt_pk_bf16_f32 v229, v110, v114
	v_cvt_pk_bf16_f32 v230, v118, v134
	v_cvt_pk_bf16_f32 v231, v138, v142
	global_store_dwordx4 v219, v[228:231], s[64:65] sc1
	v_cvt_pk_bf16_f32 v232, v103, v107
	v_cvt_pk_bf16_f32 v233, v111, v115
	v_cvt_pk_bf16_f32 v234, v119, v135
	v_cvt_pk_bf16_f32 v235, v139, v143
	global_store_dwordx4 v236, v[232:235], s[64:65] sc1
	s_waitcnt vmcnt(16)
	v_cvt_pk_bf16_f32 v228, v148, v152
	v_cvt_pk_bf16_f32 v229, v156, v160
	v_cvt_pk_bf16_f32 v230, v166, v170
	v_cvt_pk_bf16_f32 v231, v174, v178
	global_store_dwordx4 v214, v[228:231], s[66:67] sc1
	v_cvt_pk_bf16_f32 v232, v149, v153
	v_cvt_pk_bf16_f32 v233, v157, v161
	v_cvt_pk_bf16_f32 v234, v167, v171
	v_cvt_pk_bf16_f32 v235, v175, v179
	global_store_dwordx4 v215, v[232:235], s[66:67] sc1
	v_cvt_pk_bf16_f32 v228, v150, v154
	v_cvt_pk_bf16_f32 v229, v158, v162
	v_cvt_pk_bf16_f32 v230, v168, v172
	v_cvt_pk_bf16_f32 v231, v176, v180
	global_store_dwordx4 v219, v[228:231], s[66:67] sc1
	v_cvt_pk_bf16_f32 v232, v151, v155
	v_cvt_pk_bf16_f32 v233, v159, v163
	v_cvt_pk_bf16_f32 v234, v169, v173
	v_cvt_pk_bf16_f32 v235, v177, v181
	global_store_dwordx4 v236, v[232:235], s[66:67] sc1
	s_waitcnt vmcnt(12)
	v_cvt_pk_bf16_f32 v228, v182, v186
	v_cvt_pk_bf16_f32 v229, v190, v194
	v_cvt_pk_bf16_f32 v230, v198, v202
	v_cvt_pk_bf16_f32 v231, v206, v210
	global_store_dwordx4 v214, v[228:231], s[68:69] sc1
	v_cvt_pk_bf16_f32 v232, v183, v187
	v_cvt_pk_bf16_f32 v233, v191, v195
	v_cvt_pk_bf16_f32 v234, v199, v203
	v_cvt_pk_bf16_f32 v235, v207, v211
	global_store_dwordx4 v215, v[232:235], s[68:69] sc1
	v_cvt_pk_bf16_f32 v228, v184, v188
	v_cvt_pk_bf16_f32 v229, v192, v196
	v_cvt_pk_bf16_f32 v230, v200, v204
	v_cvt_pk_bf16_f32 v231, v208, v212
	global_store_dwordx4 v219, v[228:231], s[68:69] sc1
	v_cvt_pk_bf16_f32 v232, v185, v189
	v_cvt_pk_bf16_f32 v233, v193, v197
	v_cvt_pk_bf16_f32 v234, v201, v205
	v_cvt_pk_bf16_f32 v235, v209, v213
	global_store_dwordx4 v236, v[232:235], s[68:69] sc1
	s_branch .Lpz_ret

; #define LAS __attribute__((address_space(3)))
; __device__ __forceinline__ unsigned cvt_pk_bf16(float lo, float hi) { unsigned r; asm volatile("v_cvt_pk_bf16_f32 %0, %1, %2" : "=v"(r) : "v"(lo), "v"(hi)); return r; }
; #define LDS_WAIT() asm volatile("s_waitcnt lgkmcnt(0)" ::: "memory")
; __device__ __forceinline__ unsigned cvt_pk_bf16(float lo, float hi) { unsigned r; asm volatile("v_cvt_pk_bf16_f32 %0, %1, %2" : "=v"(r) : "v"(lo), "v"(hi)); return r; }
; template <bool NT = true> __device__ __forceinline__ void tr_finish(const TrDesc& d, const f32x4 (&v)[8], LAS float* scr, int lane) {
;     const int c = lane & 7;
;     f32x4 g0 = {1.f, 1.f, 1.f, 1.f}, g1 = {1.f, 1.f, 1.f, 1.f};
;     if (d.gain) { g0 = *(const f32x4*)(d.gain + 8 * c); g1 = *(const f32x4*)(d.gain + 8 * c + 4); }
; #pragma unroll
;     for (int i = 0; i < 8; ++i) { LAS float* w = scr + (8 * i + (lane >> 3)) * 33 + 4 * c; w[0] = v[i].x; w[1] = v[i].y; w[2] = v[i].z; w[3] = v[i].w; }
;     LDS_WAIT(); asm volatile("" ::: "memory");
; #pragma unroll
;     for (int j = 0; j < 4; ++j) { const int n = (lane >> 3) + 8 * j; const LAS float* s = scr + (8 * c) * 33 + n;
;         u32x4 o; o.x = cvt_pk_bf16(s[0 * 33] * g0.x, s[1 * 33] * g0.y); o.y = cvt_pk_bf16(s[2 * 33] * g0.z, s[3 * 33] * g0.w); o.z = cvt_pk_bf16(s[4 * 33] * g1.x, s[5 * 33] * g1.y); o.w = cvt_pk_bf16(s[6 * 33] * g1.z, s[7 * 33] * g1.w);
;         if (NT) __builtin_nontemporal_store(o, (u32x4*)(d.dst + (size_t)n * d.K + 8 * c)); else *(u32x4*)(d.dst + (size_t)n * d.K + 8 * c) = o; }
;     LDS_WAIT(); asm volatile("" ::: "memory");
.LBB0_171:
	ds_write2_b32 v115, v66, v67 offset1:1
	ds_write2_b32 v115, v68, v69 offset0:2 offset1:3
	ds_write2_b32 v117, v70, v71 offset1:1
	ds_write2_b32 v118, v72, v73 offset1:1
	ds_write2_b32 v119, v74, v75 offset1:1
	ds_write2_b32 v120, v76, v77 offset1:1
	ds_write2_b32 v121, v78, v79 offset1:1
	ds_write2_b32 v122, v80, v81 offset1:1
	ds_write2_b32 v123, v82, v83 offset1:1
	ds_write2_b32 v124, v84, v85 offset1:1
	ds_write2_b32 v125, v86, v87 offset1:1
	ds_write2_b32 v126, v88, v89 offset1:1
	ds_write2_b32 v127, v90, v91 offset1:1
	ds_write2_b32 v128, v92, v93 offset1:1
	ds_write2_b32 v129, v94, v95 offset1:1
	ds_write2_b32 v130, v96, v97 offset1:1
	s_waitcnt lgkmcnt(0)
	ds_read2_b32 v[118:119], v113 offset1:33
	v_mad_i64_i32 v[124:125], s[14:15], s93, v109, 0
	v_lshl_add_u64 v[124:125], v[124:125], 1, s[4:5]
	v_lshl_add_u64 v[124:125], v[124:125], 0, v[110:111]
	s_waitcnt vmcnt(0) lgkmcnt(0)
	v_mul_f32_e32 v107, v102, v118
	v_mul_f32_e32 v117, v103, v119
	v_cvt_pk_bf16_f32 v118, v107, v117
	ds_read2_b32 v[120:121], v113 offset0:66 offset1:99
	s_waitcnt lgkmcnt(0)
	v_mul_f32_e32 v107, v104, v120
	v_mul_f32_e32 v117, v105, v121
	v_cvt_pk_bf16_f32 v119, v107, v117
	ds_read2_b32 v[120:121], v113 offset0:132 offset1:165
	s_waitcnt lgkmcnt(0)
	v_mul_f32_e32 v107, v98, v120
	v_mul_f32_e32 v117, v99, v121
	v_cvt_pk_bf16_f32 v120, v107, v117
	ds_read2_b32 v[122:123], v113 offset0:198 offset1:231
	s_waitcnt lgkmcnt(0)
	v_mul_f32_e32 v107, v100, v122
	v_mul_f32_e32 v117, v101, v123
	v_cvt_pk_bf16_f32 v121, v107, v117
	ds_read2_b32 v[122:123], v113 offset0:8 offset1:41
	global_store_dwordx4 v[124:125], v[118:121], off sc1
	v_mad_i64_i32 v[124:125], s[14:15], s93, v112, 0
	v_lshl_add_u64 v[124:125], v[124:125], 1, s[4:5]
	s_waitcnt lgkmcnt(0)
	v_mul_f32_e32 v107, v102, v122
	v_mul_f32_e32 v117, v103, v123
	v_cvt_pk_bf16_f32 v118, v107, v117
	ds_read2_b32 v[120:121], v113 offset0:74 offset1:107
	v_lshl_add_u64 v[124:125], v[124:125], 0, v[110:111]
	s_waitcnt lgkmcnt(0)
	v_mul_f32_e32 v107, v104, v120
	v_mul_f32_e32 v117, v105, v121
	v_cvt_pk_bf16_f32 v119, v107, v117
	ds_read2_b32 v[120:121], v113 offset0:140 offset1:173
	s_waitcnt lgkmcnt(0)
	v_mul_f32_e32 v107, v98, v120
	v_mul_f32_e32 v117, v99, v121
	v_cvt_pk_bf16_f32 v120, v107, v117
	ds_read2_b32 v[122:123], v113 offset0:206 offset1:239
	s_waitcnt lgkmcnt(0)
	v_mul_f32_e32 v107, v100, v122
	v_mul_f32_e32 v117, v101, v123
	v_cvt_pk_bf16_f32 v121, v107, v117
	ds_read2_b32 v[122:123], v113 offset0:16 offset1:49
	global_store_dwordx4 v[124:125], v[118:121], off sc1
	v_mad_i64_i32 v[124:125], s[14:15], s93, v114, 0
	v_lshl_add_u64 v[124:125], v[124:125], 1, s[4:5]
	s_waitcnt lgkmcnt(0)
	v_mul_f32_e32 v107, v102, v122
	v_mul_f32_e32 v117, v103, v123
	v_cvt_pk_bf16_f32 v118, v107, v117
	ds_read2_b32 v[120:121], v113 offset0:82 offset1:115
	v_lshl_add_u64 v[124:125], v[124:125], 0, v[110:111]
	s_waitcnt lgkmcnt(0)
	v_mul_f32_e32 v107, v104, v120
	v_mul_f32_e32 v117, v105, v121
	v_cvt_pk_bf16_f32 v119, v107, v117
	ds_read2_b32 v[120:121], v113 offset0:148 offset1:181
	s_waitcnt lgkmcnt(0)
	v_mul_f32_e32 v107, v98, v120
	v_mul_f32_e32 v117, v99, v121
	v_cvt_pk_bf16_f32 v120, v107, v117
	ds_read2_b32 v[122:123], v113 offset0:214 offset1:247
	s_waitcnt lgkmcnt(0)
	v_mul_f32_e32 v107, v100, v122
	v_mul_f32_e32 v117, v101, v123
	v_cvt_pk_bf16_f32 v121, v107, v117
	ds_read2_b32 v[122:123], v113 offset0:24 offset1:57
	global_store_dwordx4 v[124:125], v[118:121], off sc1
	s_waitcnt lgkmcnt(0)
	v_mul_f32_e32 v102, v102, v122
	v_mul_f32_e32 v103, v103, v123
	v_cvt_pk_bf16_f32 v102, v102, v103
	ds_read2_b32 v[118:119], v113 offset0:90 offset1:123
	s_waitcnt lgkmcnt(0)
	v_mul_f32_e32 v103, v104, v118
	v_mul_f32_e32 v104, v105, v119
	v_cvt_pk_bf16_f32 v103, v103, v104
	ds_read2_b32 v[104:105], v113 offset0:156 offset1:189
	v_mad_i64_i32 v[118:119], s[14:15], s93, v116, 0
	v_lshl_add_u64 v[118:119], v[118:119], 1, s[4:5]
	s_waitcnt lgkmcnt(0)
	v_mul_f32_e32 v98, v98, v104
	v_mul_f32_e32 v99, v99, v105
	v_cvt_pk_bf16_f32 v104, v98, v99
	ds_read2_b32 v[98:99], v113 offset0:222 offset1:255
	s_waitcnt lgkmcnt(0)
	v_mul_f32_e32 v98, v100, v98
	v_mul_f32_e32 v99, v101, v99
	v_cvt_pk_bf16_f32 v105, v98, v99
	v_lshl_add_u64 v[98:99], v[118:119], 0, v[110:111]
	global_store_dwordx4 v[98:99], v[102:105], off sc1
	s_waitcnt lgkmcnt(0)

; #define LAS __attribute__((address_space(3)))
; __device__ __forceinline__ unsigned cvt_pk_bf16(float lo, float hi) { unsigned r; asm volatile("v_cvt_pk_bf16_f32 %0, %1, %2" : "=v"(r) : "v"(lo), "v"(hi)); return r; }
; #define LDS_WAIT() asm volatile("s_waitcnt lgkmcnt(0)" ::: "memory")
; __device__ __forceinline__ unsigned cvt_pk_bf16(float lo, float hi) { unsigned r; asm volatile("v_cvt_pk_bf16_f32 %0, %1, %2" : "=v"(r) : "v"(lo), "v"(hi)); return r; }
; template <bool NT = true> __device__ __forceinline__ void tr_finish(const TrDesc& d, const f32x4 (&v)[8], LAS float* scr, int lane) {
;     const int c = lane & 7;
;     f32x4 g0 = {1.f, 1.f, 1.f, 1.f}, g1 = {1.f, 1.f, 1.f, 1.f};
;     if (d.gain) { g0 = *(const f32x4*)(d.gain + 8 * c); g1 = *(const f32x4*)(d.gain + 8 * c + 4); }
; #pragma unroll
;     for (int i = 0; i < 8; ++i) { LAS float* w = scr + (8 * i + (lane >> 3)) * 33 + 4 * c; w[0] = v[i].x; w[1] = v[i].y; w[2] = v[i].z; w[3] = v[i].w; }
;     LDS_WAIT(); asm volatile("" ::: "memory");
; #pragma unroll
;     for (int j = 0; j < 4; ++j) { const int n = (lane >> 3) + 8 * j; const LAS float* s = scr + (8 * c) * 33 + n;
;         u32x4 o; o.x = cvt_pk_bf16(s[0 * 33] * g0.x, s[1 * 33] * g0.y); o.y = cvt_pk_bf16(s[2 * 33] * g0.z, s[3 * 33] * g0.w); o.z = cvt_pk_bf16(s[4 * 33] * g1.x, s[5 * 33] * g1.y); o.w = cvt_pk_bf16(s[6 * 33] * g1.z, s[7 * 33] * g1.w);
;         if (NT) __builtin_nontemporal_store(o, (u32x4*)(d.dst + (size_t)n * d.K + 8 * c)); else *(u32x4*)(d.dst + (size_t)n * d.K + 8 * c) = o; }
;     LDS_WAIT(); asm volatile("" ::: "memory");
; template <class F, bool NT = true> __device__ __forceinline__ void tr_run(F item, int first, int step, int n, LAS float* scr, int lane) {
;     ...
;     for (int it = first; it < n; it += 3 * step) {
;         const bool h1 = it + step < n, h2 = it + 2 * step < n, h3 = it + 3 * step < n, h4 = it + 4 * step < n;
;         if (h2) { dc = item(it + 2 * step); tr_load<NT>(dc, vc, lane); }
;         tr_finish<NT>(da, va, scr, lane);
;         if (h3) { da = item(it + 3 * step); tr_load<NT>(da, va, lane); }
.LBB0_188:
	v_add_u32_e32 v117, 0x420, v115
	v_add_u32_e32 v118, 0x428, v115
	v_add_u32_e32 v119, 0x840, v115
	v_add_u32_e32 v120, 0x848, v115
	v_add_u32_e32 v121, 0xc60, v115
	v_add_u32_e32 v122, 0xc68, v115
	v_add_u32_e32 v123, 0x1080, v115
	v_add_u32_e32 v124, 0x1088, v115
	v_add_u32_e32 v125, 0x14a0, v115
	v_add_u32_e32 v126, 0x14a8, v115
	v_add_u32_e32 v127, 0x18c0, v115
	v_add_u32_e32 v128, 0x18c8, v115
	v_add_u32_e32 v129, 0x1ce0, v115
	v_add_u32_e32 v130, 0x1ce8, v115
	s_waitcnt vmcnt(7)
	ds_write2_b32 v115, v2, v3 offset1:1
	ds_write2_b32 v115, v4, v5 offset0:2 offset1:3
	s_waitcnt vmcnt(6)
	ds_write2_b32 v117, v6, v7 offset1:1
	ds_write2_b32 v118, v8, v9 offset1:1
	s_waitcnt vmcnt(5)
	ds_write2_b32 v119, v10, v11 offset1:1
	ds_write2_b32 v120, v12, v13 offset1:1
	s_waitcnt vmcnt(4)
	ds_write2_b32 v121, v14, v15 offset1:1
	ds_write2_b32 v122, v16, v17 offset1:1
	s_waitcnt vmcnt(3)
	ds_write2_b32 v123, v18, v19 offset1:1
	ds_write2_b32 v124, v20, v21 offset1:1
	s_waitcnt vmcnt(2)
	ds_write2_b32 v125, v22, v23 offset1:1
	ds_write2_b32 v126, v24, v25 offset1:1
	s_waitcnt vmcnt(1)
	ds_write2_b32 v127, v26, v27 offset1:1
	ds_write2_b32 v128, v28, v29 offset1:1
	s_waitcnt vmcnt(0)
	ds_write2_b32 v129, v30, v31 offset1:1
	ds_write2_b32 v130, v32, v33 offset1:1
	s_waitcnt lgkmcnt(0)
	ds_read2_b32 v[132:133], v113 offset1:33
	v_mad_i64_i32 v[138:139], s[20:21], s95, v109, 0
	v_lshl_add_u64 v[138:139], v[138:139], 1, s[18:19]
	v_lshl_add_u64 v[138:139], v[138:139], 0, v[110:111]
	s_waitcnt lgkmcnt(0)
	v_mul_f32_e32 v107, v102, v132
	v_mul_f32_e32 v131, v103, v133
	v_cvt_pk_bf16_f32 v132, v107, v131
	ds_read2_b32 v[134:135], v113 offset0:66 offset1:99
	s_mul_i32 s10, s92, 24
	s_add_i32 s10, s10, s36
	s_waitcnt lgkmcnt(0)
	v_mul_f32_e32 v107, v104, v134
	v_mul_f32_e32 v131, v105, v135
	v_cvt_pk_bf16_f32 v133, v107, v131
	ds_read2_b32 v[134:135], v113 offset0:132 offset1:165
	s_waitcnt lgkmcnt(0)
	v_mul_f32_e32 v107, v98, v134
	v_mul_f32_e32 v131, v99, v135
	v_cvt_pk_bf16_f32 v134, v107, v131
	ds_read2_b32 v[136:137], v113 offset0:198 offset1:231
	s_waitcnt lgkmcnt(0)
	v_mul_f32_e32 v107, v100, v136
	v_mul_f32_e32 v131, v101, v137
	v_cvt_pk_bf16_f32 v135, v107, v131
	ds_read2_b32 v[136:137], v113 offset0:8 offset1:41
	global_store_dwordx4 v[138:139], v[132:135], off sc1
	v_mad_i64_i32 v[138:139], s[20:21], s95, v112, 0
	v_lshl_add_u64 v[138:139], v[138:139], 1, s[18:19]
	s_waitcnt lgkmcnt(0)
	v_mul_f32_e32 v107, v102, v136
	v_mul_f32_e32 v131, v103, v137
	v_cvt_pk_bf16_f32 v132, v107, v131
	ds_read2_b32 v[134:135], v113 offset0:74 offset1:107
	v_lshl_add_u64 v[138:139], v[138:139], 0, v[110:111]
	s_waitcnt lgkmcnt(0)
	v_mul_f32_e32 v107, v104, v134
	v_mul_f32_e32 v131, v105, v135
	v_cvt_pk_bf16_f32 v133, v107, v131
	ds_read2_b32 v[134:135], v113 offset0:140 offset1:173
	s_waitcnt lgkmcnt(0)
	v_mul_f32_e32 v107, v98, v134
	v_mul_f32_e32 v131, v99, v135
	v_cvt_pk_bf16_f32 v134, v107, v131
	ds_read2_b32 v[136:137], v113 offset0:206 offset1:239
	s_waitcnt lgkmcnt(0)
	v_mul_f32_e32 v107, v100, v136
	v_mul_f32_e32 v131, v101, v137
	v_cvt_pk_bf16_f32 v135, v107, v131
	ds_read2_b32 v[136:137], v113 offset0:16 offset1:49
	global_store_dwordx4 v[138:139], v[132:135], off sc1
	v_mad_i64_i32 v[138:139], s[20:21], s95, v114, 0
	v_lshl_add_u64 v[138:139], v[138:139], 1, s[18:19]
	s_waitcnt lgkmcnt(0)
	v_mul_f32_e32 v107, v102, v136
	v_mul_f32_e32 v131, v103, v137
	v_cvt_pk_bf16_f32 v132, v107, v131
	ds_read2_b32 v[134:135], v113 offset0:82 offset1:115
	v_lshl_add_u64 v[138:139], v[138:139], 0, v[110:111]
	v_readlane_b32 s20, v240, 29
	v_readlane_b32 s21, v240, 30
	s_add_i32 s37, s37, s20
	s_waitcnt lgkmcnt(0)
	v_mul_f32_e32 v107, v104, v134
	v_mul_f32_e32 v131, v105, v135
	v_cvt_pk_bf16_f32 v133, v107, v131
	ds_read2_b32 v[134:135], v113 offset0:148 offset1:181
	s_cmp_gt_i32 s10, 0x23fff
	s_waitcnt lgkmcnt(0)
	v_mul_f32_e32 v107, v98, v134
	v_mul_f32_e32 v131, v99, v135
	v_cvt_pk_bf16_f32 v134, v107, v131
	ds_read2_b32 v[136:137], v113 offset0:214 offset1:247
	s_waitcnt lgkmcnt(0)
	v_mul_f32_e32 v107, v100, v136
	v_mul_f32_e32 v131, v101, v137
	v_cvt_pk_bf16_f32 v135, v107, v131
	ds_read2_b32 v[136:137], v113 offset0:24 offset1:57
	global_store_dwordx4 v[138:139], v[132:135], off sc1
	s_waitcnt lgkmcnt(0)
	v_mul_f32_e32 v102, v102, v136
	v_mul_f32_e32 v103, v103, v137
	v_cvt_pk_bf16_f32 v102, v102, v103
	ds_read2_b32 v[132:133], v113 offset0:90 offset1:123
	s_waitcnt lgkmcnt(0)
	v_mul_f32_e32 v103, v104, v132
	v_mul_f32_e32 v104, v105, v133
	v_cvt_pk_bf16_f32 v103, v103, v104
	ds_read2_b32 v[104:105], v113 offset0:156 offset1:189
	s_waitcnt lgkmcnt(0)
	v_mul_f32_e32 v98, v98, v104
	v_mul_f32_e32 v99, v99, v105
	v_cvt_pk_bf16_f32 v104, v98, v99
	ds_read2_b32 v[98:99], v113 offset0:222 offset1:255
	s_waitcnt lgkmcnt(0)
	v_mul_f32_e32 v98, v100, v98
	v_mul_f32_e32 v99, v101, v99
	v_cvt_pk_bf16_f32 v105, v98, v99
	v_mad_i64_i32 v[98:99], s[20:21], s95, v116, 0
	v_lshl_add_u64 v[98:99], v[98:99], 1, s[18:19]
	v_lshl_add_u64 v[98:99], v[98:99], 0, v[110:111]
	global_store_dwordx4 v[98:99], v[102:105], off sc1
	s_waitcnt lgkmcnt(0)
	s_cbranch_scc1 .LBB0_200
	s_cmpk_gt_i32 s10, 0xcfff
	s_cselect_b64 s[22:23], -1, 0
	s_mov_b64 s[24:25], -1
	s_and_b64 vcc, exec, s[22:23]
	s_cbranch_vccz .LBB0_192
	s_andn2_b64 vcc, exec, s[24:25]
	s_cbranch_vccz .LBB0_193

; #define LAS __attribute__((address_space(3)))
; __device__ __forceinline__ unsigned cvt_pk_bf16(float lo, float hi) { unsigned r; asm volatile("v_cvt_pk_bf16_f32 %0, %1, %2" : "=v"(r) : "v"(lo), "v"(hi)); return r; }
; #define LDS_WAIT() asm volatile("s_waitcnt lgkmcnt(0)" ::: "memory")
; __device__ __forceinline__ unsigned cvt_pk_bf16(float lo, float hi) { unsigned r; asm volatile("v_cvt_pk_bf16_f32 %0, %1, %2" : "=v"(r) : "v"(lo), "v"(hi)); return r; }
; template <bool NT = true> __device__ __forceinline__ void tr_finish(const TrDesc& d, const f32x4 (&v)[8], LAS float* scr, int lane) {
;     const int c = lane & 7;
;     f32x4 g0 = {1.f, 1.f, 1.f, 1.f}, g1 = {1.f, 1.f, 1.f, 1.f};
;     if (d.gain) { g0 = *(const f32x4*)(d.gain + 8 * c); g1 = *(const f32x4*)(d.gain + 8 * c + 4); }
; #pragma unroll
;     for (int i = 0; i < 8; ++i) { LAS float* w = scr + (8 * i + (lane >> 3)) * 33 + 4 * c; w[0] = v[i].x; w[1] = v[i].y; w[2] = v[i].z; w[3] = v[i].w; }
;     LDS_WAIT(); asm volatile("" ::: "memory");
; #pragma unroll
;     for (int j = 0; j < 4; ++j) { const int n = (lane >> 3) + 8 * j; const LAS float* s = scr + (8 * c) * 33 + n;
;         u32x4 o; o.x = cvt_pk_bf16(s[0 * 33] * g0.x, s[1 * 33] * g0.y); o.y = cvt_pk_bf16(s[2 * 33] * g0.z, s[3 * 33] * g0.w); o.z = cvt_pk_bf16(s[4 * 33] * g1.x, s[5 * 33] * g1.y); o.w = cvt_pk_bf16(s[6 * 33] * g1.z, s[7 * 33] * g1.w);
;         if (NT) __builtin_nontemporal_store(o, (u32x4*)(d.dst + (size_t)n * d.K + 8 * c)); else *(u32x4*)(d.dst + (size_t)n * d.K + 8 * c) = o; }
;     LDS_WAIT(); asm volatile("" ::: "memory");
.LBB0_204:
	ds_write2_b32 v115, v34, v35 offset1:1
	ds_write2_b32 v115, v36, v37 offset0:2 offset1:3
	ds_write2_b32 v117, v38, v39 offset1:1
	ds_write2_b32 v118, v40, v41 offset1:1
	ds_write2_b32 v119, v42, v43 offset1:1
	ds_write2_b32 v120, v44, v45 offset1:1
	ds_write2_b32 v121, v46, v47 offset1:1
	ds_write2_b32 v122, v48, v49 offset1:1
	ds_write2_b32 v123, v50, v51 offset1:1
	ds_write2_b32 v124, v52, v53 offset1:1
	ds_write2_b32 v125, v54, v55 offset1:1
	ds_write2_b32 v126, v56, v57 offset1:1
	ds_write2_b32 v127, v58, v59 offset1:1
	ds_write2_b32 v128, v60, v61 offset1:1
	ds_write2_b32 v129, v62, v63 offset1:1
	ds_write2_b32 v130, v64, v65 offset1:1
	s_waitcnt lgkmcnt(0)
	ds_read2_b32 v[132:133], v113 offset1:33
	v_mad_i64_i32 v[138:139], s[20:21], s43, v109, 0
	v_lshl_add_u64 v[138:139], v[138:139], 1, s[8:9]
	v_lshl_add_u64 v[138:139], v[138:139], 0, v[110:111]
	s_waitcnt vmcnt(0) lgkmcnt(0)
	v_mul_f32_e32 v107, v102, v132
	v_mul_f32_e32 v131, v103, v133
	v_cvt_pk_bf16_f32 v132, v107, v131
	ds_read2_b32 v[134:135], v113 offset0:66 offset1:99
	s_waitcnt lgkmcnt(0)
	v_mul_f32_e32 v107, v104, v134
	v_mul_f32_e32 v131, v105, v135
	v_cvt_pk_bf16_f32 v133, v107, v131
	ds_read2_b32 v[134:135], v113 offset0:132 offset1:165
	s_waitcnt lgkmcnt(0)
	v_mul_f32_e32 v107, v98, v134
	v_mul_f32_e32 v131, v99, v135
	v_cvt_pk_bf16_f32 v134, v107, v131
	ds_read2_b32 v[136:137], v113 offset0:198 offset1:231
	s_waitcnt lgkmcnt(0)
	v_mul_f32_e32 v107, v100, v136
	v_mul_f32_e32 v131, v101, v137
	v_cvt_pk_bf16_f32 v135, v107, v131
	ds_read2_b32 v[136:137], v113 offset0:8 offset1:41
	global_store_dwordx4 v[138:139], v[132:135], off sc1
	v_mad_i64_i32 v[138:139], s[20:21], s43, v112, 0
	v_lshl_add_u64 v[138:139], v[138:139], 1, s[8:9]
	s_waitcnt lgkmcnt(0)
	v_mul_f32_e32 v107, v102, v136
	v_mul_f32_e32 v131, v103, v137
	v_cvt_pk_bf16_f32 v132, v107, v131
	ds_read2_b32 v[134:135], v113 offset0:74 offset1:107
	v_lshl_add_u64 v[138:139], v[138:139], 0, v[110:111]
	s_waitcnt lgkmcnt(0)
	v_mul_f32_e32 v107, v104, v134
	v_mul_f32_e32 v131, v105, v135
	v_cvt_pk_bf16_f32 v133, v107, v131
	ds_read2_b32 v[134:135], v113 offset0:140 offset1:173
	s_waitcnt lgkmcnt(0)
	v_mul_f32_e32 v107, v98, v134
	v_mul_f32_e32 v131, v99, v135
	v_cvt_pk_bf16_f32 v134, v107, v131
	ds_read2_b32 v[136:137], v113 offset0:206 offset1:239
	s_waitcnt lgkmcnt(0)
	v_mul_f32_e32 v107, v100, v136
	v_mul_f32_e32 v131, v101, v137
	v_cvt_pk_bf16_f32 v135, v107, v131
	ds_read2_b32 v[136:137], v113 offset0:16 offset1:49
	global_store_dwordx4 v[138:139], v[132:135], off sc1
	v_mad_i64_i32 v[138:139], s[20:21], s43, v114, 0
	v_lshl_add_u64 v[138:139], v[138:139], 1, s[8:9]
	s_waitcnt lgkmcnt(0)
	v_mul_f32_e32 v107, v102, v136
	v_mul_f32_e32 v131, v103, v137
	v_cvt_pk_bf16_f32 v132, v107, v131
	ds_read2_b32 v[134:135], v113 offset0:82 offset1:115
	v_lshl_add_u64 v[138:139], v[138:139], 0, v[110:111]
	s_waitcnt lgkmcnt(0)
	v_mul_f32_e32 v107, v104, v134
	v_mul_f32_e32 v131, v105, v135
	v_cvt_pk_bf16_f32 v133, v107, v131
	ds_read2_b32 v[134:135], v113 offset0:148 offset1:181
	s_waitcnt lgkmcnt(0)
	v_mul_f32_e32 v107, v98, v134
	v_mul_f32_e32 v131, v99, v135
	v_cvt_pk_bf16_f32 v134, v107, v131
	ds_read2_b32 v[136:137], v113 offset0:214 offset1:247
	s_waitcnt lgkmcnt(0)
	v_mul_f32_e32 v107, v100, v136
	v_mul_f32_e32 v131, v101, v137
	v_cvt_pk_bf16_f32 v135, v107, v131
	ds_read2_b32 v[136:137], v113 offset0:24 offset1:57
	global_store_dwordx4 v[138:139], v[132:135], off sc1
	s_waitcnt lgkmcnt(0)
	v_mul_f32_e32 v102, v102, v136
	v_mul_f32_e32 v103, v103, v137
	v_cvt_pk_bf16_f32 v102, v102, v103
	ds_read2_b32 v[132:133], v113 offset0:90 offset1:123
	s_waitcnt lgkmcnt(0)
	v_mul_f32_e32 v103, v104, v132
	v_mul_f32_e32 v104, v105, v133
	v_cvt_pk_bf16_f32 v103, v103, v104
	ds_read2_b32 v[104:105], v113 offset0:156 offset1:189
	v_mad_i64_i32 v[132:133], s[20:21], s43, v116, 0
	v_lshl_add_u64 v[132:133], v[132:133], 1, s[8:9]
	s_waitcnt lgkmcnt(0)
	v_mul_f32_e32 v98, v98, v104
	v_mul_f32_e32 v99, v99, v105
	v_cvt_pk_bf16_f32 v104, v98, v99
	ds_read2_b32 v[98:99], v113 offset0:222 offset1:255
	s_waitcnt lgkmcnt(0)
	v_mul_f32_e32 v98, v100, v98
	v_mul_f32_e32 v99, v101, v99
	v_cvt_pk_bf16_f32 v105, v98, v99
	v_lshl_add_u64 v[98:99], v[132:133], 0, v[110:111]
	global_store_dwordx4 v[98:99], v[102:105], off sc1
	s_waitcnt lgkmcnt(0)

; #define LAS __attribute__((address_space(3)))
; __device__ __forceinline__ unsigned cvt_pk_bf16(float lo, float hi) { unsigned r; asm volatile("v_cvt_pk_bf16_f32 %0, %1, %2" : "=v"(r) : "v"(lo), "v"(hi)); return r; }
; #define LDS_WAIT() asm volatile("s_waitcnt lgkmcnt(0)" ::: "memory")
; __device__ __forceinline__ unsigned cvt_pk_bf16(float lo, float hi) { unsigned r; asm volatile("v_cvt_pk_bf16_f32 %0, %1, %2" : "=v"(r) : "v"(lo), "v"(hi)); return r; }
; template <bool NT = true> __device__ __forceinline__ void tr_load(const TrDesc& d, f32x4 (&v)[8], int lane) {
;     const float* sp = d.src + (size_t)(lane >> 3) * d.ldn + 4 * (lane & 7);
; #pragma unroll
;     for (int i = 0; i < 8; ++i) v[i] = NT ? __builtin_nontemporal_load((const f32x4*)(sp + (size_t)(8 * i) * d.ldn)) : *(const f32x4*)(sp + (size_t)(8 * i) * d.ldn);
; }
; template <bool NT = true> __device__ __forceinline__ void tr_finish(const TrDesc& d, const f32x4 (&v)[8], LAS float* scr, int lane) {
;     const int c = lane & 7;
;     f32x4 g0 = {1.f, 1.f, 1.f, 1.f}, g1 = {1.f, 1.f, 1.f, 1.f};
;     if (d.gain) { g0 = *(const f32x4*)(d.gain + 8 * c); g1 = *(const f32x4*)(d.gain + 8 * c + 4); }
; #pragma unroll
;     for (int i = 0; i < 8; ++i) { LAS float* w = scr + (8 * i + (lane >> 3)) * 33 + 4 * c; w[0] = v[i].x; w[1] = v[i].y; w[2] = v[i].z; w[3] = v[i].w; }
;     LDS_WAIT(); asm volatile("" ::: "memory");
; #pragma unroll
;     for (int j = 0; j < 4; ++j) { const int n = (lane >> 3) + 8 * j; const LAS float* s = scr + (8 * c) * 33 + n;
;         u32x4 o; o.x = cvt_pk_bf16(s[0 * 33] * g0.x, s[1 * 33] * g0.y); o.y = cvt_pk_bf16(s[2 * 33] * g0.z, s[3 * 33] * g0.w); o.z = cvt_pk_bf16(s[4 * 33] * g1.x, s[5 * 33] * g1.y); o.w = cvt_pk_bf16(s[6 * 33] * g1.z, s[7 * 33] * g1.w);
;         if (NT) __builtin_nontemporal_store(o, (u32x4*)(d.dst + (size_t)n * d.K + 8 * c)); else *(u32x4*)(d.dst + (size_t)n * d.K + 8 * c) = o; }
.Lcv_run:
	s_cmp_eq_u32 s74, 0
	s_cbranch_scc1 .Lcv_ret
	v_mul_lo_u32 v189, v3, s6
	v_lshlrev_b32_e32 v189, 3, v189
	v_lshl_add_u32 v174, v132, 4, v189
	v_add_u32_e32 v175, s6, v174
	v_add_u32_e32 v176, s6, v175
	v_add_u32_e32 v177, s6, v176
	v_add_u32_e32 v178, s6, v177
	v_add_u32_e32 v179, s6, v178
	v_add_u32_e32 v180, s6, v179
	v_add_u32_e32 v181, s6, v180
	v_lshlrev_b32_e32 v190, 2, v132
	v_mul_lo_u32 v190, v190, s7
	v_lshl_add_u32 v182, v3, 4, v190
	v_add_u32_e32 v183, s7, v182
	v_add_u32_e32 v184, s7, v183
	v_add_u32_e32 v185, s7, v184
	s_cmp_eq_u32 s8, 0
	s_cbranch_scc1 .Lcv_nogain
	global_load_dwordx4 v[166:169], v186, s[4:5]
	global_load_dwordx4 v[170:173], v186, s[4:5] offset:16
	global_load_dwordx4 v[4:7], v174, s[60:61] offset:0 nt
	global_load_dwordx4 v[8:11], v175, s[60:61] offset:0 nt
	global_load_dwordx4 v[12:15], v176, s[60:61] offset:0 nt
	global_load_dwordx4 v[16:19], v177, s[60:61] offset:0 nt
	global_load_dwordx4 v[20:23], v178, s[60:61] offset:0 nt
	global_load_dwordx4 v[24:27], v179, s[60:61] offset:0 nt
	global_load_dwordx4 v[28:31], v180, s[60:61] offset:0 nt
	global_load_dwordx4 v[32:35], v181, s[60:61] offset:0 nt
	global_load_dwordx4 v[36:39], v174, s[60:61] offset:128 nt
	global_load_dwordx4 v[40:43], v175, s[60:61] offset:128 nt
	global_load_dwordx4 v[44:47], v176, s[60:61] offset:128 nt
	global_load_dwordx4 v[48:51], v177, s[60:61] offset:128 nt
	global_load_dwordx4 v[52:55], v178, s[60:61] offset:128 nt
	global_load_dwordx4 v[56:59], v179, s[60:61] offset:128 nt
	global_load_dwordx4 v[60:63], v180, s[60:61] offset:128 nt
	global_load_dwordx4 v[64:67], v181, s[60:61] offset:128 nt
	global_load_dwordx4 v[68:71], v174, s[60:61] offset:256 nt
	global_load_dwordx4 v[72:75], v175, s[60:61] offset:256 nt
	global_load_dwordx4 v[76:79], v176, s[60:61] offset:256 nt
	global_load_dwordx4 v[80:83], v177, s[60:61] offset:256 nt
	global_load_dwordx4 v[84:87], v178, s[60:61] offset:256 nt
	global_load_dwordx4 v[88:91], v179, s[60:61] offset:256 nt
	global_load_dwordx4 v[92:95], v180, s[60:61] offset:256 nt
	global_load_dwordx4 v[96:99], v181, s[60:61] offset:256 nt
	global_load_dwordx4 v[100:103], v174, s[60:61] offset:384 nt
	global_load_dwordx4 v[104:107], v175, s[60:61] offset:384 nt
	global_load_dwordx4 v[108:111], v176, s[60:61] offset:384 nt
	global_load_dwordx4 v[112:115], v177, s[60:61] offset:384 nt
	global_load_dwordx4 v[116:119], v178, s[60:61] offset:384 nt
	global_load_dwordx4 v[120:123], v179, s[60:61] offset:384 nt
	global_load_dwordx4 v[124:127], v180, s[60:61] offset:384 nt
	global_load_dwordx4 v[128:131], v181, s[60:61] offset:384 nt
	s_add_u32 s60, s60, s70
	s_addc_u32 s61, s61, s71
	s_cmp_eq_u32 s74, 1
	s_cbranch_scc1 .Lcv_g_last
	s_waitcnt vmcnt(24)
	v_mul_f32_e32 v4, v166, v4
	v_mul_f32_e32 v5, v166, v5
	v_mul_f32_e32 v6, v166, v6
	v_mul_f32_e32 v7, v166, v7
	v_mul_f32_e32 v8, v167, v8
	v_mul_f32_e32 v9, v167, v9
	v_mul_f32_e32 v10, v167, v10
	v_mul_f32_e32 v11, v167, v11
	v_mul_f32_e32 v12, v168, v12
	v_mul_f32_e32 v13, v168, v13
	v_mul_f32_e32 v14, v168, v14
	v_mul_f32_e32 v15, v168, v15
	v_mul_f32_e32 v16, v169, v16
	v_mul_f32_e32 v17, v169, v17
	v_mul_f32_e32 v18, v169, v18
	v_mul_f32_e32 v19, v169, v19
	v_mul_f32_e32 v20, v170, v20
	v_mul_f32_e32 v21, v170, v21
	v_mul_f32_e32 v22, v170, v22
	v_mul_f32_e32 v23, v170, v23
	v_mul_f32_e32 v24, v171, v24
	v_mul_f32_e32 v25, v171, v25
	v_mul_f32_e32 v26, v171, v26
	v_mul_f32_e32 v27, v171, v27
	v_mul_f32_e32 v28, v172, v28
	v_mul_f32_e32 v29, v172, v29
	v_mul_f32_e32 v30, v172, v30
	v_mul_f32_e32 v31, v172, v31
	v_mul_f32_e32 v32, v173, v32
	v_mul_f32_e32 v33, v173, v33
	v_mul_f32_e32 v34, v173, v34
	v_mul_f32_e32 v35, v173, v35
	v_cvt_pk_bf16_f32 v188, v4, v8
	v_cvt_pk_bf16_f32 v189, v12, v16
	v_cvt_pk_bf16_f32 v190, v20, v24
	v_cvt_pk_bf16_f32 v191, v28, v32
	global_store_dwordx4 v182, v[188:191], s[62:63] sc1
	v_cvt_pk_bf16_f32 v192, v5, v9
	v_cvt_pk_bf16_f32 v193, v13, v17
	v_cvt_pk_bf16_f32 v194, v21, v25
	v_cvt_pk_bf16_f32 v195, v29, v33
	global_store_dwordx4 v183, v[192:195], s[62:63] sc1
	v_cvt_pk_bf16_f32 v196, v6, v10
	v_cvt_pk_bf16_f32 v197, v14, v18
	v_cvt_pk_bf16_f32 v198, v22, v26
	v_cvt_pk_bf16_f32 v199, v30, v34
	global_store_dwordx4 v184, v[196:199], s[62:63] sc1
	v_cvt_pk_bf16_f32 v200, v7, v11
	v_cvt_pk_bf16_f32 v201, v15, v19
	v_cvt_pk_bf16_f32 v202, v23, v27
	v_cvt_pk_bf16_f32 v203, v31, v35
	global_store_dwordx4 v185, v[200:203], s[62:63] sc1
	global_load_dwordx4 v[4:7], v174, s[60:61] offset:0 nt
	global_load_dwordx4 v[8:11], v175, s[60:61] offset:0 nt
	global_load_dwordx4 v[12:15], v176, s[60:61] offset:0 nt
	global_load_dwordx4 v[16:19], v177, s[60:61] offset:0 nt
	global_load_dwordx4 v[20:23], v178, s[60:61] offset:0 nt
	global_load_dwordx4 v[24:27], v179, s[60:61] offset:0 nt
	global_load_dwordx4 v[28:31], v180, s[60:61] offset:0 nt
	global_load_dwordx4 v[32:35], v181, s[60:61] offset:0 nt
	s_add_u32 s62, s62, s72
	s_addc_u32 s63, s63, s73
	s_waitcnt vmcnt(28)
; #define LAS __attribute__((address_space(3)))
; __device__ __forceinline__ unsigned cvt_pk_bf16(float lo, float hi) { unsigned r; asm volatile("v_cvt_pk_bf16_f32 %0, %1, %2" : "=v"(r) : "v"(lo), "v"(hi)); return r; }
; template <bool NT = true> __device__ __forceinline__ void tr_load(const TrDesc& d, f32x4 (&v)[8], int lane) {
;     const float* sp = d.src + (size_t)(lane >> 3) * d.ldn + 4 * (lane & 7);
; #pragma unroll
;     for (int i = 0; i < 8; ++i) v[i] = NT ? __builtin_nontemporal_load((const f32x4*)(sp + (size_t)(8 * i) * d.ldn)) : *(const f32x4*)(sp + (size_t)(8 * i) * d.ldn);
; }
; template <bool NT = true> __device__ __forceinline__ void tr_finish(const TrDesc& d, const f32x4 (&v)[8], LAS float* scr, int lane) {
;     const int c = lane & 7;
;     f32x4 g0 = {1.f, 1.f, 1.f, 1.f}, g1 = {1.f, 1.f, 1.f, 1.f};
;     if (d.gain) { g0 = *(const f32x4*)(d.gain + 8 * c); g1 = *(const f32x4*)(d.gain + 8 * c + 4); }
; #pragma unroll
;     for (int i = 0; i < 8; ++i) { LAS float* w = scr + (8 * i + (lane >> 3)) * 33 + 4 * c; w[0] = v[i].x; w[1] = v[i].y; w[2] = v[i].z; w[3] = v[i].w; }
;     LDS_WAIT(); asm volatile("" ::: "memory");
; #pragma unroll
;     for (int j = 0; j < 4; ++j) { const int n = (lane >> 3) + 8 * j; const LAS float* s = scr + (8 * c) * 33 + n;
;         u32x4 o; o.x = cvt_pk_bf16(s[0 * 33] * g0.x, s[1 * 33] * g0.y); o.y = cvt_pk_bf16(s[2 * 33] * g0.z, s[3 * 33] * g0.w); o.z = cvt_pk_bf16(s[4 * 33] * g1.x, s[5 * 33] * g1.y); o.w = cvt_pk_bf16(s[6 * 33] * g1.z, s[7 * 33] * g1.w);
;         if (NT) __builtin_nontemporal_store(o, (u32x4*)(d.dst + (size_t)n * d.K + 8 * c)); else *(u32x4*)(d.dst + (size_t)n * d.K + 8 * c) = o; }
; template <class F, bool NT = true> __device__ __forceinline__ void tr_run(F item, int first, int step, int n, LAS float* scr, int lane) {
;     ...
;     for (int it = first; it < n; it += 3 * step) {
;         const bool h1 = it + step < n, h2 = it + 2 * step < n, h3 = it + 3 * step < n, h4 = it + 4 * step < n;
;         if (h2) { dc = item(it + 2 * step); tr_load<NT>(dc, vc, lane); }
;         tr_finish<NT>(da, va, scr, lane);
;         if (h3) { da = item(it + 3 * step); tr_load<NT>(da, va, lane); }
;         if (h1) tr_finish<NT>(db, vb, scr, lane);
;         if (h4) { db = item(it + 4 * step); tr_load<NT>(db, vb, lane); }
;         if (h2) tr_finish<NT>(dc, vc, scr, lane);
;     }
	v_mul_f32_e32 v36, v166, v36
	v_mul_f32_e32 v37, v166, v37
	v_mul_f32_e32 v38, v166, v38
	v_mul_f32_e32 v39, v166, v39
	v_mul_f32_e32 v40, v167, v40
	v_mul_f32_e32 v41, v167, v41
	v_mul_f32_e32 v42, v167, v42
	v_mul_f32_e32 v43, v167, v43
	v_mul_f32_e32 v44, v168, v44
	v_mul_f32_e32 v45, v168, v45
	v_mul_f32_e32 v46, v168, v46
	v_mul_f32_e32 v47, v168, v47
	v_mul_f32_e32 v48, v169, v48
	v_mul_f32_e32 v49, v169, v49
	v_mul_f32_e32 v50, v169, v50
	v_mul_f32_e32 v51, v169, v51
	v_mul_f32_e32 v52, v170, v52
	v_mul_f32_e32 v53, v170, v53
	v_mul_f32_e32 v54, v170, v54
	v_mul_f32_e32 v55, v170, v55
	v_mul_f32_e32 v56, v171, v56
	v_mul_f32_e32 v57, v171, v57
	v_mul_f32_e32 v58, v171, v58
	v_mul_f32_e32 v59, v171, v59
	v_mul_f32_e32 v60, v172, v60
	v_mul_f32_e32 v61, v172, v61
	v_mul_f32_e32 v62, v172, v62
	v_mul_f32_e32 v63, v172, v63
	v_mul_f32_e32 v64, v173, v64
	v_mul_f32_e32 v65, v173, v65
	v_mul_f32_e32 v66, v173, v66
	v_mul_f32_e32 v67, v173, v67
	v_cvt_pk_bf16_f32 v188, v36, v40
	v_cvt_pk_bf16_f32 v189, v44, v48
	v_cvt_pk_bf16_f32 v190, v52, v56
	v_cvt_pk_bf16_f32 v191, v60, v64
	global_store_dwordx4 v182, v[188:191], s[64:65] sc1
	v_cvt_pk_bf16_f32 v192, v37, v41
	v_cvt_pk_bf16_f32 v193, v45, v49
	v_cvt_pk_bf16_f32 v194, v53, v57
	v_cvt_pk_bf16_f32 v195, v61, v65
	global_store_dwordx4 v183, v[192:195], s[64:65] sc1
	v_cvt_pk_bf16_f32 v196, v38, v42
	v_cvt_pk_bf16_f32 v197, v46, v50
	v_cvt_pk_bf16_f32 v198, v54, v58
	v_cvt_pk_bf16_f32 v199, v62, v66
	global_store_dwordx4 v184, v[196:199], s[64:65] sc1
	v_cvt_pk_bf16_f32 v200, v39, v43
	v_cvt_pk_bf16_f32 v201, v47, v51
	v_cvt_pk_bf16_f32 v202, v55, v59
	v_cvt_pk_bf16_f32 v203, v63, v67
	global_store_dwordx4 v185, v[200:203], s[64:65] sc1
	global_load_dwordx4 v[36:39], v174, s[60:61] offset:128 nt
	global_load_dwordx4 v[40:43], v175, s[60:61] offset:128 nt
	global_load_dwordx4 v[44:47], v176, s[60:61] offset:128 nt
	global_load_dwordx4 v[48:51], v177, s[60:61] offset:128 nt
	global_load_dwordx4 v[52:55], v178, s[60:61] offset:128 nt
	global_load_dwordx4 v[56:59], v179, s[60:61] offset:128 nt
	global_load_dwordx4 v[60:63], v180, s[60:61] offset:128 nt
	global_load_dwordx4 v[64:67], v181, s[60:61] offset:128 nt
	s_add_u32 s64, s64, s72
	s_addc_u32 s65, s65, s73
	s_waitcnt vmcnt(32)
	v_mul_f32_e32 v68, v166, v68
	v_mul_f32_e32 v69, v166, v69
	v_mul_f32_e32 v70, v166, v70
	v_mul_f32_e32 v71, v166, v71
	v_mul_f32_e32 v72, v167, v72
	v_mul_f32_e32 v73, v167, v73
	v_mul_f32_e32 v74, v167, v74
	v_mul_f32_e32 v75, v167, v75
	v_mul_f32_e32 v76, v168, v76
	v_mul_f32_e32 v77, v168, v77
	v_mul_f32_e32 v78, v168, v78
	v_mul_f32_e32 v79, v168, v79
	v_mul_f32_e32 v80, v169, v80
	v_mul_f32_e32 v81, v169, v81
	v_mul_f32_e32 v82, v169, v82
	v_mul_f32_e32 v83, v169, v83
	v_mul_f32_e32 v84, v170, v84
	v_mul_f32_e32 v85, v170, v85
	v_mul_f32_e32 v86, v170, v86
	v_mul_f32_e32 v87, v170, v87
	v_mul_f32_e32 v88, v171, v88
	v_mul_f32_e32 v89, v171, v89
	v_mul_f32_e32 v90, v171, v90
	v_mul_f32_e32 v91, v171, v91
	v_mul_f32_e32 v92, v172, v92
	v_mul_f32_e32 v93, v172, v93
	v_mul_f32_e32 v94, v172, v94
	v_mul_f32_e32 v95, v172, v95
	v_mul_f32_e32 v96, v173, v96
	v_mul_f32_e32 v97, v173, v97
	v_mul_f32_e32 v98, v173, v98
	v_mul_f32_e32 v99, v173, v99
	v_cvt_pk_bf16_f32 v188, v68, v72
	v_cvt_pk_bf16_f32 v189, v76, v80
	v_cvt_pk_bf16_f32 v190, v84, v88
	v_cvt_pk_bf16_f32 v191, v92, v96
	global_store_dwordx4 v182, v[188:191], s[66:67] sc1
	v_cvt_pk_bf16_f32 v192, v69, v73
	v_cvt_pk_bf16_f32 v193, v77, v81
	v_cvt_pk_bf16_f32 v194, v85, v89
	v_cvt_pk_bf16_f32 v195, v93, v97
	global_store_dwordx4 v183, v[192:195], s[66:67] sc1
	v_cvt_pk_bf16_f32 v196, v70, v74
	v_cvt_pk_bf16_f32 v197, v78, v82
	v_cvt_pk_bf16_f32 v198, v86, v90
	v_cvt_pk_bf16_f32 v199, v94, v98
	global_store_dwordx4 v184, v[196:199], s[66:67] sc1
	v_cvt_pk_bf16_f32 v200, v71, v75
	v_cvt_pk_bf16_f32 v201, v79, v83
	v_cvt_pk_bf16_f32 v202, v87, v91
	v_cvt_pk_bf16_f32 v203, v95, v99
	global_store_dwordx4 v185, v[200:203], s[66:67] sc1
	global_load_dwordx4 v[68:71], v174, s[60:61] offset:256 nt
	global_load_dwordx4 v[72:75], v175, s[60:61] offset:256 nt
	global_load_dwordx4 v[76:79], v176, s[60:61] offset:256 nt
	global_load_dwordx4 v[80:83], v177, s[60:61] offset:256 nt
	global_load_dwordx4 v[84:87], v178, s[60:61] offset:256 nt
	global_load_dwordx4 v[88:91], v179, s[60:61] offset:256 nt
	global_load_dwordx4 v[92:95], v180, s[60:61] offset:256 nt
	global_load_dwordx4 v[96:99], v181, s[60:61] offset:256 nt
	s_add_u32 s66, s66, s72
	s_addc_u32 s67, s67, s73
	s_waitcnt vmcnt(36)
	v_mul_f32_e32 v100, v166, v100
	v_mul_f32_e32 v101, v166, v101
	v_mul_f32_e32 v102, v166, v102
	v_mul_f32_e32 v103, v166, v103
	v_mul_f32_e32 v104, v167, v104
	v_mul_f32_e32 v105, v167, v105
	v_mul_f32_e32 v106, v167, v106
	v_mul_f32_e32 v107, v167, v107
	v_mul_f32_e32 v108, v168, v108
	v_mul_f32_e32 v109, v168, v109
	v_mul_f32_e32 v110, v168, v110
	v_mul_f32_e32 v111, v168, v111
	v_mul_f32_e32 v112, v169, v112
	v_mul_f32_e32 v113, v169, v113
	v_mul_f32_e32 v114, v169, v114
	v_mul_f32_e32 v115, v169, v115
	v_mul_f32_e32 v116, v170, v116
	v_mul_f32_e32 v117, v170, v117
	v_mul_f32_e32 v118, v170, v118
	v_mul_f32_e32 v119, v170, v119
	v_mul_f32_e32 v120, v171, v120
	v_mul_f32_e32 v121, v171, v121
	v_mul_f32_e32 v122, v171, v122
	v_mul_f32_e32 v123, v171, v123
	v_mul_f32_e32 v124, v172, v124
	v_mul_f32_e32 v125, v172, v125
	v_mul_f32_e32 v126, v172, v126
	v_mul_f32_e32 v127, v172, v127
	v_mul_f32_e32 v128, v173, v128
	v_mul_f32_e32 v129, v173, v129
	v_mul_f32_e32 v130, v173, v130
	v_mul_f32_e32 v131, v173, v131
	v_cvt_pk_bf16_f32 v188, v100, v104
	v_cvt_pk_bf16_f32 v189, v108, v112
	v_cvt_pk_bf16_f32 v190, v116, v120
	v_cvt_pk_bf16_f32 v191, v124, v128
	global_store_dwordx4 v182, v[188:191], s[68:69] sc1
	v_cvt_pk_bf16_f32 v192, v101, v105
	v_cvt_pk_bf16_f32 v193, v109, v113
	v_cvt_pk_bf16_f32 v194, v117, v121
	v_cvt_pk_bf16_f32 v195, v125, v129
	global_store_dwordx4 v183, v[192:195], s[68:69] sc1
	v_cvt_pk_bf16_f32 v196, v102, v106
	v_cvt_pk_bf16_f32 v197, v110, v114
	v_cvt_pk_bf16_f32 v198, v118, v122
	v_cvt_pk_bf16_f32 v199, v126, v130
	global_store_dwordx4 v184, v[196:199], s[68:69] sc1
	v_cvt_pk_bf16_f32 v200, v103, v107
	v_cvt_pk_bf16_f32 v201, v111, v115
	v_cvt_pk_bf16_f32 v202, v119, v123
	v_cvt_pk_bf16_f32 v203, v127, v131
	global_store_dwordx4 v185, v[200:203], s[68:69] sc1
	global_load_dwordx4 v[100:103], v174, s[60:61] offset:384 nt
	global_load_dwordx4 v[104:107], v175, s[60:61] offset:384 nt
	global_load_dwordx4 v[108:111], v176, s[60:61] offset:384 nt
	global_load_dwordx4 v[112:115], v177, s[60:61] offset:384 nt
	global_load_dwordx4 v[116:119], v178, s[60:61] offset:384 nt
	global_load_dwordx4 v[120:123], v179, s[60:61] offset:384 nt
	global_load_dwordx4 v[124:127], v180, s[60:61] offset:384 nt
	global_load_dwordx4 v[128:131], v181, s[60:61] offset:384 nt
	s_add_u32 s68, s68, s72
	s_addc_u32 s69, s69, s73
	s_add_u32 s60, s60, s70
	s_addc_u32 s61, s61, s71
	s_sub_i32 s74, s74, 1
	s_cmp_eq_u32 s74, 1
	s_cbranch_scc1 .Lcv_g_last
; #define LAS __attribute__((address_space(3)))
; __device__ __forceinline__ unsigned cvt_pk_bf16(float lo, float hi) { unsigned r; asm volatile("v_cvt_pk_bf16_f32 %0, %1, %2" : "=v"(r) : "v"(lo), "v"(hi)); return r; }
; template <bool NT = true> __device__ __forceinline__ void tr_load(const TrDesc& d, f32x4 (&v)[8], int lane) {
;     const float* sp = d.src + (size_t)(lane >> 3) * d.ldn + 4 * (lane & 7);
; #pragma unroll
;     for (int i = 0; i < 8; ++i) v[i] = NT ? __builtin_nontemporal_load((const f32x4*)(sp + (size_t)(8 * i) * d.ldn)) : *(const f32x4*)(sp + (size_t)(8 * i) * d.ldn);
; }
; template <bool NT = true> __device__ __forceinline__ void tr_finish(const TrDesc& d, const f32x4 (&v)[8], LAS float* scr, int lane) {
;     const int c = lane & 7;
;     f32x4 g0 = {1.f, 1.f, 1.f, 1.f}, g1 = {1.f, 1.f, 1.f, 1.f};
;     if (d.gain) { g0 = *(const f32x4*)(d.gain + 8 * c); g1 = *(const f32x4*)(d.gain + 8 * c + 4); }
; #pragma unroll
;     for (int i = 0; i < 8; ++i) { LAS float* w = scr + (8 * i + (lane >> 3)) * 33 + 4 * c; w[0] = v[i].x; w[1] = v[i].y; w[2] = v[i].z; w[3] = v[i].w; }
;     LDS_WAIT(); asm volatile("" ::: "memory");
; #pragma unroll
;     for (int j = 0; j < 4; ++j) { const int n = (lane >> 3) + 8 * j; const LAS float* s = scr + (8 * c) * 33 + n;
;         u32x4 o; o.x = cvt_pk_bf16(s[0 * 33] * g0.x, s[1 * 33] * g0.y); o.y = cvt_pk_bf16(s[2 * 33] * g0.z, s[3 * 33] * g0.w); o.z = cvt_pk_bf16(s[4 * 33] * g1.x, s[5 * 33] * g1.y); o.w = cvt_pk_bf16(s[6 * 33] * g1.z, s[7 * 33] * g1.w);
;         if (NT) __builtin_nontemporal_store(o, (u32x4*)(d.dst + (size_t)n * d.K + 8 * c)); else *(u32x4*)(d.dst + (size_t)n * d.K + 8 * c) = o; }
; template <class F, bool NT = true> __device__ __forceinline__ void tr_run(F item, int first, int step, int n, LAS float* scr, int lane) {
;     ...
;     for (int it = first; it < n; it += 3 * step) {
;         const bool h1 = it + step < n, h2 = it + 2 * step < n, h3 = it + 3 * step < n, h4 = it + 4 * step < n;
;         if (h2) { dc = item(it + 2 * step); tr_load<NT>(dc, vc, lane); }
;         tr_finish<NT>(da, va, scr, lane);
;         if (h3) { da = item(it + 3 * step); tr_load<NT>(da, va, lane); }
;         if (h1) tr_finish<NT>(db, vb, scr, lane);
;         if (h4) { db = item(it + 4 * step); tr_load<NT>(db, vb, lane); }
;         if (h2) tr_finish<NT>(dc, vc, scr, lane);
;     }
.Lcv_g_steady:
	s_waitcnt vmcnt(36)
	v_mul_f32_e32 v4, v166, v4
	v_mul_f32_e32 v5, v166, v5
	v_mul_f32_e32 v6, v166, v6
	v_mul_f32_e32 v7, v166, v7
	v_mul_f32_e32 v8, v167, v8
	v_mul_f32_e32 v9, v167, v9
	v_mul_f32_e32 v10, v167, v10
	v_mul_f32_e32 v11, v167, v11
	v_mul_f32_e32 v12, v168, v12
	v_mul_f32_e32 v13, v168, v13
	v_mul_f32_e32 v14, v168, v14
	v_mul_f32_e32 v15, v168, v15
	v_mul_f32_e32 v16, v169, v16
	v_mul_f32_e32 v17, v169, v17
	v_mul_f32_e32 v18, v169, v18
	v_mul_f32_e32 v19, v169, v19
	v_mul_f32_e32 v20, v170, v20
	v_mul_f32_e32 v21, v170, v21
	v_mul_f32_e32 v22, v170, v22
	v_mul_f32_e32 v23, v170, v23
	v_mul_f32_e32 v24, v171, v24
	v_mul_f32_e32 v25, v171, v25
	v_mul_f32_e32 v26, v171, v26
	v_mul_f32_e32 v27, v171, v27
	v_mul_f32_e32 v28, v172, v28
	v_mul_f32_e32 v29, v172, v29
	v_mul_f32_e32 v30, v172, v30
	v_mul_f32_e32 v31, v172, v31
	v_mul_f32_e32 v32, v173, v32
	v_mul_f32_e32 v33, v173, v33
	v_mul_f32_e32 v34, v173, v34
	v_mul_f32_e32 v35, v173, v35
	v_cvt_pk_bf16_f32 v188, v4, v8
	v_cvt_pk_bf16_f32 v189, v12, v16
	v_cvt_pk_bf16_f32 v190, v20, v24
	v_cvt_pk_bf16_f32 v191, v28, v32
	global_store_dwordx4 v182, v[188:191], s[62:63] sc1
	v_cvt_pk_bf16_f32 v192, v5, v9
	v_cvt_pk_bf16_f32 v193, v13, v17
	v_cvt_pk_bf16_f32 v194, v21, v25
	v_cvt_pk_bf16_f32 v195, v29, v33
	global_store_dwordx4 v183, v[192:195], s[62:63] sc1
	v_cvt_pk_bf16_f32 v196, v6, v10
	v_cvt_pk_bf16_f32 v197, v14, v18
	v_cvt_pk_bf16_f32 v198, v22, v26
	v_cvt_pk_bf16_f32 v199, v30, v34
	global_store_dwordx4 v184, v[196:199], s[62:63] sc1
	v_cvt_pk_bf16_f32 v200, v7, v11
	v_cvt_pk_bf16_f32 v201, v15, v19
	v_cvt_pk_bf16_f32 v202, v23, v27
	v_cvt_pk_bf16_f32 v203, v31, v35
	global_store_dwordx4 v185, v[200:203], s[62:63] sc1
	global_load_dwordx4 v[4:7], v174, s[60:61] offset:0 nt
	global_load_dwordx4 v[8:11], v175, s[60:61] offset:0 nt
	global_load_dwordx4 v[12:15], v176, s[60:61] offset:0 nt
	global_load_dwordx4 v[16:19], v177, s[60:61] offset:0 nt
	global_load_dwordx4 v[20:23], v178, s[60:61] offset:0 nt
	global_load_dwordx4 v[24:27], v179, s[60:61] offset:0 nt
	global_load_dwordx4 v[28:31], v180, s[60:61] offset:0 nt
	global_load_dwordx4 v[32:35], v181, s[60:61] offset:0 nt
	s_add_u32 s62, s62, s72
	s_addc_u32 s63, s63, s73
	s_waitcnt vmcnt(36)
	v_mul_f32_e32 v36, v166, v36
	v_mul_f32_e32 v37, v166, v37
	v_mul_f32_e32 v38, v166, v38
	v_mul_f32_e32 v39, v166, v39
	v_mul_f32_e32 v40, v167, v40
	v_mul_f32_e32 v41, v167, v41
	v_mul_f32_e32 v42, v167, v42
	v_mul_f32_e32 v43, v167, v43
	v_mul_f32_e32 v44, v168, v44
	v_mul_f32_e32 v45, v168, v45
	v_mul_f32_e32 v46, v168, v46
	v_mul_f32_e32 v47, v168, v47
	v_mul_f32_e32 v48, v169, v48
	v_mul_f32_e32 v49, v169, v49
	v_mul_f32_e32 v50, v169, v50
	v_mul_f32_e32 v51, v169, v51
	v_mul_f32_e32 v52, v170, v52
	v_mul_f32_e32 v53, v170, v53
	v_mul_f32_e32 v54, v170, v54
	v_mul_f32_e32 v55, v170, v55
	v_mul_f32_e32 v56, v171, v56
	v_mul_f32_e32 v57, v171, v57
	v_mul_f32_e32 v58, v171, v58
	v_mul_f32_e32 v59, v171, v59
	v_mul_f32_e32 v60, v172, v60
	v_mul_f32_e32 v61, v172, v61
	v_mul_f32_e32 v62, v172, v62
	v_mul_f32_e32 v63, v172, v63
	v_mul_f32_e32 v64, v173, v64
	v_mul_f32_e32 v65, v173, v65
	v_mul_f32_e32 v66, v173, v66
	v_mul_f32_e32 v67, v173, v67
	v_cvt_pk_bf16_f32 v188, v36, v40
	v_cvt_pk_bf16_f32 v189, v44, v48
	v_cvt_pk_bf16_f32 v190, v52, v56
	v_cvt_pk_bf16_f32 v191, v60, v64
	global_store_dwordx4 v182, v[188:191], s[64:65] sc1
	v_cvt_pk_bf16_f32 v192, v37, v41
	v_cvt_pk_bf16_f32 v193, v45, v49
	v_cvt_pk_bf16_f32 v194, v53, v57
	v_cvt_pk_bf16_f32 v195, v61, v65
	global_store_dwordx4 v183, v[192:195], s[64:65] sc1
	v_cvt_pk_bf16_f32 v196, v38, v42
	v_cvt_pk_bf16_f32 v197, v46, v50
	v_cvt_pk_bf16_f32 v198, v54, v58
	v_cvt_pk_bf16_f32 v199, v62, v66
	global_store_dwordx4 v184, v[196:199], s[64:65] sc1
	v_cvt_pk_bf16_f32 v200, v39, v43
	v_cvt_pk_bf16_f32 v201, v47, v51
	v_cvt_pk_bf16_f32 v202, v55, v59
	v_cvt_pk_bf16_f32 v203, v63, v67
	global_store_dwordx4 v185, v[200:203], s[64:65] sc1
	global_load_dwordx4 v[36:39], v174, s[60:61] offset:128 nt
	global_load_dwordx4 v[40:43], v175, s[60:61] offset:128 nt
	global_load_dwordx4 v[44:47], v176, s[60:61] offset:128 nt
	global_load_dwordx4 v[48:51], v177, s[60:61] offset:128 nt
	global_load_dwordx4 v[52:55], v178, s[60:61] offset:128 nt
	global_load_dwordx4 v[56:59], v179, s[60:61] offset:128 nt
	global_load_dwordx4 v[60:63], v180, s[60:61] offset:128 nt
	global_load_dwordx4 v[64:67], v181, s[60:61] offset:128 nt
	s_add_u32 s64, s64, s72
	s_addc_u32 s65, s65, s73
	s_waitcnt vmcnt(36)
; #define LAS __attribute__((address_space(3)))
; __device__ __forceinline__ unsigned cvt_pk_bf16(float lo, float hi) { unsigned r; asm volatile("v_cvt_pk_bf16_f32 %0, %1, %2" : "=v"(r) : "v"(lo), "v"(hi)); return r; }
; template <bool NT = true> __device__ __forceinline__ void tr_load(const TrDesc& d, f32x4 (&v)[8], int lane) {
;     const float* sp = d.src + (size_t)(lane >> 3) * d.ldn + 4 * (lane & 7);
; #pragma unroll
;     for (int i = 0; i < 8; ++i) v[i] = NT ? __builtin_nontemporal_load((const f32x4*)(sp + (size_t)(8 * i) * d.ldn)) : *(const f32x4*)(sp + (size_t)(8 * i) * d.ldn);
; }
; template <bool NT = true> __device__ __forceinline__ void tr_finish(const TrDesc& d, const f32x4 (&v)[8], LAS float* scr, int lane) {
;     const int c = lane & 7;
;     f32x4 g0 = {1.f, 1.f, 1.f, 1.f}, g1 = {1.f, 1.f, 1.f, 1.f};
;     if (d.gain) { g0 = *(const f32x4*)(d.gain + 8 * c); g1 = *(const f32x4*)(d.gain + 8 * c + 4); }
; #pragma unroll
;     for (int i = 0; i < 8; ++i) { LAS float* w = scr + (8 * i + (lane >> 3)) * 33 + 4 * c; w[0] = v[i].x; w[1] = v[i].y; w[2] = v[i].z; w[3] = v[i].w; }
;     LDS_WAIT(); asm volatile("" ::: "memory");
; #pragma unroll
;     for (int j = 0; j < 4; ++j) { const int n = (lane >> 3) + 8 * j; const LAS float* s = scr + (8 * c) * 33 + n;
;         u32x4 o; o.x = cvt_pk_bf16(s[0 * 33] * g0.x, s[1 * 33] * g0.y); o.y = cvt_pk_bf16(s[2 * 33] * g0.z, s[3 * 33] * g0.w); o.z = cvt_pk_bf16(s[4 * 33] * g1.x, s[5 * 33] * g1.y); o.w = cvt_pk_bf16(s[6 * 33] * g1.z, s[7 * 33] * g1.w);
;         if (NT) __builtin_nontemporal_store(o, (u32x4*)(d.dst + (size_t)n * d.K + 8 * c)); else *(u32x4*)(d.dst + (size_t)n * d.K + 8 * c) = o; }
; template <class F, bool NT = true> __device__ __forceinline__ void tr_run(F item, int first, int step, int n, LAS float* scr, int lane) {
;     ...
;     for (int it = first; it < n; it += 3 * step) {
;         const bool h1 = it + step < n, h2 = it + 2 * step < n, h3 = it + 3 * step < n, h4 = it + 4 * step < n;
;         if (h2) { dc = item(it + 2 * step); tr_load<NT>(dc, vc, lane); }
;         tr_finish<NT>(da, va, scr, lane);
;         if (h3) { da = item(it + 3 * step); tr_load<NT>(da, va, lane); }
;         if (h1) tr_finish<NT>(db, vb, scr, lane);
;         if (h4) { db = item(it + 4 * step); tr_load<NT>(db, vb, lane); }
;         if (h2) tr_finish<NT>(dc, vc, scr, lane);
;     }
	v_mul_f32_e32 v68, v166, v68
	v_mul_f32_e32 v69, v166, v69
	v_mul_f32_e32 v70, v166, v70
	v_mul_f32_e32 v71, v166, v71
	v_mul_f32_e32 v72, v167, v72
	v_mul_f32_e32 v73, v167, v73
	v_mul_f32_e32 v74, v167, v74
	v_mul_f32_e32 v75, v167, v75
	v_mul_f32_e32 v76, v168, v76
	v_mul_f32_e32 v77, v168, v77
	v_mul_f32_e32 v78, v168, v78
	v_mul_f32_e32 v79, v168, v79
	v_mul_f32_e32 v80, v169, v80
	v_mul_f32_e32 v81, v169, v81
	v_mul_f32_e32 v82, v169, v82
	v_mul_f32_e32 v83, v169, v83
	v_mul_f32_e32 v84, v170, v84
	v_mul_f32_e32 v85, v170, v85
	v_mul_f32_e32 v86, v170, v86
	v_mul_f32_e32 v87, v170, v87
	v_mul_f32_e32 v88, v171, v88
	v_mul_f32_e32 v89, v171, v89
	v_mul_f32_e32 v90, v171, v90
	v_mul_f32_e32 v91, v171, v91
	v_mul_f32_e32 v92, v172, v92
	v_mul_f32_e32 v93, v172, v93
	v_mul_f32_e32 v94, v172, v94
	v_mul_f32_e32 v95, v172, v95
	v_mul_f32_e32 v96, v173, v96
	v_mul_f32_e32 v97, v173, v97
	v_mul_f32_e32 v98, v173, v98
	v_mul_f32_e32 v99, v173, v99
	v_cvt_pk_bf16_f32 v188, v68, v72
	v_cvt_pk_bf16_f32 v189, v76, v80
	v_cvt_pk_bf16_f32 v190, v84, v88
	v_cvt_pk_bf16_f32 v191, v92, v96
	global_store_dwordx4 v182, v[188:191], s[66:67] sc1
	v_cvt_pk_bf16_f32 v192, v69, v73
	v_cvt_pk_bf16_f32 v193, v77, v81
	v_cvt_pk_bf16_f32 v194, v85, v89
	v_cvt_pk_bf16_f32 v195, v93, v97
	global_store_dwordx4 v183, v[192:195], s[66:67] sc1
	v_cvt_pk_bf16_f32 v196, v70, v74
	v_cvt_pk_bf16_f32 v197, v78, v82
	v_cvt_pk_bf16_f32 v198, v86, v90
	v_cvt_pk_bf16_f32 v199, v94, v98
	global_store_dwordx4 v184, v[196:199], s[66:67] sc1
	v_cvt_pk_bf16_f32 v200, v71, v75
	v_cvt_pk_bf16_f32 v201, v79, v83
	v_cvt_pk_bf16_f32 v202, v87, v91
	v_cvt_pk_bf16_f32 v203, v95, v99
	global_store_dwordx4 v185, v[200:203], s[66:67] sc1
	global_load_dwordx4 v[68:71], v174, s[60:61] offset:256 nt
	global_load_dwordx4 v[72:75], v175, s[60:61] offset:256 nt
	global_load_dwordx4 v[76:79], v176, s[60:61] offset:256 nt
	global_load_dwordx4 v[80:83], v177, s[60:61] offset:256 nt
	global_load_dwordx4 v[84:87], v178, s[60:61] offset:256 nt
	global_load_dwordx4 v[88:91], v179, s[60:61] offset:256 nt
	global_load_dwordx4 v[92:95], v180, s[60:61] offset:256 nt
	global_load_dwordx4 v[96:99], v181, s[60:61] offset:256 nt
	s_add_u32 s66, s66, s72
	s_addc_u32 s67, s67, s73
	s_waitcnt vmcnt(36)
	v_mul_f32_e32 v100, v166, v100
	v_mul_f32_e32 v101, v166, v101
	v_mul_f32_e32 v102, v166, v102
	v_mul_f32_e32 v103, v166, v103
	v_mul_f32_e32 v104, v167, v104
	v_mul_f32_e32 v105, v167, v105
	v_mul_f32_e32 v106, v167, v106
	v_mul_f32_e32 v107, v167, v107
	v_mul_f32_e32 v108, v168, v108
	v_mul_f32_e32 v109, v168, v109
	v_mul_f32_e32 v110, v168, v110
	v_mul_f32_e32 v111, v168, v111
	v_mul_f32_e32 v112, v169, v112
	v_mul_f32_e32 v113, v169, v113
	v_mul_f32_e32 v114, v169, v114
	v_mul_f32_e32 v115, v169, v115
	v_mul_f32_e32 v116, v170, v116
	v_mul_f32_e32 v117, v170, v117
	v_mul_f32_e32 v118, v170, v118
	v_mul_f32_e32 v119, v170, v119
	v_mul_f32_e32 v120, v171, v120
	v_mul_f32_e32 v121, v171, v121
	v_mul_f32_e32 v122, v171, v122
	v_mul_f32_e32 v123, v171, v123
	v_mul_f32_e32 v124, v172, v124
	v_mul_f32_e32 v125, v172, v125
	v_mul_f32_e32 v126, v172, v126
	v_mul_f32_e32 v127, v172, v127
	v_mul_f32_e32 v128, v173, v128
	v_mul_f32_e32 v129, v173, v129
	v_mul_f32_e32 v130, v173, v130
	v_mul_f32_e32 v131, v173, v131
	v_cvt_pk_bf16_f32 v188, v100, v104
	v_cvt_pk_bf16_f32 v189, v108, v112
	v_cvt_pk_bf16_f32 v190, v116, v120
	v_cvt_pk_bf16_f32 v191, v124, v128
	global_store_dwordx4 v182, v[188:191], s[68:69] sc1
	v_cvt_pk_bf16_f32 v192, v101, v105
	v_cvt_pk_bf16_f32 v193, v109, v113
	v_cvt_pk_bf16_f32 v194, v117, v121
	v_cvt_pk_bf16_f32 v195, v125, v129
	global_store_dwordx4 v183, v[192:195], s[68:69] sc1
	v_cvt_pk_bf16_f32 v196, v102, v106
	v_cvt_pk_bf16_f32 v197, v110, v114
	v_cvt_pk_bf16_f32 v198, v118, v122
	v_cvt_pk_bf16_f32 v199, v126, v130
	global_store_dwordx4 v184, v[196:199], s[68:69] sc1
	v_cvt_pk_bf16_f32 v200, v103, v107
	v_cvt_pk_bf16_f32 v201, v111, v115
	v_cvt_pk_bf16_f32 v202, v119, v123
	v_cvt_pk_bf16_f32 v203, v127, v131
	global_store_dwordx4 v185, v[200:203], s[68:69] sc1
	global_load_dwordx4 v[100:103], v174, s[60:61] offset:384 nt
	global_load_dwordx4 v[104:107], v175, s[60:61] offset:384 nt
	global_load_dwordx4 v[108:111], v176, s[60:61] offset:384 nt
	global_load_dwordx4 v[112:115], v177, s[60:61] offset:384 nt
	global_load_dwordx4 v[116:119], v178, s[60:61] offset:384 nt
	global_load_dwordx4 v[120:123], v179, s[60:61] offset:384 nt
	global_load_dwordx4 v[124:127], v180, s[60:61] offset:384 nt
	global_load_dwordx4 v[128:131], v181, s[60:61] offset:384 nt
	s_add_u32 s68, s68, s72
	s_addc_u32 s69, s69, s73
	s_add_u32 s60, s60, s70
	s_addc_u32 s61, s61, s71
	s_sub_i32 s74, s74, 1
	s_cmp_eq_u32 s74, 1
	s_cbranch_scc0 .Lcv_g_steady
; #define LAS __attribute__((address_space(3)))
; __device__ __forceinline__ unsigned cvt_pk_bf16(float lo, float hi) { unsigned r; asm volatile("v_cvt_pk_bf16_f32 %0, %1, %2" : "=v"(r) : "v"(lo), "v"(hi)); return r; }
; #define LDS_WAIT() asm volatile("s_waitcnt lgkmcnt(0)" ::: "memory")
; __device__ __forceinline__ unsigned cvt_pk_bf16(float lo, float hi) { unsigned r; asm volatile("v_cvt_pk_bf16_f32 %0, %1, %2" : "=v"(r) : "v"(lo), "v"(hi)); return r; }
; template <bool NT = true> __device__ __forceinline__ void tr_load(const TrDesc& d, f32x4 (&v)[8], int lane) {
;     const float* sp = d.src + (size_t)(lane >> 3) * d.ldn + 4 * (lane & 7);
; #pragma unroll
;     for (int i = 0; i < 8; ++i) v[i] = NT ? __builtin_nontemporal_load((const f32x4*)(sp + (size_t)(8 * i) * d.ldn)) : *(const f32x4*)(sp + (size_t)(8 * i) * d.ldn);
; }
; template <bool NT = true> __device__ __forceinline__ void tr_finish(const TrDesc& d, const f32x4 (&v)[8], LAS float* scr, int lane) {
;     const int c = lane & 7;
;     f32x4 g0 = {1.f, 1.f, 1.f, 1.f}, g1 = {1.f, 1.f, 1.f, 1.f};
;     if (d.gain) { g0 = *(const f32x4*)(d.gain + 8 * c); g1 = *(const f32x4*)(d.gain + 8 * c + 4); }
; #pragma unroll
;     for (int i = 0; i < 8; ++i) { LAS float* w = scr + (8 * i + (lane >> 3)) * 33 + 4 * c; w[0] = v[i].x; w[1] = v[i].y; w[2] = v[i].z; w[3] = v[i].w; }
;     LDS_WAIT(); asm volatile("" ::: "memory");
; #pragma unroll
;     for (int j = 0; j < 4; ++j) { const int n = (lane >> 3) + 8 * j; const LAS float* s = scr + (8 * c) * 33 + n;
;         u32x4 o; o.x = cvt_pk_bf16(s[0 * 33] * g0.x, s[1 * 33] * g0.y); o.y = cvt_pk_bf16(s[2 * 33] * g0.z, s[3 * 33] * g0.w); o.z = cvt_pk_bf16(s[4 * 33] * g1.x, s[5 * 33] * g1.y); o.w = cvt_pk_bf16(s[6 * 33] * g1.z, s[7 * 33] * g1.w);
;         if (NT) __builtin_nontemporal_store(o, (u32x4*)(d.dst + (size_t)n * d.K + 8 * c)); else *(u32x4*)(d.dst + (size_t)n * d.K + 8 * c) = o; }
.Lcv_g_last:
	s_waitcnt vmcnt(24)
	v_mul_f32_e32 v4, v166, v4
	v_mul_f32_e32 v5, v166, v5
	v_mul_f32_e32 v6, v166, v6
	v_mul_f32_e32 v7, v166, v7
	v_mul_f32_e32 v8, v167, v8
	v_mul_f32_e32 v9, v167, v9
	v_mul_f32_e32 v10, v167, v10
	v_mul_f32_e32 v11, v167, v11
	v_mul_f32_e32 v12, v168, v12
	v_mul_f32_e32 v13, v168, v13
	v_mul_f32_e32 v14, v168, v14
	v_mul_f32_e32 v15, v168, v15
	v_mul_f32_e32 v16, v169, v16
	v_mul_f32_e32 v17, v169, v17
	v_mul_f32_e32 v18, v169, v18
	v_mul_f32_e32 v19, v169, v19
	v_mul_f32_e32 v20, v170, v20
	v_mul_f32_e32 v21, v170, v21
	v_mul_f32_e32 v22, v170, v22
	v_mul_f32_e32 v23, v170, v23
	v_mul_f32_e32 v24, v171, v24
	v_mul_f32_e32 v25, v171, v25
	v_mul_f32_e32 v26, v171, v26
	v_mul_f32_e32 v27, v171, v27
	v_mul_f32_e32 v28, v172, v28
	v_mul_f32_e32 v29, v172, v29
	v_mul_f32_e32 v30, v172, v30
	v_mul_f32_e32 v31, v172, v31
	v_mul_f32_e32 v32, v173, v32
	v_mul_f32_e32 v33, v173, v33
	v_mul_f32_e32 v34, v173, v34
	v_mul_f32_e32 v35, v173, v35
	v_cvt_pk_bf16_f32 v188, v4, v8
	v_cvt_pk_bf16_f32 v189, v12, v16
	v_cvt_pk_bf16_f32 v190, v20, v24
	v_cvt_pk_bf16_f32 v191, v28, v32
	global_store_dwordx4 v182, v[188:191], s[62:63] sc1
	v_cvt_pk_bf16_f32 v192, v5, v9
	v_cvt_pk_bf16_f32 v193, v13, v17
	v_cvt_pk_bf16_f32 v194, v21, v25
	v_cvt_pk_bf16_f32 v195, v29, v33
	global_store_dwordx4 v183, v[192:195], s[62:63] sc1
	v_cvt_pk_bf16_f32 v196, v6, v10
	v_cvt_pk_bf16_f32 v197, v14, v18
	v_cvt_pk_bf16_f32 v198, v22, v26
	v_cvt_pk_bf16_f32 v199, v30, v34
	global_store_dwordx4 v184, v[196:199], s[62:63] sc1
	v_cvt_pk_bf16_f32 v200, v7, v11
	v_cvt_pk_bf16_f32 v201, v15, v19
	v_cvt_pk_bf16_f32 v202, v23, v27
	v_cvt_pk_bf16_f32 v203, v31, v35
	global_store_dwordx4 v185, v[200:203], s[62:63] sc1
	s_waitcnt vmcnt(20)
	v_mul_f32_e32 v36, v166, v36
	v_mul_f32_e32 v37, v166, v37
	v_mul_f32_e32 v38, v166, v38
	v_mul_f32_e32 v39, v166, v39
	v_mul_f32_e32 v40, v167, v40
	v_mul_f32_e32 v41, v167, v41
	v_mul_f32_e32 v42, v167, v42
	v_mul_f32_e32 v43, v167, v43
	v_mul_f32_e32 v44, v168, v44
	v_mul_f32_e32 v45, v168, v45
	v_mul_f32_e32 v46, v168, v46
	v_mul_f32_e32 v47, v168, v47
	v_mul_f32_e32 v48, v169, v48
	v_mul_f32_e32 v49, v169, v49
	v_mul_f32_e32 v50, v169, v50
	v_mul_f32_e32 v51, v169, v51
	v_mul_f32_e32 v52, v170, v52
	v_mul_f32_e32 v53, v170, v53
	v_mul_f32_e32 v54, v170, v54
	v_mul_f32_e32 v55, v170, v55
	v_mul_f32_e32 v56, v171, v56
	v_mul_f32_e32 v57, v171, v57
	v_mul_f32_e32 v58, v171, v58
	v_mul_f32_e32 v59, v171, v59
	v_mul_f32_e32 v60, v172, v60
	v_mul_f32_e32 v61, v172, v61
	v_mul_f32_e32 v62, v172, v62
	v_mul_f32_e32 v63, v172, v63
	v_mul_f32_e32 v64, v173, v64
	v_mul_f32_e32 v65, v173, v65
	v_mul_f32_e32 v66, v173, v66
	v_mul_f32_e32 v67, v173, v67
	v_cvt_pk_bf16_f32 v188, v36, v40
	v_cvt_pk_bf16_f32 v189, v44, v48
	v_cvt_pk_bf16_f32 v190, v52, v56
	v_cvt_pk_bf16_f32 v191, v60, v64
	global_store_dwordx4 v182, v[188:191], s[64:65] sc1
	v_cvt_pk_bf16_f32 v192, v37, v41
	v_cvt_pk_bf16_f32 v193, v45, v49
	v_cvt_pk_bf16_f32 v194, v53, v57
	v_cvt_pk_bf16_f32 v195, v61, v65
	global_store_dwordx4 v183, v[192:195], s[64:65] sc1
	v_cvt_pk_bf16_f32 v196, v38, v42
	v_cvt_pk_bf16_f32 v197, v46, v50
	v_cvt_pk_bf16_f32 v198, v54, v58
	v_cvt_pk_bf16_f32 v199, v62, v66
	global_store_dwordx4 v184, v[196:199], s[64:65] sc1
	v_cvt_pk_bf16_f32 v200, v39, v43
	v_cvt_pk_bf16_f32 v201, v47, v51
	v_cvt_pk_bf16_f32 v202, v55, v59
	v_cvt_pk_bf16_f32 v203, v63, v67
	global_store_dwordx4 v185, v[200:203], s[64:65] sc1
	s_waitcnt vmcnt(16)
	v_mul_f32_e32 v68, v166, v68
	v_mul_f32_e32 v69, v166, v69
	v_mul_f32_e32 v70, v166, v70
	v_mul_f32_e32 v71, v166, v71
	v_mul_f32_e32 v72, v167, v72
	v_mul_f32_e32 v73, v167, v73
	v_mul_f32_e32 v74, v167, v74
	v_mul_f32_e32 v75, v167, v75
	v_mul_f32_e32 v76, v168, v76
	v_mul_f32_e32 v77, v168, v77
	v_mul_f32_e32 v78, v168, v78
	v_mul_f32_e32 v79, v168, v79
	v_mul_f32_e32 v80, v169, v80
	v_mul_f32_e32 v81, v169, v81
	v_mul_f32_e32 v82, v169, v82
	v_mul_f32_e32 v83, v169, v83
	v_mul_f32_e32 v84, v170, v84
	v_mul_f32_e32 v85, v170, v85
	v_mul_f32_e32 v86, v170, v86
	v_mul_f32_e32 v87, v170, v87
	v_mul_f32_e32 v88, v171, v88
	v_mul_f32_e32 v89, v171, v89
	v_mul_f32_e32 v90, v171, v90
	v_mul_f32_e32 v91, v171, v91
	v_mul_f32_e32 v92, v172, v92
	v_mul_f32_e32 v93, v172, v93
	v_mul_f32_e32 v94, v172, v94
	v_mul_f32_e32 v95, v172, v95
	v_mul_f32_e32 v96, v173, v96
	v_mul_f32_e32 v97, v173, v97
	v_mul_f32_e32 v98, v173, v98
	v_mul_f32_e32 v99, v173, v99
	v_cvt_pk_bf16_f32 v188, v68, v72
	v_cvt_pk_bf16_f32 v189, v76, v80
	v_cvt_pk_bf16_f32 v190, v84, v88
	v_cvt_pk_bf16_f32 v191, v92, v96
	global_store_dwordx4 v182, v[188:191], s[66:67] sc1
	v_cvt_pk_bf16_f32 v192, v69, v73
	v_cvt_pk_bf16_f32 v193, v77, v81
	v_cvt_pk_bf16_f32 v194, v85, v89
	v_cvt_pk_bf16_f32 v195, v93, v97
	global_store_dwordx4 v183, v[192:195], s[66:67] sc1
	v_cvt_pk_bf16_f32 v196, v70, v74
	v_cvt_pk_bf16_f32 v197, v78, v82
	v_cvt_pk_bf16_f32 v198, v86, v90
	v_cvt_pk_bf16_f32 v199, v94, v98
	global_store_dwordx4 v184, v[196:199], s[66:67] sc1
	v_cvt_pk_bf16_f32 v200, v71, v75
	v_cvt_pk_bf16_f32 v201, v79, v83
	v_cvt_pk_bf16_f32 v202, v87, v91
	v_cvt_pk_bf16_f32 v203, v95, v99
	global_store_dwordx4 v185, v[200:203], s[66:67] sc1
	s_waitcnt vmcnt(12)
; #define LAS __attribute__((address_space(3)))
; __device__ __forceinline__ unsigned cvt_pk_bf16(float lo, float hi) { unsigned r; asm volatile("v_cvt_pk_bf16_f32 %0, %1, %2" : "=v"(r) : "v"(lo), "v"(hi)); return r; }
; #define LDS_WAIT() asm volatile("s_waitcnt lgkmcnt(0)" ::: "memory")
; __device__ __forceinline__ unsigned cvt_pk_bf16(float lo, float hi) { unsigned r; asm volatile("v_cvt_pk_bf16_f32 %0, %1, %2" : "=v"(r) : "v"(lo), "v"(hi)); return r; }
; template <bool NT = true> __device__ __forceinline__ void tr_load(const TrDesc& d, f32x4 (&v)[8], int lane) {
;     const float* sp = d.src + (size_t)(lane >> 3) * d.ldn + 4 * (lane & 7);
; #pragma unroll
;     for (int i = 0; i < 8; ++i) v[i] = NT ? __builtin_nontemporal_load((const f32x4*)(sp + (size_t)(8 * i) * d.ldn)) : *(const f32x4*)(sp + (size_t)(8 * i) * d.ldn);
; }
; template <bool NT = true> __device__ __forceinline__ void tr_finish(const TrDesc& d, const f32x4 (&v)[8], LAS float* scr, int lane) {
;     const int c = lane & 7;
;     f32x4 g0 = {1.f, 1.f, 1.f, 1.f}, g1 = {1.f, 1.f, 1.f, 1.f};
;     if (d.gain) { g0 = *(const f32x4*)(d.gain + 8 * c); g1 = *(const f32x4*)(d.gain + 8 * c + 4); }
; #pragma unroll
;     for (int i = 0; i < 8; ++i) { LAS float* w = scr + (8 * i + (lane >> 3)) * 33 + 4 * c; w[0] = v[i].x; w[1] = v[i].y; w[2] = v[i].z; w[3] = v[i].w; }
;     LDS_WAIT(); asm volatile("" ::: "memory");
; #pragma unroll
;     for (int j = 0; j < 4; ++j) { const int n = (lane >> 3) + 8 * j; const LAS float* s = scr + (8 * c) * 33 + n;
;         u32x4 o; o.x = cvt_pk_bf16(s[0 * 33] * g0.x, s[1 * 33] * g0.y); o.y = cvt_pk_bf16(s[2 * 33] * g0.z, s[3 * 33] * g0.w); o.z = cvt_pk_bf16(s[4 * 33] * g1.x, s[5 * 33] * g1.y); o.w = cvt_pk_bf16(s[6 * 33] * g1.z, s[7 * 33] * g1.w);
;         if (NT) __builtin_nontemporal_store(o, (u32x4*)(d.dst + (size_t)n * d.K + 8 * c)); else *(u32x4*)(d.dst + (size_t)n * d.K + 8 * c) = o; }
	v_mul_f32_e32 v100, v166, v100
	v_mul_f32_e32 v101, v166, v101
	v_mul_f32_e32 v102, v166, v102
	v_mul_f32_e32 v103, v166, v103
	v_mul_f32_e32 v104, v167, v104
	v_mul_f32_e32 v105, v167, v105
	v_mul_f32_e32 v106, v167, v106
	v_mul_f32_e32 v107, v167, v107
	v_mul_f32_e32 v108, v168, v108
	v_mul_f32_e32 v109, v168, v109
	v_mul_f32_e32 v110, v168, v110
	v_mul_f32_e32 v111, v168, v111
	v_mul_f32_e32 v112, v169, v112
	v_mul_f32_e32 v113, v169, v113
	v_mul_f32_e32 v114, v169, v114
	v_mul_f32_e32 v115, v169, v115
	v_mul_f32_e32 v116, v170, v116
	v_mul_f32_e32 v117, v170, v117
	v_mul_f32_e32 v118, v170, v118
	v_mul_f32_e32 v119, v170, v119
	v_mul_f32_e32 v120, v171, v120
	v_mul_f32_e32 v121, v171, v121
	v_mul_f32_e32 v122, v171, v122
	v_mul_f32_e32 v123, v171, v123
	v_mul_f32_e32 v124, v172, v124
	v_mul_f32_e32 v125, v172, v125
	v_mul_f32_e32 v126, v172, v126
	v_mul_f32_e32 v127, v172, v127
	v_mul_f32_e32 v128, v173, v128
	v_mul_f32_e32 v129, v173, v129
	v_mul_f32_e32 v130, v173, v130
	v_mul_f32_e32 v131, v173, v131
	v_cvt_pk_bf16_f32 v188, v100, v104
	v_cvt_pk_bf16_f32 v189, v108, v112
	v_cvt_pk_bf16_f32 v190, v116, v120
	v_cvt_pk_bf16_f32 v191, v124, v128
	global_store_dwordx4 v182, v[188:191], s[68:69] sc1
	v_cvt_pk_bf16_f32 v192, v101, v105
	v_cvt_pk_bf16_f32 v193, v109, v113
	v_cvt_pk_bf16_f32 v194, v117, v121
	v_cvt_pk_bf16_f32 v195, v125, v129
	global_store_dwordx4 v183, v[192:195], s[68:69] sc1
	v_cvt_pk_bf16_f32 v196, v102, v106
	v_cvt_pk_bf16_f32 v197, v110, v114
	v_cvt_pk_bf16_f32 v198, v118, v122
	v_cvt_pk_bf16_f32 v199, v126, v130
	global_store_dwordx4 v184, v[196:199], s[68:69] sc1
	v_cvt_pk_bf16_f32 v200, v103, v107
	v_cvt_pk_bf16_f32 v201, v111, v115
	v_cvt_pk_bf16_f32 v202, v119, v123
	v_cvt_pk_bf16_f32 v203, v127, v131
	global_store_dwordx4 v185, v[200:203], s[68:69] sc1
	s_branch .Lcv_ret
.Lcv_nogain:
	global_load_dwordx4 v[4:7], v174, s[60:61] offset:0 nt
	global_load_dwordx4 v[8:11], v175, s[60:61] offset:0 nt
	global_load_dwordx4 v[12:15], v176, s[60:61] offset:0 nt
	global_load_dwordx4 v[16:19], v177, s[60:61] offset:0 nt
	global_load_dwordx4 v[20:23], v178, s[60:61] offset:0 nt
	global_load_dwordx4 v[24:27], v179, s[60:61] offset:0 nt
	global_load_dwordx4 v[28:31], v180, s[60:61] offset:0 nt
	global_load_dwordx4 v[32:35], v181, s[60:61] offset:0 nt
	global_load_dwordx4 v[36:39], v174, s[60:61] offset:128 nt
	global_load_dwordx4 v[40:43], v175, s[60:61] offset:128 nt
	global_load_dwordx4 v[44:47], v176, s[60:61] offset:128 nt
	global_load_dwordx4 v[48:51], v177, s[60:61] offset:128 nt
	global_load_dwordx4 v[52:55], v178, s[60:61] offset:128 nt
	global_load_dwordx4 v[56:59], v179, s[60:61] offset:128 nt
	global_load_dwordx4 v[60:63], v180, s[60:61] offset:128 nt
	global_load_dwordx4 v[64:67], v181, s[60:61] offset:128 nt
	global_load_dwordx4 v[68:71], v174, s[60:61] offset:256 nt
	global_load_dwordx4 v[72:75], v175, s[60:61] offset:256 nt
	global_load_dwordx4 v[76:79], v176, s[60:61] offset:256 nt
	global_load_dwordx4 v[80:83], v177, s[60:61] offset:256 nt
	global_load_dwordx4 v[84:87], v178, s[60:61] offset:256 nt
	global_load_dwordx4 v[88:91], v179, s[60:61] offset:256 nt
	global_load_dwordx4 v[92:95], v180, s[60:61] offset:256 nt
	global_load_dwordx4 v[96:99], v181, s[60:61] offset:256 nt
	global_load_dwordx4 v[100:103], v174, s[60:61] offset:384 nt
	global_load_dwordx4 v[104:107], v175, s[60:61] offset:384 nt
	global_load_dwordx4 v[108:111], v176, s[60:61] offset:384 nt
	global_load_dwordx4 v[112:115], v177, s[60:61] offset:384 nt
	global_load_dwordx4 v[116:119], v178, s[60:61] offset:384 nt
	global_load_dwordx4 v[120:123], v179, s[60:61] offset:384 nt
	global_load_dwordx4 v[124:127], v180, s[60:61] offset:384 nt
	global_load_dwordx4 v[128:131], v181, s[60:61] offset:384 nt
	s_add_u32 s60, s60, s70
	s_addc_u32 s61, s61, s71
	s_cmp_eq_u32 s74, 1
	s_cbranch_scc1 .Lcv_n_last
	s_waitcnt vmcnt(24)
	v_cvt_pk_bf16_f32 v188, v4, v8
	v_cvt_pk_bf16_f32 v189, v12, v16
	v_cvt_pk_bf16_f32 v190, v20, v24
	v_cvt_pk_bf16_f32 v191, v28, v32
	global_store_dwordx4 v182, v[188:191], s[62:63] sc1
	v_cvt_pk_bf16_f32 v192, v5, v9
	v_cvt_pk_bf16_f32 v193, v13, v17
	v_cvt_pk_bf16_f32 v194, v21, v25
	v_cvt_pk_bf16_f32 v195, v29, v33
	global_store_dwordx4 v183, v[192:195], s[62:63] sc1
	v_cvt_pk_bf16_f32 v196, v6, v10
	v_cvt_pk_bf16_f32 v197, v14, v18
	v_cvt_pk_bf16_f32 v198, v22, v26
	v_cvt_pk_bf16_f32 v199, v30, v34
	global_store_dwordx4 v184, v[196:199], s[62:63] sc1
	v_cvt_pk_bf16_f32 v200, v7, v11
	v_cvt_pk_bf16_f32 v201, v15, v19
	v_cvt_pk_bf16_f32 v202, v23, v27
	v_cvt_pk_bf16_f32 v203, v31, v35
	global_store_dwordx4 v185, v[200:203], s[62:63] sc1
	global_load_dwordx4 v[4:7], v174, s[60:61] offset:0 nt
	global_load_dwordx4 v[8:11], v175, s[60:61] offset:0 nt
	global_load_dwordx4 v[12:15], v176, s[60:61] offset:0 nt
	global_load_dwordx4 v[16:19], v177, s[60:61] offset:0 nt
	global_load_dwordx4 v[20:23], v178, s[60:61] offset:0 nt
	global_load_dwordx4 v[24:27], v179, s[60:61] offset:0 nt
	global_load_dwordx4 v[28:31], v180, s[60:61] offset:0 nt
	global_load_dwordx4 v[32:35], v181, s[60:61] offset:0 nt
	s_add_u32 s62, s62, s72
	s_addc_u32 s63, s63, s73
	s_waitcnt vmcnt(28)
; #define LAS __attribute__((address_space(3)))
; __device__ __forceinline__ unsigned cvt_pk_bf16(float lo, float hi) { unsigned r; asm volatile("v_cvt_pk_bf16_f32 %0, %1, %2" : "=v"(r) : "v"(lo), "v"(hi)); return r; }
; template <bool NT = true> __device__ __forceinline__ void tr_load(const TrDesc& d, f32x4 (&v)[8], int lane) {
;     const float* sp = d.src + (size_t)(lane >> 3) * d.ldn + 4 * (lane & 7);
; #pragma unroll
;     for (int i = 0; i < 8; ++i) v[i] = NT ? __builtin_nontemporal_load((const f32x4*)(sp + (size_t)(8 * i) * d.ldn)) : *(const f32x4*)(sp + (size_t)(8 * i) * d.ldn);
; }
; template <bool NT = true> __device__ __forceinline__ void tr_finish(const TrDesc& d, const f32x4 (&v)[8], LAS float* scr, int lane) {
;     const int c = lane & 7;
;     f32x4 g0 = {1.f, 1.f, 1.f, 1.f}, g1 = {1.f, 1.f, 1.f, 1.f};
;     if (d.gain) { g0 = *(const f32x4*)(d.gain + 8 * c); g1 = *(const f32x4*)(d.gain + 8 * c + 4); }
; #pragma unroll
;     for (int i = 0; i < 8; ++i) { LAS float* w = scr + (8 * i + (lane >> 3)) * 33 + 4 * c; w[0] = v[i].x; w[1] = v[i].y; w[2] = v[i].z; w[3] = v[i].w; }
;     LDS_WAIT(); asm volatile("" ::: "memory");
; #pragma unroll
;     for (int j = 0; j < 4; ++j) { const int n = (lane >> 3) + 8 * j; const LAS float* s = scr + (8 * c) * 33 + n;
;         u32x4 o; o.x = cvt_pk_bf16(s[0 * 33] * g0.x, s[1 * 33] * g0.y); o.y = cvt_pk_bf16(s[2 * 33] * g0.z, s[3 * 33] * g0.w); o.z = cvt_pk_bf16(s[4 * 33] * g1.x, s[5 * 33] * g1.y); o.w = cvt_pk_bf16(s[6 * 33] * g1.z, s[7 * 33] * g1.w);
;         if (NT) __builtin_nontemporal_store(o, (u32x4*)(d.dst + (size_t)n * d.K + 8 * c)); else *(u32x4*)(d.dst + (size_t)n * d.K + 8 * c) = o; }
; template <class F, bool NT = true> __device__ __forceinline__ void tr_run(F item, int first, int step, int n, LAS float* scr, int lane) {
;     ...
;     for (int it = first; it < n; it += 3 * step) {
;         const bool h1 = it + step < n, h2 = it + 2 * step < n, h3 = it + 3 * step < n, h4 = it + 4 * step < n;
;         if (h2) { dc = item(it + 2 * step); tr_load<NT>(dc, vc, lane); }
;         tr_finish<NT>(da, va, scr, lane);
;         if (h3) { da = item(it + 3 * step); tr_load<NT>(da, va, lane); }
;         if (h1) tr_finish<NT>(db, vb, scr, lane);
;         if (h4) { db = item(it + 4 * step); tr_load<NT>(db, vb, lane); }
;         if (h2) tr_finish<NT>(dc, vc, scr, lane);
;     }
	v_cvt_pk_bf16_f32 v188, v36, v40
	v_cvt_pk_bf16_f32 v189, v44, v48
	v_cvt_pk_bf16_f32 v190, v52, v56
	v_cvt_pk_bf16_f32 v191, v60, v64
	global_store_dwordx4 v182, v[188:191], s[64:65] sc1
	v_cvt_pk_bf16_f32 v192, v37, v41
	v_cvt_pk_bf16_f32 v193, v45, v49
	v_cvt_pk_bf16_f32 v194, v53, v57
	v_cvt_pk_bf16_f32 v195, v61, v65
	global_store_dwordx4 v183, v[192:195], s[64:65] sc1
	v_cvt_pk_bf16_f32 v196, v38, v42
	v_cvt_pk_bf16_f32 v197, v46, v50
	v_cvt_pk_bf16_f32 v198, v54, v58
	v_cvt_pk_bf16_f32 v199, v62, v66
	global_store_dwordx4 v184, v[196:199], s[64:65] sc1
	v_cvt_pk_bf16_f32 v200, v39, v43
	v_cvt_pk_bf16_f32 v201, v47, v51
	v_cvt_pk_bf16_f32 v202, v55, v59
	v_cvt_pk_bf16_f32 v203, v63, v67
	global_store_dwordx4 v185, v[200:203], s[64:65] sc1
	global_load_dwordx4 v[36:39], v174, s[60:61] offset:128 nt
	global_load_dwordx4 v[40:43], v175, s[60:61] offset:128 nt
	global_load_dwordx4 v[44:47], v176, s[60:61] offset:128 nt
	global_load_dwordx4 v[48:51], v177, s[60:61] offset:128 nt
	global_load_dwordx4 v[52:55], v178, s[60:61] offset:128 nt
	global_load_dwordx4 v[56:59], v179, s[60:61] offset:128 nt
	global_load_dwordx4 v[60:63], v180, s[60:61] offset:128 nt
	global_load_dwordx4 v[64:67], v181, s[60:61] offset:128 nt
	s_add_u32 s64, s64, s72
	s_addc_u32 s65, s65, s73
	s_waitcnt vmcnt(32)
	v_cvt_pk_bf16_f32 v188, v68, v72
	v_cvt_pk_bf16_f32 v189, v76, v80
	v_cvt_pk_bf16_f32 v190, v84, v88
	v_cvt_pk_bf16_f32 v191, v92, v96
	global_store_dwordx4 v182, v[188:191], s[66:67] sc1
	v_cvt_pk_bf16_f32 v192, v69, v73
	v_cvt_pk_bf16_f32 v193, v77, v81
	v_cvt_pk_bf16_f32 v194, v85, v89
	v_cvt_pk_bf16_f32 v195, v93, v97
	global_store_dwordx4 v183, v[192:195], s[66:67] sc1
	v_cvt_pk_bf16_f32 v196, v70, v74
	v_cvt_pk_bf16_f32 v197, v78, v82
	v_cvt_pk_bf16_f32 v198, v86, v90
	v_cvt_pk_bf16_f32 v199, v94, v98
	global_store_dwordx4 v184, v[196:199], s[66:67] sc1
	v_cvt_pk_bf16_f32 v200, v71, v75
	v_cvt_pk_bf16_f32 v201, v79, v83
	v_cvt_pk_bf16_f32 v202, v87, v91
	v_cvt_pk_bf16_f32 v203, v95, v99
	global_store_dwordx4 v185, v[200:203], s[66:67] sc1
	global_load_dwordx4 v[68:71], v174, s[60:61] offset:256 nt
	global_load_dwordx4 v[72:75], v175, s[60:61] offset:256 nt
	global_load_dwordx4 v[76:79], v176, s[60:61] offset:256 nt
	global_load_dwordx4 v[80:83], v177, s[60:61] offset:256 nt
	global_load_dwordx4 v[84:87], v178, s[60:61] offset:256 nt
	global_load_dwordx4 v[88:91], v179, s[60:61] offset:256 nt
	global_load_dwordx4 v[92:95], v180, s[60:61] offset:256 nt
	global_load_dwordx4 v[96:99], v181, s[60:61] offset:256 nt
	s_add_u32 s66, s66, s72
	s_addc_u32 s67, s67, s73
	s_waitcnt vmcnt(36)
	v_cvt_pk_bf16_f32 v188, v100, v104
	v_cvt_pk_bf16_f32 v189, v108, v112
	v_cvt_pk_bf16_f32 v190, v116, v120
	v_cvt_pk_bf16_f32 v191, v124, v128
	global_store_dwordx4 v182, v[188:191], s[68:69] sc1
	v_cvt_pk_bf16_f32 v192, v101, v105
	v_cvt_pk_bf16_f32 v193, v109, v113
	v_cvt_pk_bf16_f32 v194, v117, v121
	v_cvt_pk_bf16_f32 v195, v125, v129
	global_store_dwordx4 v183, v[192:195], s[68:69] sc1
	v_cvt_pk_bf16_f32 v196, v102, v106
	v_cvt_pk_bf16_f32 v197, v110, v114
	v_cvt_pk_bf16_f32 v198, v118, v122
	v_cvt_pk_bf16_f32 v199, v126, v130
	global_store_dwordx4 v184, v[196:199], s[68:69] sc1
	v_cvt_pk_bf16_f32 v200, v103, v107
	v_cvt_pk_bf16_f32 v201, v111, v115
	v_cvt_pk_bf16_f32 v202, v119, v123
	v_cvt_pk_bf16_f32 v203, v127, v131
	global_store_dwordx4 v185, v[200:203], s[68:69] sc1
	global_load_dwordx4 v[100:103], v174, s[60:61] offset:384 nt
	global_load_dwordx4 v[104:107], v175, s[60:61] offset:384 nt
	global_load_dwordx4 v[108:111], v176, s[60:61] offset:384 nt
	global_load_dwordx4 v[112:115], v177, s[60:61] offset:384 nt
	global_load_dwordx4 v[116:119], v178, s[60:61] offset:384 nt
	global_load_dwordx4 v[120:123], v179, s[60:61] offset:384 nt
	global_load_dwordx4 v[124:127], v180, s[60:61] offset:384 nt
	global_load_dwordx4 v[128:131], v181, s[60:61] offset:384 nt
	s_add_u32 s68, s68, s72
	s_addc_u32 s69, s69, s73
	s_add_u32 s60, s60, s70
	s_addc_u32 s61, s61, s71
	s_sub_i32 s74, s74, 1
	s_cmp_eq_u32 s74, 1
	s_cbranch_scc1 .Lcv_n_last
.Lcv_n_steady:
	s_waitcnt vmcnt(36)
	v_cvt_pk_bf16_f32 v188, v4, v8
	v_cvt_pk_bf16_f32 v189, v12, v16
	v_cvt_pk_bf16_f32 v190, v20, v24
	v_cvt_pk_bf16_f32 v191, v28, v32
	global_store_dwordx4 v182, v[188:191], s[62:63] sc1
	v_cvt_pk_bf16_f32 v192, v5, v9
	v_cvt_pk_bf16_f32 v193, v13, v17
	v_cvt_pk_bf16_f32 v194, v21, v25
	v_cvt_pk_bf16_f32 v195, v29, v33
	global_store_dwordx4 v183, v[192:195], s[62:63] sc1
	v_cvt_pk_bf16_f32 v196, v6, v10
	v_cvt_pk_bf16_f32 v197, v14, v18
	v_cvt_pk_bf16_f32 v198, v22, v26
	v_cvt_pk_bf16_f32 v199, v30, v34
	global_store_dwordx4 v184, v[196:199], s[62:63] sc1
	v_cvt_pk_bf16_f32 v200, v7, v11
	v_cvt_pk_bf16_f32 v201, v15, v19
	v_cvt_pk_bf16_f32 v202, v23, v27
	v_cvt_pk_bf16_f32 v203, v31, v35
	global_store_dwordx4 v185, v[200:203], s[62:63] sc1
	global_load_dwordx4 v[4:7], v174, s[60:61] offset:0 nt
	global_load_dwordx4 v[8:11], v175, s[60:61] offset:0 nt
	global_load_dwordx4 v[12:15], v176, s[60:61] offset:0 nt
	global_load_dwordx4 v[16:19], v177, s[60:61] offset:0 nt
	global_load_dwordx4 v[20:23], v178, s[60:61] offset:0 nt
	global_load_dwordx4 v[24:27], v179, s[60:61] offset:0 nt
	global_load_dwordx4 v[28:31], v180, s[60:61] offset:0 nt
	global_load_dwordx4 v[32:35], v181, s[60:61] offset:0 nt
	s_add_u32 s62, s62, s72
	s_addc_u32 s63, s63, s73
	s_waitcnt vmcnt(36)
; #define LAS __attribute__((address_space(3)))
; __device__ __forceinline__ unsigned cvt_pk_bf16(float lo, float hi) { unsigned r; asm volatile("v_cvt_pk_bf16_f32 %0, %1, %2" : "=v"(r) : "v"(lo), "v"(hi)); return r; }
; template <bool NT = true> __device__ __forceinline__ void tr_load(const TrDesc& d, f32x4 (&v)[8], int lane) {
;     const float* sp = d.src + (size_t)(lane >> 3) * d.ldn + 4 * (lane & 7);
; #pragma unroll
;     for (int i = 0; i < 8; ++i) v[i] = NT ? __builtin_nontemporal_load((const f32x4*)(sp + (size_t)(8 * i) * d.ldn)) : *(const f32x4*)(sp + (size_t)(8 * i) * d.ldn);
; }
; template <bool NT = true> __device__ __forceinline__ void tr_finish(const TrDesc& d, const f32x4 (&v)[8], LAS float* scr, int lane) {
;     const int c = lane & 7;
;     f32x4 g0 = {1.f, 1.f, 1.f, 1.f}, g1 = {1.f, 1.f, 1.f, 1.f};
;     if (d.gain) { g0 = *(const f32x4*)(d.gain + 8 * c); g1 = *(const f32x4*)(d.gain + 8 * c + 4); }
; #pragma unroll
;     for (int i = 0; i < 8; ++i) { LAS float* w = scr + (8 * i + (lane >> 3)) * 33 + 4 * c; w[0] = v[i].x; w[1] = v[i].y; w[2] = v[i].z; w[3] = v[i].w; }
;     LDS_WAIT(); asm volatile("" ::: "memory");
; #pragma unroll
;     for (int j = 0; j < 4; ++j) { const int n = (lane >> 3) + 8 * j; const LAS float* s = scr + (8 * c) * 33 + n;
;         u32x4 o; o.x = cvt_pk_bf16(s[0 * 33] * g0.x, s[1 * 33] * g0.y); o.y = cvt_pk_bf16(s[2 * 33] * g0.z, s[3 * 33] * g0.w); o.z = cvt_pk_bf16(s[4 * 33] * g1.x, s[5 * 33] * g1.y); o.w = cvt_pk_bf16(s[6 * 33] * g1.z, s[7 * 33] * g1.w);
;         if (NT) __builtin_nontemporal_store(o, (u32x4*)(d.dst + (size_t)n * d.K + 8 * c)); else *(u32x4*)(d.dst + (size_t)n * d.K + 8 * c) = o; }
; template <class F, bool NT = true> __device__ __forceinline__ void tr_run(F item, int first, int step, int n, LAS float* scr, int lane) {
;     ...
;     for (int it = first; it < n; it += 3 * step) {
;         const bool h1 = it + step < n, h2 = it + 2 * step < n, h3 = it + 3 * step < n, h4 = it + 4 * step < n;
;         if (h2) { dc = item(it + 2 * step); tr_load<NT>(dc, vc, lane); }
;         tr_finish<NT>(da, va, scr, lane);
;         if (h3) { da = item(it + 3 * step); tr_load<NT>(da, va, lane); }
;         if (h1) tr_finish<NT>(db, vb, scr, lane);
;         if (h4) { db = item(it + 4 * step); tr_load<NT>(db, vb, lane); }
;         if (h2) tr_finish<NT>(dc, vc, scr, lane);
;     }
	v_cvt_pk_bf16_f32 v188, v36, v40
	v_cvt_pk_bf16_f32 v189, v44, v48
	v_cvt_pk_bf16_f32 v190, v52, v56
	v_cvt_pk_bf16_f32 v191, v60, v64
	global_store_dwordx4 v182, v[188:191], s[64:65] sc1
	v_cvt_pk_bf16_f32 v192, v37, v41
	v_cvt_pk_bf16_f32 v193, v45, v49
	v_cvt_pk_bf16_f32 v194, v53, v57
	v_cvt_pk_bf16_f32 v195, v61, v65
	global_store_dwordx4 v183, v[192:195], s[64:65] sc1
	v_cvt_pk_bf16_f32 v196, v38, v42
	v_cvt_pk_bf16_f32 v197, v46, v50
	v_cvt_pk_bf16_f32 v198, v54, v58
	v_cvt_pk_bf16_f32 v199, v62, v66
	global_store_dwordx4 v184, v[196:199], s[64:65] sc1
	v_cvt_pk_bf16_f32 v200, v39, v43
	v_cvt_pk_bf16_f32 v201, v47, v51
	v_cvt_pk_bf16_f32 v202, v55, v59
	v_cvt_pk_bf16_f32 v203, v63, v67
	global_store_dwordx4 v185, v[200:203], s[64:65] sc1
	global_load_dwordx4 v[36:39], v174, s[60:61] offset:128 nt
	global_load_dwordx4 v[40:43], v175, s[60:61] offset:128 nt
	global_load_dwordx4 v[44:47], v176, s[60:61] offset:128 nt
	global_load_dwordx4 v[48:51], v177, s[60:61] offset:128 nt
	global_load_dwordx4 v[52:55], v178, s[60:61] offset:128 nt
	global_load_dwordx4 v[56:59], v179, s[60:61] offset:128 nt
	global_load_dwordx4 v[60:63], v180, s[60:61] offset:128 nt
	global_load_dwordx4 v[64:67], v181, s[60:61] offset:128 nt
	s_add_u32 s64, s64, s72
	s_addc_u32 s65, s65, s73
	s_waitcnt vmcnt(36)
	v_cvt_pk_bf16_f32 v188, v68, v72
	v_cvt_pk_bf16_f32 v189, v76, v80
	v_cvt_pk_bf16_f32 v190, v84, v88
	v_cvt_pk_bf16_f32 v191, v92, v96
	global_store_dwordx4 v182, v[188:191], s[66:67] sc1
	v_cvt_pk_bf16_f32 v192, v69, v73
	v_cvt_pk_bf16_f32 v193, v77, v81
	v_cvt_pk_bf16_f32 v194, v85, v89
	v_cvt_pk_bf16_f32 v195, v93, v97
	global_store_dwordx4 v183, v[192:195], s[66:67] sc1
	v_cvt_pk_bf16_f32 v196, v70, v74
	v_cvt_pk_bf16_f32 v197, v78, v82
	v_cvt_pk_bf16_f32 v198, v86, v90
	v_cvt_pk_bf16_f32 v199, v94, v98
	global_store_dwordx4 v184, v[196:199], s[66:67] sc1
	v_cvt_pk_bf16_f32 v200, v71, v75
	v_cvt_pk_bf16_f32 v201, v79, v83
	v_cvt_pk_bf16_f32 v202, v87, v91
	v_cvt_pk_bf16_f32 v203, v95, v99
	global_store_dwordx4 v185, v[200:203], s[66:67] sc1
	global_load_dwordx4 v[68:71], v174, s[60:61] offset:256 nt
	global_load_dwordx4 v[72:75], v175, s[60:61] offset:256 nt
	global_load_dwordx4 v[76:79], v176, s[60:61] offset:256 nt
	global_load_dwordx4 v[80:83], v177, s[60:61] offset:256 nt
	global_load_dwordx4 v[84:87], v178, s[60:61] offset:256 nt
	global_load_dwordx4 v[88:91], v179, s[60:61] offset:256 nt
	global_load_dwordx4 v[92:95], v180, s[60:61] offset:256 nt
	global_load_dwordx4 v[96:99], v181, s[60:61] offset:256 nt
	s_add_u32 s66, s66, s72
	s_addc_u32 s67, s67, s73
	s_waitcnt vmcnt(36)
	v_cvt_pk_bf16_f32 v188, v100, v104
	v_cvt_pk_bf16_f32 v189, v108, v112
	v_cvt_pk_bf16_f32 v190, v116, v120
	v_cvt_pk_bf16_f32 v191, v124, v128
	global_store_dwordx4 v182, v[188:191], s[68:69] sc1
	v_cvt_pk_bf16_f32 v192, v101, v105
	v_cvt_pk_bf16_f32 v193, v109, v113
	v_cvt_pk_bf16_f32 v194, v117, v121
	v_cvt_pk_bf16_f32 v195, v125, v129
	global_store_dwordx4 v183, v[192:195], s[68:69] sc1
	v_cvt_pk_bf16_f32 v196, v102, v106
	v_cvt_pk_bf16_f32 v197, v110, v114
	v_cvt_pk_bf16_f32 v198, v118, v122
	v_cvt_pk_bf16_f32 v199, v126, v130
	global_store_dwordx4 v184, v[196:199], s[68:69] sc1
	v_cvt_pk_bf16_f32 v200, v103, v107
	v_cvt_pk_bf16_f32 v201, v111, v115
	v_cvt_pk_bf16_f32 v202, v119, v123
	v_cvt_pk_bf16_f32 v203, v127, v131
	global_store_dwordx4 v185, v[200:203], s[68:69] sc1
	global_load_dwordx4 v[100:103], v174, s[60:61] offset:384 nt
	global_load_dwordx4 v[104:107], v175, s[60:61] offset:384 nt
	global_load_dwordx4 v[108:111], v176, s[60:61] offset:384 nt
	global_load_dwordx4 v[112:115], v177, s[60:61] offset:384 nt
	global_load_dwordx4 v[116:119], v178, s[60:61] offset:384 nt
	global_load_dwordx4 v[120:123], v179, s[60:61] offset:384 nt
	global_load_dwordx4 v[124:127], v180, s[60:61] offset:384 nt
	global_load_dwordx4 v[128:131], v181, s[60:61] offset:384 nt
	s_add_u32 s68, s68, s72
	s_addc_u32 s69, s69, s73
	s_add_u32 s60, s60, s70
	s_addc_u32 s61, s61, s71
	s_sub_i32 s74, s74, 1
	s_cmp_eq_u32 s74, 1
	s_cbranch_scc0 .Lcv_n_steady
; #define LAS __attribute__((address_space(3)))
; __device__ __forceinline__ unsigned cvt_pk_bf16(float lo, float hi) { unsigned r; asm volatile("v_cvt_pk_bf16_f32 %0, %1, %2" : "=v"(r) : "v"(lo), "v"(hi)); return r; }
; #define LDS_WAIT() asm volatile("s_waitcnt lgkmcnt(0)" ::: "memory")
; __device__ __forceinline__ unsigned cvt_pk_bf16(float lo, float hi) { unsigned r; asm volatile("v_cvt_pk_bf16_f32 %0, %1, %2" : "=v"(r) : "v"(lo), "v"(hi)); return r; }
; template <bool NT = true> __device__ __forceinline__ void tr_load(const TrDesc& d, f32x4 (&v)[8], int lane) {
;     const float* sp = d.src + (size_t)(lane >> 3) * d.ldn + 4 * (lane & 7);
; #pragma unroll
;     for (int i = 0; i < 8; ++i) v[i] = NT ? __builtin_nontemporal_load((const f32x4*)(sp + (size_t)(8 * i) * d.ldn)) : *(const f32x4*)(sp + (size_t)(8 * i) * d.ldn);
; }
; template <bool NT = true> __device__ __forceinline__ void tr_finish(const TrDesc& d, const f32x4 (&v)[8], LAS float* scr, int lane) {
;     const int c = lane & 7;
;     f32x4 g0 = {1.f, 1.f, 1.f, 1.f}, g1 = {1.f, 1.f, 1.f, 1.f};
;     if (d.gain) { g0 = *(const f32x4*)(d.gain + 8 * c); g1 = *(const f32x4*)(d.gain + 8 * c + 4); }
; #pragma unroll
;     for (int i = 0; i < 8; ++i) { LAS float* w = scr + (8 * i + (lane >> 3)) * 33 + 4 * c; w[0] = v[i].x; w[1] = v[i].y; w[2] = v[i].z; w[3] = v[i].w; }
;     LDS_WAIT(); asm volatile("" ::: "memory");
; #pragma unroll
;     for (int j = 0; j < 4; ++j) { const int n = (lane >> 3) + 8 * j; const LAS float* s = scr + (8 * c) * 33 + n;
;         u32x4 o; o.x = cvt_pk_bf16(s[0 * 33] * g0.x, s[1 * 33] * g0.y); o.y = cvt_pk_bf16(s[2 * 33] * g0.z, s[3 * 33] * g0.w); o.z = cvt_pk_bf16(s[4 * 33] * g1.x, s[5 * 33] * g1.y); o.w = cvt_pk_bf16(s[6 * 33] * g1.z, s[7 * 33] * g1.w);
;         if (NT) __builtin_nontemporal_store(o, (u32x4*)(d.dst + (size_t)n * d.K + 8 * c)); else *(u32x4*)(d.dst + (size_t)n * d.K + 8 * c) = o; }
.Lcv_n_last:
	s_waitcnt vmcnt(24)
	v_cvt_pk_bf16_f32 v188, v4, v8
	v_cvt_pk_bf16_f32 v189, v12, v16
	v_cvt_pk_bf16_f32 v190, v20, v24
	v_cvt_pk_bf16_f32 v191, v28, v32
	global_store_dwordx4 v182, v[188:191], s[62:63] sc1
	v_cvt_pk_bf16_f32 v192, v5, v9
	v_cvt_pk_bf16_f32 v193, v13, v17
	v_cvt_pk_bf16_f32 v194, v21, v25
	v_cvt_pk_bf16_f32 v195, v29, v33
	global_store_dwordx4 v183, v[192:195], s[62:63] sc1
	v_cvt_pk_bf16_f32 v196, v6, v10
	v_cvt_pk_bf16_f32 v197, v14, v18
	v_cvt_pk_bf16_f32 v198, v22, v26
	v_cvt_pk_bf16_f32 v199, v30, v34
	global_store_dwordx4 v184, v[196:199], s[62:63] sc1
	v_cvt_pk_bf16_f32 v200, v7, v11
	v_cvt_pk_bf16_f32 v201, v15, v19
	v_cvt_pk_bf16_f32 v202, v23, v27
	v_cvt_pk_bf16_f32 v203, v31, v35
	global_store_dwordx4 v185, v[200:203], s[62:63] sc1
	s_waitcnt vmcnt(20)
	v_cvt_pk_bf16_f32 v188, v36, v40
	v_cvt_pk_bf16_f32 v189, v44, v48
	v_cvt_pk_bf16_f32 v190, v52, v56
	v_cvt_pk_bf16_f32 v191, v60, v64
	global_store_dwordx4 v182, v[188:191], s[64:65] sc1
	v_cvt_pk_bf16_f32 v192, v37, v41
	v_cvt_pk_bf16_f32 v193, v45, v49
	v_cvt_pk_bf16_f32 v194, v53, v57
	v_cvt_pk_bf16_f32 v195, v61, v65
	global_store_dwordx4 v183, v[192:195], s[64:65] sc1
	v_cvt_pk_bf16_f32 v196, v38, v42
	v_cvt_pk_bf16_f32 v197, v46, v50
	v_cvt_pk_bf16_f32 v198, v54, v58
	v_cvt_pk_bf16_f32 v199, v62, v66
	global_store_dwordx4 v184, v[196:199], s[64:65] sc1
	v_cvt_pk_bf16_f32 v200, v39, v43
	v_cvt_pk_bf16_f32 v201, v47, v51
	v_cvt_pk_bf16_f32 v202, v55, v59
	v_cvt_pk_bf16_f32 v203, v63, v67
	global_store_dwordx4 v185, v[200:203], s[64:65] sc1
	s_waitcnt vmcnt(16)
	v_cvt_pk_bf16_f32 v188, v68, v72
	v_cvt_pk_bf16_f32 v189, v76, v80
	v_cvt_pk_bf16_f32 v190, v84, v88
	v_cvt_pk_bf16_f32 v191, v92, v96
	global_store_dwordx4 v182, v[188:191], s[66:67] sc1
	v_cvt_pk_bf16_f32 v192, v69, v73
	v_cvt_pk_bf16_f32 v193, v77, v81
	v_cvt_pk_bf16_f32 v194, v85, v89
	v_cvt_pk_bf16_f32 v195, v93, v97
	global_store_dwordx4 v183, v[192:195], s[66:67] sc1
	v_cvt_pk_bf16_f32 v196, v70, v74
	v_cvt_pk_bf16_f32 v197, v78, v82
	v_cvt_pk_bf16_f32 v198, v86, v90
	v_cvt_pk_bf16_f32 v199, v94, v98
	global_store_dwordx4 v184, v[196:199], s[66:67] sc1
	v_cvt_pk_bf16_f32 v200, v71, v75
	v_cvt_pk_bf16_f32 v201, v79, v83
	v_cvt_pk_bf16_f32 v202, v87, v91
	v_cvt_pk_bf16_f32 v203, v95, v99
	global_store_dwordx4 v185, v[200:203], s[66:67] sc1
	s_waitcnt vmcnt(12)
	v_cvt_pk_bf16_f32 v188, v100, v104
	v_cvt_pk_bf16_f32 v189, v108, v112
	v_cvt_pk_bf16_f32 v190, v116, v120
	v_cvt_pk_bf16_f32 v191, v124, v128
	global_store_dwordx4 v182, v[188:191], s[68:69] sc1
	v_cvt_pk_bf16_f32 v192, v101, v105
	v_cvt_pk_bf16_f32 v193, v109, v113
	v_cvt_pk_bf16_f32 v194, v117, v121
	v_cvt_pk_bf16_f32 v195, v125, v129
	global_store_dwordx4 v183, v[192:195], s[68:69] sc1
	v_cvt_pk_bf16_f32 v196, v102, v106
	v_cvt_pk_bf16_f32 v197, v110, v114
	v_cvt_pk_bf16_f32 v198, v118, v122
	v_cvt_pk_bf16_f32 v199, v126, v130
	global_store_dwordx4 v184, v[196:199], s[68:69] sc1
	v_cvt_pk_bf16_f32 v200, v103, v107
	v_cvt_pk_bf16_f32 v201, v111, v115
	v_cvt_pk_bf16_f32 v202, v119, v123
	v_cvt_pk_bf16_f32 v203, v127, v131
	global_store_dwordx4 v185, v[200:203], s[68:69] sc1
	s_branch .Lcv_ret

; #define LAS __attribute__((address_space(3)))
; __device__ __forceinline__ unsigned cvt_pk_bf16(float lo, float hi) { unsigned r; asm volatile("v_cvt_pk_bf16_f32 %0, %1, %2" : "=v"(r) : "v"(lo), "v"(hi)); return r; }
; #define LDS_WAIT() asm volatile("s_waitcnt lgkmcnt(0)" ::: "memory")
; __device__ __forceinline__ unsigned cvt_pk_bf16(float lo, float hi) { unsigned r; asm volatile("v_cvt_pk_bf16_f32 %0, %1, %2" : "=v"(r) : "v"(lo), "v"(hi)); return r; }
; template <bool NT = true> __device__ __forceinline__ void tr_finish(const TrDesc& d, const f32x4 (&v)[8], LAS float* scr, int lane) {
;     const int c = lane & 7;
;     f32x4 g0 = {1.f, 1.f, 1.f, 1.f}, g1 = {1.f, 1.f, 1.f, 1.f};
;     if (d.gain) { g0 = *(const f32x4*)(d.gain + 8 * c); g1 = *(const f32x4*)(d.gain + 8 * c + 4); }
; #pragma unroll
;     for (int i = 0; i < 8; ++i) { LAS float* w = scr + (8 * i + (lane >> 3)) * 33 + 4 * c; w[0] = v[i].x; w[1] = v[i].y; w[2] = v[i].z; w[3] = v[i].w; }
;     LDS_WAIT(); asm volatile("" ::: "memory");
; #pragma unroll
;     for (int j = 0; j < 4; ++j) { const int n = (lane >> 3) + 8 * j; const LAS float* s = scr + (8 * c) * 33 + n;
;         u32x4 o; o.x = cvt_pk_bf16(s[0 * 33] * g0.x, s[1 * 33] * g0.y); o.y = cvt_pk_bf16(s[2 * 33] * g0.z, s[3 * 33] * g0.w); o.z = cvt_pk_bf16(s[4 * 33] * g1.x, s[5 * 33] * g1.y); o.w = cvt_pk_bf16(s[6 * 33] * g1.z, s[7 * 33] * g1.w);
;         if (NT) __builtin_nontemporal_store(o, (u32x4*)(d.dst + (size_t)n * d.K + 8 * c)); else *(u32x4*)(d.dst + (size_t)n * d.K + 8 * c) = o; }
;     LDS_WAIT(); asm volatile("" ::: "memory");
; }
; template <class F, bool NT = true> __device__ __forceinline__ void tr_run(F item, int first, int step, int n, LAS float* scr, int lane) {
;     ...
;     for (int it = first; it < n; it += 3 * step) {
;         const bool h1 = it + step < n, h2 = it + 2 * step < n, h3 = it + 3 * step < n, h4 = it + 4 * step < n;
;         if (h2) { dc = item(it + 2 * step); tr_load<NT>(dc, vc, lane); }
;         tr_finish<NT>(da, va, scr, lane);
;         if (h3) { da = item(it + 3 * step); tr_load<NT>(da, va, lane); }
;         if (h1) tr_finish<NT>(db, vb, scr, lane);
;         if (h4) { db = item(it + 4 * step); tr_load<NT>(db, vb, lane); }
;         if (h2) tr_finish<NT>(dc, vc, scr, lane);
;     }
.LBB0_1142:
	v_add_u32_e32 v111, 0x420, v110
	v_add_u32_e32 v112, 0x428, v110
	v_add_u32_e32 v113, 0x840, v110
	v_add_u32_e32 v114, 0x848, v110
	v_add_u32_e32 v115, 0xc60, v110
	v_add_u32_e32 v116, 0xc68, v110
	v_add_u32_e32 v117, 0x1080, v110
	v_add_u32_e32 v118, 0x1088, v110
	v_add_u32_e32 v119, 0x14a0, v110
	v_add_u32_e32 v120, 0x14a8, v110
	v_add_u32_e32 v121, 0x18c0, v110
	v_add_u32_e32 v122, 0x18c8, v110
	v_add_u32_e32 v123, 0x1ce0, v110
	v_add_u32_e32 v124, 0x1ce8, v110
	s_waitcnt vmcnt(7)
	ds_write2_b32 v110, v2, v3 offset1:1
	ds_write2_b32 v110, v4, v5 offset0:2 offset1:3
	s_waitcnt vmcnt(6)
	ds_write2_b32 v111, v6, v7 offset1:1
	ds_write2_b32 v112, v8, v9 offset1:1
	s_waitcnt vmcnt(5)
	ds_write2_b32 v113, v10, v11 offset1:1
	ds_write2_b32 v114, v12, v13 offset1:1
	s_waitcnt vmcnt(4)
	ds_write2_b32 v115, v14, v15 offset1:1
	ds_write2_b32 v116, v16, v17 offset1:1
	s_waitcnt vmcnt(3)
	ds_write2_b32 v117, v18, v19 offset1:1
	ds_write2_b32 v118, v20, v21 offset1:1
	s_waitcnt vmcnt(2)
	ds_write2_b32 v119, v22, v23 offset1:1
	ds_write2_b32 v120, v24, v25 offset1:1
	s_waitcnt vmcnt(1)
	ds_write2_b32 v121, v26, v27 offset1:1
	ds_write2_b32 v122, v28, v29 offset1:1
	s_waitcnt vmcnt(0)
	ds_write2_b32 v123, v30, v31 offset1:1
	ds_write2_b32 v124, v32, v33 offset1:1
	s_waitcnt lgkmcnt(0)
	ds_read2_b32 v[126:127], v105 offset1:33
	s_waitcnt lgkmcnt(0)
	v_cvt_pk_bf16_f32 v126, v126, v127
	ds_read2_b32 v[128:129], v105 offset0:66 offset1:99
	s_waitcnt lgkmcnt(0)
	v_cvt_pk_bf16_f32 v127, v128, v129
	ds_read2_b32 v[128:129], v105 offset0:132 offset1:165
	v_lshl_add_u64 v[132:133], s[4:5], 0, v[106:107]
	v_lshlrev_b32_e32 v98, 1, v104
	s_waitcnt lgkmcnt(0)
	v_cvt_pk_bf16_f32 v128, v128, v129
	ds_read2_b32 v[130:131], v105 offset0:198 offset1:231
	s_waitcnt lgkmcnt(0)
	v_cvt_pk_bf16_f32 v129, v130, v131
	v_lshl_add_u64 v[132:133], v[132:133], 0, v[98:99]
	ds_read2_b32 v[130:131], v105 offset0:8 offset1:41
	global_store_dwordx4 v[132:133], v[126:129], off sc1
	v_lshl_add_u64 v[132:133], s[4:5], 0, v[108:109]
	v_lshl_add_u64 v[132:133], v[132:133], 0, v[98:99]
	s_waitcnt lgkmcnt(0)
	v_cvt_pk_bf16_f32 v126, v130, v131
	ds_read2_b32 v[128:129], v105 offset0:74 offset1:107
	s_waitcnt lgkmcnt(0)
	v_cvt_pk_bf16_f32 v127, v128, v129
	ds_read2_b32 v[128:129], v105 offset0:140 offset1:173
	s_waitcnt lgkmcnt(0)
	v_cvt_pk_bf16_f32 v128, v128, v129
	ds_read2_b32 v[130:131], v105 offset0:206 offset1:239
	s_waitcnt lgkmcnt(0)
	v_cvt_pk_bf16_f32 v129, v130, v131
	ds_read2_b32 v[130:131], v105 offset0:16 offset1:49
	global_store_dwordx4 v[132:133], v[126:129], off sc1
	v_add_co_u32_e32 v134, vcc, s25, v132
	s_waitcnt lgkmcnt(0)
	v_cvt_pk_bf16_f32 v126, v130, v131
	ds_read2_b32 v[128:129], v105 offset0:82 offset1:115
	s_waitcnt lgkmcnt(0)
	v_cvt_pk_bf16_f32 v127, v128, v129
	ds_read2_b32 v[128:129], v105 offset0:148 offset1:181
	s_waitcnt lgkmcnt(0)
	v_cvt_pk_bf16_f32 v128, v128, v129
	ds_read2_b32 v[130:131], v105 offset0:214 offset1:247
	s_waitcnt lgkmcnt(0)
	v_cvt_pk_bf16_f32 v129, v130, v131
	v_addc_co_u32_e32 v135, vcc, 0, v133, vcc
	ds_read2_b32 v[130:131], v105 offset0:24 offset1:57
	global_store_dwordx4 v[134:135], v[126:129], off sc1
	v_add_co_u32_e32 v132, vcc, 0x56000, v132
	s_waitcnt lgkmcnt(0)
	v_cvt_pk_bf16_f32 v126, v130, v131
	ds_read2_b32 v[128:129], v105 offset0:90 offset1:123
	s_waitcnt lgkmcnt(0)
	v_cvt_pk_bf16_f32 v127, v128, v129
	ds_read2_b32 v[128:129], v105 offset0:156 offset1:189
	v_addc_co_u32_e32 v133, vcc, 0, v133, vcc
	s_waitcnt lgkmcnt(0)
	v_cvt_pk_bf16_f32 v128, v128, v129
	ds_read2_b32 v[130:131], v105 offset0:222 offset1:255
	s_waitcnt lgkmcnt(0)
	v_cvt_pk_bf16_f32 v129, v130, v131
	global_store_dwordx4 v[132:133], v[126:129], off sc1
	s_waitcnt lgkmcnt(0)
	s_add_i32 s27, s21, s26
	s_cmpk_gt_i32 s27, 0x3fff
	s_cbranch_scc0 .LBB0_1146
	s_add_i32 s27, s23, s26
	s_cmpk_gt_i32 s27, 0x3fff
	s_cbranch_scc0 .LBB0_1147

; #define LAS __attribute__((address_space(3)))
; __device__ __forceinline__ unsigned cvt_pk_bf16(float lo, float hi) { unsigned r; asm volatile("v_cvt_pk_bf16_f32 %0, %1, %2" : "=v"(r) : "v"(lo), "v"(hi)); return r; }
; #define LDS_WAIT() asm volatile("s_waitcnt lgkmcnt(0)" ::: "memory")
; __device__ __forceinline__ unsigned cvt_pk_bf16(float lo, float hi) { unsigned r; asm volatile("v_cvt_pk_bf16_f32 %0, %1, %2" : "=v"(r) : "v"(lo), "v"(hi)); return r; }
; template <bool NT = true> __device__ __forceinline__ void tr_finish(const TrDesc& d, const f32x4 (&v)[8], LAS float* scr, int lane) {
;     const int c = lane & 7;
;     f32x4 g0 = {1.f, 1.f, 1.f, 1.f}, g1 = {1.f, 1.f, 1.f, 1.f};
;     if (d.gain) { g0 = *(const f32x4*)(d.gain + 8 * c); g1 = *(const f32x4*)(d.gain + 8 * c + 4); }
; #pragma unroll
;     for (int i = 0; i < 8; ++i) { LAS float* w = scr + (8 * i + (lane >> 3)) * 33 + 4 * c; w[0] = v[i].x; w[1] = v[i].y; w[2] = v[i].z; w[3] = v[i].w; }
;     LDS_WAIT(); asm volatile("" ::: "memory");
; #pragma unroll
;     for (int j = 0; j < 4; ++j) { const int n = (lane >> 3) + 8 * j; const LAS float* s = scr + (8 * c) * 33 + n;
;         u32x4 o; o.x = cvt_pk_bf16(s[0 * 33] * g0.x, s[1 * 33] * g0.y); o.y = cvt_pk_bf16(s[2 * 33] * g0.z, s[3 * 33] * g0.w); o.z = cvt_pk_bf16(s[4 * 33] * g1.x, s[5 * 33] * g1.y); o.w = cvt_pk_bf16(s[6 * 33] * g1.z, s[7 * 33] * g1.w);
;         if (NT) __builtin_nontemporal_store(o, (u32x4*)(d.dst + (size_t)n * d.K + 8 * c)); else *(u32x4*)(d.dst + (size_t)n * d.K + 8 * c) = o; }
;     LDS_WAIT(); asm volatile("" ::: "memory");
; }
; template <class F, bool NT = true> __device__ __forceinline__ void tr_run(F item, int first, int step, int n, LAS float* scr, int lane) {
;     ...
;     for (int it = first; it < n; it += 3 * step) {
;         const bool h1 = it + step < n, h2 = it + 2 * step < n, h3 = it + 3 * step < n, h4 = it + 4 * step < n;
;         if (h2) { dc = item(it + 2 * step); tr_load<NT>(dc, vc, lane); }
;         tr_finish<NT>(da, va, scr, lane);
;         if (h3) { da = item(it + 3 * step); tr_load<NT>(da, va, lane); }
;         if (h1) tr_finish<NT>(db, vb, scr, lane);
;         if (h4) { db = item(it + 4 * step); tr_load<NT>(db, vb, lane); }
;         if (h2) tr_finish<NT>(dc, vc, scr, lane);
;     }
.LBB0_1147:
	ds_write2_b32 v110, v34, v35 offset1:1
	ds_write2_b32 v110, v36, v37 offset0:2 offset1:3
	ds_write2_b32 v111, v38, v39 offset1:1
	ds_write2_b32 v112, v40, v41 offset1:1
	ds_write2_b32 v113, v42, v43 offset1:1
	ds_write2_b32 v114, v44, v45 offset1:1
	ds_write2_b32 v115, v46, v47 offset1:1
	ds_write2_b32 v116, v48, v49 offset1:1
	ds_write2_b32 v117, v50, v51 offset1:1
	ds_write2_b32 v118, v52, v53 offset1:1
	ds_write2_b32 v119, v54, v55 offset1:1
	ds_write2_b32 v120, v56, v57 offset1:1
	ds_write2_b32 v121, v58, v59 offset1:1
	ds_write2_b32 v122, v60, v61 offset1:1
	ds_write2_b32 v123, v62, v63 offset1:1
	ds_write2_b32 v124, v64, v65 offset1:1
	s_waitcnt lgkmcnt(0)
	ds_read2_b32 v[126:127], v105 offset1:33
	s_waitcnt lgkmcnt(0)
	v_cvt_pk_bf16_f32 v126, v126, v127
	ds_read2_b32 v[128:129], v105 offset0:66 offset1:99
	s_waitcnt lgkmcnt(0)
	v_cvt_pk_bf16_f32 v127, v128, v129
	ds_read2_b32 v[128:129], v105 offset0:132 offset1:165
	v_lshl_add_u64 v[132:133], s[2:3], 0, v[106:107]
	s_waitcnt lgkmcnt(0)
	v_cvt_pk_bf16_f32 v128, v128, v129
	ds_read2_b32 v[130:131], v105 offset0:198 offset1:231
	s_waitcnt lgkmcnt(0)
	v_cvt_pk_bf16_f32 v129, v130, v131
	v_lshl_add_u64 v[132:133], v[132:133], 0, v[98:99]
	ds_read2_b32 v[130:131], v105 offset0:8 offset1:41
	global_store_dwordx4 v[132:133], v[126:129], off sc1
	v_lshl_add_u64 v[132:133], s[2:3], 0, v[108:109]
	v_lshl_add_u64 v[132:133], v[132:133], 0, v[98:99]
	s_waitcnt lgkmcnt(0)
	v_cvt_pk_bf16_f32 v126, v130, v131
	ds_read2_b32 v[128:129], v105 offset0:74 offset1:107
	s_waitcnt lgkmcnt(0)
	v_cvt_pk_bf16_f32 v127, v128, v129
	ds_read2_b32 v[128:129], v105 offset0:140 offset1:173
	s_waitcnt lgkmcnt(0)
	v_cvt_pk_bf16_f32 v128, v128, v129
	ds_read2_b32 v[130:131], v105 offset0:206 offset1:239
	s_waitcnt lgkmcnt(0)
	v_cvt_pk_bf16_f32 v129, v130, v131
	ds_read2_b32 v[130:131], v105 offset0:16 offset1:49
	global_store_dwordx4 v[132:133], v[126:129], off sc1
	v_add_co_u32_e32 v134, vcc, s25, v132
	s_waitcnt lgkmcnt(0)
	v_cvt_pk_bf16_f32 v126, v130, v131
	ds_read2_b32 v[128:129], v105 offset0:82 offset1:115
	s_waitcnt lgkmcnt(0)
	v_cvt_pk_bf16_f32 v127, v128, v129
	ds_read2_b32 v[128:129], v105 offset0:148 offset1:181
	s_waitcnt lgkmcnt(0)
	v_cvt_pk_bf16_f32 v128, v128, v129
	ds_read2_b32 v[130:131], v105 offset0:214 offset1:247
	s_waitcnt lgkmcnt(0)
	v_cvt_pk_bf16_f32 v129, v130, v131
	v_addc_co_u32_e32 v135, vcc, 0, v133, vcc
	ds_read2_b32 v[130:131], v105 offset0:24 offset1:57
	global_store_dwordx4 v[134:135], v[126:129], off sc1
	v_add_co_u32_e32 v132, vcc, 0x56000, v132
	s_waitcnt lgkmcnt(0)
	v_cvt_pk_bf16_f32 v126, v130, v131
	ds_read2_b32 v[128:129], v105 offset0:90 offset1:123
	s_waitcnt lgkmcnt(0)
	v_cvt_pk_bf16_f32 v127, v128, v129
	ds_read2_b32 v[128:129], v105 offset0:156 offset1:189
	v_addc_co_u32_e32 v133, vcc, 0, v133, vcc
	s_waitcnt lgkmcnt(0)
	v_cvt_pk_bf16_f32 v128, v128, v129
	ds_read2_b32 v[130:131], v105 offset0:222 offset1:255
	s_waitcnt lgkmcnt(0)
	v_cvt_pk_bf16_f32 v129, v130, v131
	global_store_dwordx4 v[132:133], v[126:129], off sc1
	s_waitcnt lgkmcnt(0)
	s_add_i32 s27, s22, s26
	s_cmpk_gt_i32 s27, 0x3fff
	s_cbranch_scc1 .LBB0_1145

; #define LAS __attribute__((address_space(3)))
; __device__ __forceinline__ unsigned cvt_pk_bf16(float lo, float hi) { unsigned r; asm volatile("v_cvt_pk_bf16_f32 %0, %1, %2" : "=v"(r) : "v"(lo), "v"(hi)); return r; }
; #define LDS_WAIT() asm volatile("s_waitcnt lgkmcnt(0)" ::: "memory")
; __device__ __forceinline__ unsigned cvt_pk_bf16(float lo, float hi) { unsigned r; asm volatile("v_cvt_pk_bf16_f32 %0, %1, %2" : "=v"(r) : "v"(lo), "v"(hi)); return r; }
; template <bool NT = true> __device__ __forceinline__ void tr_finish(const TrDesc& d, const f32x4 (&v)[8], LAS float* scr, int lane) {
;     const int c = lane & 7;
;     f32x4 g0 = {1.f, 1.f, 1.f, 1.f}, g1 = {1.f, 1.f, 1.f, 1.f};
;     if (d.gain) { g0 = *(const f32x4*)(d.gain + 8 * c); g1 = *(const f32x4*)(d.gain + 8 * c + 4); }
; #pragma unroll
;     for (int i = 0; i < 8; ++i) { LAS float* w = scr + (8 * i + (lane >> 3)) * 33 + 4 * c; w[0] = v[i].x; w[1] = v[i].y; w[2] = v[i].z; w[3] = v[i].w; }
;     LDS_WAIT(); asm volatile("" ::: "memory");
; #pragma unroll
;     for (int j = 0; j < 4; ++j) { const int n = (lane >> 3) + 8 * j; const LAS float* s = scr + (8 * c) * 33 + n;
;         u32x4 o; o.x = cvt_pk_bf16(s[0 * 33] * g0.x, s[1 * 33] * g0.y); o.y = cvt_pk_bf16(s[2 * 33] * g0.z, s[3 * 33] * g0.w); o.z = cvt_pk_bf16(s[4 * 33] * g1.x, s[5 * 33] * g1.y); o.w = cvt_pk_bf16(s[6 * 33] * g1.z, s[7 * 33] * g1.w);
;         if (NT) __builtin_nontemporal_store(o, (u32x4*)(d.dst + (size_t)n * d.K + 8 * c)); else *(u32x4*)(d.dst + (size_t)n * d.K + 8 * c) = o; }
;     LDS_WAIT(); asm volatile("" ::: "memory");
; }
; template <class F, bool NT = true> __device__ __forceinline__ void tr_run(F item, int first, int step, int n, LAS float* scr, int lane) {
;     ...
;     for (int it = first; it < n; it += 3 * step) {
;         const bool h1 = it + step < n, h2 = it + 2 * step < n, h3 = it + 3 * step < n, h4 = it + 4 * step < n;
;         if (h2) { dc = item(it + 2 * step); tr_load<NT>(dc, vc, lane); }
;         tr_finish<NT>(da, va, scr, lane);
;         if (h3) { da = item(it + 3 * step); tr_load<NT>(da, va, lane); }
;         if (h1) tr_finish<NT>(db, vb, scr, lane);
;         if (h4) { db = item(it + 4 * step); tr_load<NT>(db, vb, lane); }
;         if (h2) tr_finish<NT>(dc, vc, scr, lane);
;     }
.LBB0_1149:
	ds_write2_b32 v110, v66, v67 offset1:1
	ds_write2_b32 v110, v68, v69 offset0:2 offset1:3
	ds_write2_b32 v111, v70, v71 offset1:1
	ds_write2_b32 v112, v72, v73 offset1:1
	ds_write2_b32 v113, v74, v75 offset1:1
	ds_write2_b32 v114, v76, v77 offset1:1
	ds_write2_b32 v115, v78, v79 offset1:1
	ds_write2_b32 v116, v80, v81 offset1:1
	ds_write2_b32 v117, v82, v83 offset1:1
	ds_write2_b32 v118, v84, v85 offset1:1
	ds_write2_b32 v119, v86, v87 offset1:1
	ds_write2_b32 v120, v88, v89 offset1:1
	ds_write2_b32 v121, v90, v91 offset1:1
	ds_write2_b32 v122, v92, v93 offset1:1
	ds_write2_b32 v123, v94, v95 offset1:1
	ds_write2_b32 v124, v96, v97 offset1:1
	s_waitcnt lgkmcnt(0)
	ds_read2_b32 v[112:113], v105 offset1:33
	s_waitcnt lgkmcnt(0)
	v_cvt_pk_bf16_f32 v112, v112, v113
	ds_read2_b32 v[114:115], v105 offset0:66 offset1:99
	s_waitcnt lgkmcnt(0)
	v_cvt_pk_bf16_f32 v113, v114, v115
	ds_read2_b32 v[114:115], v105 offset0:132 offset1:165
	v_lshl_add_u64 v[118:119], s[0:1], 0, v[106:107]
	s_waitcnt lgkmcnt(0)
	v_cvt_pk_bf16_f32 v114, v114, v115
	ds_read2_b32 v[116:117], v105 offset0:198 offset1:231
	s_waitcnt lgkmcnt(0)
	v_cvt_pk_bf16_f32 v115, v116, v117
	v_lshl_add_u64 v[118:119], v[118:119], 0, v[98:99]
	ds_read2_b32 v[116:117], v105 offset0:8 offset1:41
	global_store_dwordx4 v[118:119], v[112:115], off sc1
	v_lshl_add_u64 v[118:119], s[0:1], 0, v[108:109]
	v_lshl_add_u64 v[118:119], v[118:119], 0, v[98:99]
	s_waitcnt lgkmcnt(0)
	v_cvt_pk_bf16_f32 v112, v116, v117
	ds_read2_b32 v[114:115], v105 offset0:74 offset1:107
	s_waitcnt lgkmcnt(0)
	v_cvt_pk_bf16_f32 v113, v114, v115
	ds_read2_b32 v[114:115], v105 offset0:140 offset1:173
	s_waitcnt lgkmcnt(0)
	v_cvt_pk_bf16_f32 v114, v114, v115
	ds_read2_b32 v[116:117], v105 offset0:206 offset1:239
	s_waitcnt lgkmcnt(0)
	v_cvt_pk_bf16_f32 v115, v116, v117
	ds_read2_b32 v[116:117], v105 offset0:16 offset1:49
	global_store_dwordx4 v[118:119], v[112:115], off sc1
	v_add_co_u32_e32 v120, vcc, s25, v118
	s_waitcnt lgkmcnt(0)
	v_cvt_pk_bf16_f32 v112, v116, v117
	ds_read2_b32 v[114:115], v105 offset0:82 offset1:115
	s_waitcnt lgkmcnt(0)
	v_cvt_pk_bf16_f32 v113, v114, v115
	ds_read2_b32 v[114:115], v105 offset0:148 offset1:181
	s_waitcnt lgkmcnt(0)
	v_cvt_pk_bf16_f32 v114, v114, v115
	ds_read2_b32 v[116:117], v105 offset0:214 offset1:247
	s_waitcnt lgkmcnt(0)
	v_cvt_pk_bf16_f32 v115, v116, v117
	v_addc_co_u32_e32 v121, vcc, 0, v119, vcc
	ds_read2_b32 v[116:117], v105 offset0:24 offset1:57
	global_store_dwordx4 v[120:121], v[112:115], off sc1
	v_add_co_u32_e32 v118, vcc, 0x56000, v118
	s_waitcnt lgkmcnt(0)
	v_cvt_pk_bf16_f32 v112, v116, v117
	ds_read2_b32 v[114:115], v105 offset0:90 offset1:123
	s_waitcnt lgkmcnt(0)
	v_cvt_pk_bf16_f32 v113, v114, v115
	ds_read2_b32 v[114:115], v105 offset0:156 offset1:189
	v_addc_co_u32_e32 v119, vcc, 0, v119, vcc
	s_waitcnt lgkmcnt(0)
	v_cvt_pk_bf16_f32 v114, v114, v115
	ds_read2_b32 v[116:117], v105 offset0:222 offset1:255
	s_waitcnt lgkmcnt(0)
	v_cvt_pk_bf16_f32 v115, v116, v117
	global_store_dwordx4 v[118:119], v[112:115], off sc1
	s_waitcnt lgkmcnt(0)
	s_branch .LBB0_1139

; #define LAS __attribute__((address_space(3)))
; __device__ __forceinline__ unsigned cvt_pk_bf16(float lo, float hi) { unsigned r; asm volatile("v_cvt_pk_bf16_f32 %0, %1, %2" : "=v"(r) : "v"(lo), "v"(hi)); return r; }
; #define LDS_WAIT() asm volatile("s_waitcnt lgkmcnt(0)" ::: "memory")
; __device__ __forceinline__ unsigned cvt_pk_bf16(float lo, float hi) { unsigned r; asm volatile("v_cvt_pk_bf16_f32 %0, %1, %2" : "=v"(r) : "v"(lo), "v"(hi)); return r; }
; template <bool NT = true> __device__ __forceinline__ void tr_finish(const TrDesc& d, const f32x4 (&v)[8], LAS float* scr, int lane) {
;     const int c = lane & 7;
;     f32x4 g0 = {1.f, 1.f, 1.f, 1.f}, g1 = {1.f, 1.f, 1.f, 1.f};
;     if (d.gain) { g0 = *(const f32x4*)(d.gain + 8 * c); g1 = *(const f32x4*)(d.gain + 8 * c + 4); }
; #pragma unroll
;     for (int i = 0; i < 8; ++i) { LAS float* w = scr + (8 * i + (lane >> 3)) * 33 + 4 * c; w[0] = v[i].x; w[1] = v[i].y; w[2] = v[i].z; w[3] = v[i].w; }
;     LDS_WAIT(); asm volatile("" ::: "memory");
; #pragma unroll
;     for (int j = 0; j < 4; ++j) { const int n = (lane >> 3) + 8 * j; const LAS float* s = scr + (8 * c) * 33 + n;
;         u32x4 o; o.x = cvt_pk_bf16(s[0 * 33] * g0.x, s[1 * 33] * g0.y); o.y = cvt_pk_bf16(s[2 * 33] * g0.z, s[3 * 33] * g0.w); o.z = cvt_pk_bf16(s[4 * 33] * g1.x, s[5 * 33] * g1.y); o.w = cvt_pk_bf16(s[6 * 33] * g1.z, s[7 * 33] * g1.w);
;         if (NT) __builtin_nontemporal_store(o, (u32x4*)(d.dst + (size_t)n * d.K + 8 * c)); else *(u32x4*)(d.dst + (size_t)n * d.K + 8 * c) = o; }
;     LDS_WAIT(); asm volatile("" ::: "memory");
; }
; template <class F, bool NT = true> __device__ __forceinline__ void tr_run(F item, int first, int step, int n, LAS float* scr, int lane) {
;     ...
;     for (int it = first; it < n; it += 3 * step) {
;         const bool h1 = it + step < n, h2 = it + 2 * step < n, h3 = it + 3 * step < n, h4 = it + 4 * step < n;
;         if (h2) { dc = item(it + 2 * step); tr_load<NT>(dc, vc, lane); }
;         tr_finish<NT>(da, va, scr, lane);
;         if (h3) { da = item(it + 3 * step); tr_load<NT>(da, va, lane); }
;         if (h1) tr_finish<NT>(db, vb, scr, lane);
;         if (h4) { db = item(it + 4 * step); tr_load<NT>(db, vb, lane); }
;         if (h2) tr_finish<NT>(dc, vc, scr, lane);
;     }
.LBB0_1159:
	v_add_u32_e32 v110, 0x420, v105
	v_add_u32_e32 v111, 0x428, v105
	v_add_u32_e32 v112, 0x840, v105
	v_add_u32_e32 v113, 0x848, v105
	v_add_u32_e32 v114, 0xc60, v105
	v_add_u32_e32 v115, 0xc68, v105
	v_add_u32_e32 v116, 0x1080, v105
	v_add_u32_e32 v117, 0x1088, v105
	v_add_u32_e32 v118, 0x14a0, v105
	v_add_u32_e32 v119, 0x14a8, v105
	v_add_u32_e32 v120, 0x18c0, v105
	v_add_u32_e32 v121, 0x18c8, v105
	v_add_u32_e32 v122, 0x1ce0, v105
	v_add_u32_e32 v123, 0x1ce8, v105
	s_waitcnt vmcnt(7)
	ds_write2_b32 v105, v2, v3 offset1:1
	ds_write2_b32 v105, v4, v5 offset0:2 offset1:3
	s_waitcnt vmcnt(6)
	ds_write2_b32 v110, v6, v7 offset1:1
	ds_write2_b32 v111, v8, v9 offset1:1
	s_waitcnt vmcnt(5)
	ds_write2_b32 v112, v10, v11 offset1:1
	ds_write2_b32 v113, v12, v13 offset1:1
	s_waitcnt vmcnt(4)
	ds_write2_b32 v114, v14, v15 offset1:1
	ds_write2_b32 v115, v16, v17 offset1:1
	s_waitcnt vmcnt(3)
	ds_write2_b32 v116, v18, v19 offset1:1
	ds_write2_b32 v117, v20, v21 offset1:1
	s_waitcnt vmcnt(2)
	ds_write2_b32 v118, v22, v23 offset1:1
	ds_write2_b32 v119, v24, v25 offset1:1
	s_waitcnt vmcnt(1)
	ds_write2_b32 v120, v26, v27 offset1:1
	ds_write2_b32 v121, v28, v29 offset1:1
	s_waitcnt vmcnt(0)
	ds_write2_b32 v122, v30, v31 offset1:1
	ds_write2_b32 v123, v32, v33 offset1:1
	s_waitcnt lgkmcnt(0)
	ds_read2_b32 v[124:125], v1 offset1:33
	s_waitcnt lgkmcnt(0)
	v_cvt_pk_bf16_f32 v124, v124, v125
	ds_read2_b32 v[126:127], v1 offset0:66 offset1:99
	s_waitcnt lgkmcnt(0)
	v_cvt_pk_bf16_f32 v125, v126, v127
	ds_read2_b32 v[126:127], v1 offset0:132 offset1:165
	v_lshl_add_u64 v[130:131], s[4:5], 0, v[106:107]
	v_lshlrev_b32_e32 v98, 1, v104
	s_waitcnt lgkmcnt(0)
	v_cvt_pk_bf16_f32 v126, v126, v127
	ds_read2_b32 v[128:129], v1 offset0:198 offset1:231
	s_waitcnt lgkmcnt(0)
	v_cvt_pk_bf16_f32 v127, v128, v129
	v_lshl_add_u64 v[130:131], v[130:131], 0, v[98:99]
	ds_read2_b32 v[128:129], v1 offset0:8 offset1:41
	global_store_dwordx4 v[130:131], v[124:127], off sc1
	v_lshl_add_u64 v[130:131], s[4:5], 0, v[108:109]
	v_lshl_add_u64 v[130:131], v[130:131], 0, v[98:99]
	s_waitcnt lgkmcnt(0)
	v_cvt_pk_bf16_f32 v124, v128, v129
	ds_read2_b32 v[126:127], v1 offset0:74 offset1:107
	s_waitcnt lgkmcnt(0)
	v_cvt_pk_bf16_f32 v125, v126, v127
	ds_read2_b32 v[126:127], v1 offset0:140 offset1:173
	s_waitcnt lgkmcnt(0)
	v_cvt_pk_bf16_f32 v126, v126, v127
	ds_read2_b32 v[128:129], v1 offset0:206 offset1:239
	s_waitcnt lgkmcnt(0)
	v_cvt_pk_bf16_f32 v127, v128, v129
	ds_read2_b32 v[128:129], v1 offset0:16 offset1:49
	global_store_dwordx4 v[130:131], v[124:127], off sc1
	v_add_co_u32_e32 v132, vcc, s22, v130
	s_waitcnt lgkmcnt(0)
	v_cvt_pk_bf16_f32 v124, v128, v129
	ds_read2_b32 v[126:127], v1 offset0:82 offset1:115
	s_waitcnt lgkmcnt(0)
	v_cvt_pk_bf16_f32 v125, v126, v127
	ds_read2_b32 v[126:127], v1 offset0:148 offset1:181
	s_waitcnt lgkmcnt(0)
	v_cvt_pk_bf16_f32 v126, v126, v127
	ds_read2_b32 v[128:129], v1 offset0:214 offset1:247
	s_waitcnt lgkmcnt(0)
	v_cvt_pk_bf16_f32 v127, v128, v129
	v_addc_co_u32_e32 v133, vcc, 0, v131, vcc
	ds_read2_b32 v[128:129], v1 offset0:24 offset1:57
	global_store_dwordx4 v[132:133], v[124:127], off sc1
	v_add_co_u32_e32 v130, vcc, 0x56000, v130
	s_waitcnt lgkmcnt(0)
	v_cvt_pk_bf16_f32 v124, v128, v129
	ds_read2_b32 v[126:127], v1 offset0:90 offset1:123
	s_waitcnt lgkmcnt(0)
	v_cvt_pk_bf16_f32 v125, v126, v127
	ds_read2_b32 v[126:127], v1 offset0:156 offset1:189
	v_addc_co_u32_e32 v131, vcc, 0, v131, vcc
	s_waitcnt lgkmcnt(0)
	v_cvt_pk_bf16_f32 v126, v126, v127
	ds_read2_b32 v[128:129], v1 offset0:222 offset1:255
	s_waitcnt lgkmcnt(0)
	v_cvt_pk_bf16_f32 v127, v128, v129
	global_store_dwordx4 v[130:131], v[124:127], off sc1
	s_waitcnt lgkmcnt(0)
	s_add_i32 s24, s20, s23
	s_cmpk_gt_i32 s24, 0x3fff
	s_cbranch_scc0 .LBB0_1163
	s_add_i32 s24, s23, s74
	s_cmpk_gt_i32 s24, 0x3fff
	s_cbranch_scc0 .LBB0_1164

; #define LAS __attribute__((address_space(3)))
; __device__ __forceinline__ unsigned cvt_pk_bf16(float lo, float hi) { unsigned r; asm volatile("v_cvt_pk_bf16_f32 %0, %1, %2" : "=v"(r) : "v"(lo), "v"(hi)); return r; }
; #define LDS_WAIT() asm volatile("s_waitcnt lgkmcnt(0)" ::: "memory")
; __device__ __forceinline__ unsigned cvt_pk_bf16(float lo, float hi) { unsigned r; asm volatile("v_cvt_pk_bf16_f32 %0, %1, %2" : "=v"(r) : "v"(lo), "v"(hi)); return r; }
; template <bool NT = true> __device__ __forceinline__ void tr_finish(const TrDesc& d, const f32x4 (&v)[8], LAS float* scr, int lane) {
;     const int c = lane & 7;
;     f32x4 g0 = {1.f, 1.f, 1.f, 1.f}, g1 = {1.f, 1.f, 1.f, 1.f};
;     if (d.gain) { g0 = *(const f32x4*)(d.gain + 8 * c); g1 = *(const f32x4*)(d.gain + 8 * c + 4); }
; #pragma unroll
;     for (int i = 0; i < 8; ++i) { LAS float* w = scr + (8 * i + (lane >> 3)) * 33 + 4 * c; w[0] = v[i].x; w[1] = v[i].y; w[2] = v[i].z; w[3] = v[i].w; }
;     LDS_WAIT(); asm volatile("" ::: "memory");
; #pragma unroll
;     for (int j = 0; j < 4; ++j) { const int n = (lane >> 3) + 8 * j; const LAS float* s = scr + (8 * c) * 33 + n;
;         u32x4 o; o.x = cvt_pk_bf16(s[0 * 33] * g0.x, s[1 * 33] * g0.y); o.y = cvt_pk_bf16(s[2 * 33] * g0.z, s[3 * 33] * g0.w); o.z = cvt_pk_bf16(s[4 * 33] * g1.x, s[5 * 33] * g1.y); o.w = cvt_pk_bf16(s[6 * 33] * g1.z, s[7 * 33] * g1.w);
;         if (NT) __builtin_nontemporal_store(o, (u32x4*)(d.dst + (size_t)n * d.K + 8 * c)); else *(u32x4*)(d.dst + (size_t)n * d.K + 8 * c) = o; }
;     LDS_WAIT(); asm volatile("" ::: "memory");
; }
; template <class F, bool NT = true> __device__ __forceinline__ void tr_run(F item, int first, int step, int n, LAS float* scr, int lane) {
;     ...
;     for (int it = first; it < n; it += 3 * step) {
;         const bool h1 = it + step < n, h2 = it + 2 * step < n, h3 = it + 3 * step < n, h4 = it + 4 * step < n;
;         if (h2) { dc = item(it + 2 * step); tr_load<NT>(dc, vc, lane); }
;         tr_finish<NT>(da, va, scr, lane);
;         if (h3) { da = item(it + 3 * step); tr_load<NT>(da, va, lane); }
;         if (h1) tr_finish<NT>(db, vb, scr, lane);
;         if (h4) { db = item(it + 4 * step); tr_load<NT>(db, vb, lane); }
;         if (h2) tr_finish<NT>(dc, vc, scr, lane);
;     }
.LBB0_1164:
	ds_write2_b32 v105, v34, v35 offset1:1
	ds_write2_b32 v105, v36, v37 offset0:2 offset1:3
	ds_write2_b32 v110, v38, v39 offset1:1
	ds_write2_b32 v111, v40, v41 offset1:1
	ds_write2_b32 v112, v42, v43 offset1:1
	ds_write2_b32 v113, v44, v45 offset1:1
	ds_write2_b32 v114, v46, v47 offset1:1
	ds_write2_b32 v115, v48, v49 offset1:1
	ds_write2_b32 v116, v50, v51 offset1:1
	ds_write2_b32 v117, v52, v53 offset1:1
	ds_write2_b32 v118, v54, v55 offset1:1
	ds_write2_b32 v119, v56, v57 offset1:1
	ds_write2_b32 v120, v58, v59 offset1:1
	ds_write2_b32 v121, v60, v61 offset1:1
	ds_write2_b32 v122, v62, v63 offset1:1
	ds_write2_b32 v123, v64, v65 offset1:1
	s_waitcnt lgkmcnt(0)
	ds_read2_b32 v[124:125], v1 offset1:33
	s_waitcnt lgkmcnt(0)
	v_cvt_pk_bf16_f32 v124, v124, v125
	ds_read2_b32 v[126:127], v1 offset0:66 offset1:99
	s_waitcnt lgkmcnt(0)
	v_cvt_pk_bf16_f32 v125, v126, v127
	ds_read2_b32 v[126:127], v1 offset0:132 offset1:165
	v_lshl_add_u64 v[130:131], s[2:3], 0, v[106:107]
	s_waitcnt lgkmcnt(0)
	v_cvt_pk_bf16_f32 v126, v126, v127
	ds_read2_b32 v[128:129], v1 offset0:198 offset1:231
	s_waitcnt lgkmcnt(0)
	v_cvt_pk_bf16_f32 v127, v128, v129
	v_lshl_add_u64 v[130:131], v[130:131], 0, v[98:99]
	ds_read2_b32 v[128:129], v1 offset0:8 offset1:41
	global_store_dwordx4 v[130:131], v[124:127], off sc1
	v_lshl_add_u64 v[130:131], s[2:3], 0, v[108:109]
	v_lshl_add_u64 v[130:131], v[130:131], 0, v[98:99]
	s_waitcnt lgkmcnt(0)
	v_cvt_pk_bf16_f32 v124, v128, v129
	ds_read2_b32 v[126:127], v1 offset0:74 offset1:107
	s_waitcnt lgkmcnt(0)
	v_cvt_pk_bf16_f32 v125, v126, v127
	ds_read2_b32 v[126:127], v1 offset0:140 offset1:173
	s_waitcnt lgkmcnt(0)
	v_cvt_pk_bf16_f32 v126, v126, v127
	ds_read2_b32 v[128:129], v1 offset0:206 offset1:239
	s_waitcnt lgkmcnt(0)
	v_cvt_pk_bf16_f32 v127, v128, v129
	ds_read2_b32 v[128:129], v1 offset0:16 offset1:49
	global_store_dwordx4 v[130:131], v[124:127], off sc1
	v_add_co_u32_e32 v132, vcc, s22, v130
	s_waitcnt lgkmcnt(0)
	v_cvt_pk_bf16_f32 v124, v128, v129
	ds_read2_b32 v[126:127], v1 offset0:82 offset1:115
	s_waitcnt lgkmcnt(0)
	v_cvt_pk_bf16_f32 v125, v126, v127
	ds_read2_b32 v[126:127], v1 offset0:148 offset1:181
	s_waitcnt lgkmcnt(0)
	v_cvt_pk_bf16_f32 v126, v126, v127
	ds_read2_b32 v[128:129], v1 offset0:214 offset1:247
	s_waitcnt lgkmcnt(0)
	v_cvt_pk_bf16_f32 v127, v128, v129
	v_addc_co_u32_e32 v133, vcc, 0, v131, vcc
	ds_read2_b32 v[128:129], v1 offset0:24 offset1:57
	global_store_dwordx4 v[132:133], v[124:127], off sc1
	v_add_co_u32_e32 v130, vcc, 0x56000, v130
	s_waitcnt lgkmcnt(0)
	v_cvt_pk_bf16_f32 v124, v128, v129
	ds_read2_b32 v[126:127], v1 offset0:90 offset1:123
	s_waitcnt lgkmcnt(0)
	v_cvt_pk_bf16_f32 v125, v126, v127
	ds_read2_b32 v[126:127], v1 offset0:156 offset1:189
	v_addc_co_u32_e32 v131, vcc, 0, v131, vcc
	s_waitcnt lgkmcnt(0)
	v_cvt_pk_bf16_f32 v126, v126, v127
	ds_read2_b32 v[128:129], v1 offset0:222 offset1:255
	s_waitcnt lgkmcnt(0)
	v_cvt_pk_bf16_f32 v127, v128, v129
	global_store_dwordx4 v[130:131], v[124:127], off sc1
	s_waitcnt lgkmcnt(0)
	s_add_i32 s23, s21, s23
	s_cmpk_gt_i32 s23, 0x3fff
	s_cbranch_scc1 .LBB0_1162

; #define LAS __attribute__((address_space(3)))
; __device__ __forceinline__ unsigned cvt_pk_bf16(float lo, float hi) { unsigned r; asm volatile("v_cvt_pk_bf16_f32 %0, %1, %2" : "=v"(r) : "v"(lo), "v"(hi)); return r; }
; #define LDS_WAIT() asm volatile("s_waitcnt lgkmcnt(0)" ::: "memory")
; __device__ __forceinline__ unsigned cvt_pk_bf16(float lo, float hi) { unsigned r; asm volatile("v_cvt_pk_bf16_f32 %0, %1, %2" : "=v"(r) : "v"(lo), "v"(hi)); return r; }
; template <bool NT = true> __device__ __forceinline__ void tr_finish(const TrDesc& d, const f32x4 (&v)[8], LAS float* scr, int lane) {
;     const int c = lane & 7;
;     f32x4 g0 = {1.f, 1.f, 1.f, 1.f}, g1 = {1.f, 1.f, 1.f, 1.f};
;     if (d.gain) { g0 = *(const f32x4*)(d.gain + 8 * c); g1 = *(const f32x4*)(d.gain + 8 * c + 4); }
; #pragma unroll
;     for (int i = 0; i < 8; ++i) { LAS float* w = scr + (8 * i + (lane >> 3)) * 33 + 4 * c; w[0] = v[i].x; w[1] = v[i].y; w[2] = v[i].z; w[3] = v[i].w; }
;     LDS_WAIT(); asm volatile("" ::: "memory");
; #pragma unroll
;     for (int j = 0; j < 4; ++j) { const int n = (lane >> 3) + 8 * j; const LAS float* s = scr + (8 * c) * 33 + n;
;         u32x4 o; o.x = cvt_pk_bf16(s[0 * 33] * g0.x, s[1 * 33] * g0.y); o.y = cvt_pk_bf16(s[2 * 33] * g0.z, s[3 * 33] * g0.w); o.z = cvt_pk_bf16(s[4 * 33] * g1.x, s[5 * 33] * g1.y); o.w = cvt_pk_bf16(s[6 * 33] * g1.z, s[7 * 33] * g1.w);
;         if (NT) __builtin_nontemporal_store(o, (u32x4*)(d.dst + (size_t)n * d.K + 8 * c)); else *(u32x4*)(d.dst + (size_t)n * d.K + 8 * c) = o; }
;     LDS_WAIT(); asm volatile("" ::: "memory");
; }
; template <class F, bool NT = true> __device__ __forceinline__ void tr_run(F item, int first, int step, int n, LAS float* scr, int lane) {
;     ...
;     for (int it = first; it < n; it += 3 * step) {
;         const bool h1 = it + step < n, h2 = it + 2 * step < n, h3 = it + 3 * step < n, h4 = it + 4 * step < n;
;         if (h2) { dc = item(it + 2 * step); tr_load<NT>(dc, vc, lane); }
;         tr_finish<NT>(da, va, scr, lane);
;         if (h3) { da = item(it + 3 * step); tr_load<NT>(da, va, lane); }
;         if (h1) tr_finish<NT>(db, vb, scr, lane);
;         if (h4) { db = item(it + 4 * step); tr_load<NT>(db, vb, lane); }
;         if (h2) tr_finish<NT>(dc, vc, scr, lane);
;     }
.LBB0_1166:
	ds_write2_b32 v105, v66, v67 offset1:1
	ds_write2_b32 v105, v68, v69 offset0:2 offset1:3
	ds_write2_b32 v110, v70, v71 offset1:1
	ds_write2_b32 v111, v72, v73 offset1:1
	ds_write2_b32 v112, v74, v75 offset1:1
	ds_write2_b32 v113, v76, v77 offset1:1
	ds_write2_b32 v114, v78, v79 offset1:1
	ds_write2_b32 v115, v80, v81 offset1:1
	ds_write2_b32 v116, v82, v83 offset1:1
	ds_write2_b32 v117, v84, v85 offset1:1
	ds_write2_b32 v118, v86, v87 offset1:1
	ds_write2_b32 v119, v88, v89 offset1:1
	ds_write2_b32 v120, v90, v91 offset1:1
	ds_write2_b32 v121, v92, v93 offset1:1
	ds_write2_b32 v122, v94, v95 offset1:1
	ds_write2_b32 v123, v96, v97 offset1:1
	s_waitcnt lgkmcnt(0)
	ds_read2_b32 v[110:111], v1 offset1:33
	s_waitcnt lgkmcnt(0)
	v_cvt_pk_bf16_f32 v110, v110, v111
	ds_read2_b32 v[112:113], v1 offset0:66 offset1:99
	s_waitcnt lgkmcnt(0)
	v_cvt_pk_bf16_f32 v111, v112, v113
	ds_read2_b32 v[112:113], v1 offset0:132 offset1:165
	v_lshl_add_u64 v[116:117], s[0:1], 0, v[106:107]
	s_waitcnt lgkmcnt(0)
	v_cvt_pk_bf16_f32 v112, v112, v113
	ds_read2_b32 v[114:115], v1 offset0:198 offset1:231
	s_waitcnt lgkmcnt(0)
	v_cvt_pk_bf16_f32 v113, v114, v115
	v_lshl_add_u64 v[116:117], v[116:117], 0, v[98:99]
	ds_read2_b32 v[114:115], v1 offset0:8 offset1:41
	global_store_dwordx4 v[116:117], v[110:113], off sc1
	v_lshl_add_u64 v[116:117], s[0:1], 0, v[108:109]
	v_lshl_add_u64 v[116:117], v[116:117], 0, v[98:99]
	s_waitcnt lgkmcnt(0)
	v_cvt_pk_bf16_f32 v110, v114, v115
	ds_read2_b32 v[112:113], v1 offset0:74 offset1:107
	s_waitcnt lgkmcnt(0)
	v_cvt_pk_bf16_f32 v111, v112, v113
	ds_read2_b32 v[112:113], v1 offset0:140 offset1:173
	s_waitcnt lgkmcnt(0)
	v_cvt_pk_bf16_f32 v112, v112, v113
	ds_read2_b32 v[114:115], v1 offset0:206 offset1:239
	s_waitcnt lgkmcnt(0)
	v_cvt_pk_bf16_f32 v113, v114, v115
	ds_read2_b32 v[114:115], v1 offset0:16 offset1:49
	global_store_dwordx4 v[116:117], v[110:113], off sc1
	v_add_co_u32_e32 v118, vcc, s22, v116
	s_waitcnt lgkmcnt(0)
	v_cvt_pk_bf16_f32 v110, v114, v115
	ds_read2_b32 v[112:113], v1 offset0:82 offset1:115
	s_waitcnt lgkmcnt(0)
	v_cvt_pk_bf16_f32 v111, v112, v113
	ds_read2_b32 v[112:113], v1 offset0:148 offset1:181
	s_waitcnt lgkmcnt(0)
	v_cvt_pk_bf16_f32 v112, v112, v113
	ds_read2_b32 v[114:115], v1 offset0:214 offset1:247
	s_waitcnt lgkmcnt(0)
	v_cvt_pk_bf16_f32 v113, v114, v115
	v_addc_co_u32_e32 v119, vcc, 0, v117, vcc
	ds_read2_b32 v[114:115], v1 offset0:24 offset1:57
	global_store_dwordx4 v[118:119], v[110:113], off sc1
	v_add_co_u32_e32 v116, vcc, 0x56000, v116
	s_waitcnt lgkmcnt(0)
	v_cvt_pk_bf16_f32 v110, v114, v115
	ds_read2_b32 v[112:113], v1 offset0:90 offset1:123
	s_waitcnt lgkmcnt(0)
	v_cvt_pk_bf16_f32 v111, v112, v113
	ds_read2_b32 v[112:113], v1 offset0:156 offset1:189
	v_addc_co_u32_e32 v117, vcc, 0, v117, vcc
	s_waitcnt lgkmcnt(0)
	v_cvt_pk_bf16_f32 v112, v112, v113
	ds_read2_b32 v[114:115], v1 offset0:222 offset1:255
	s_waitcnt lgkmcnt(0)
	v_cvt_pk_bf16_f32 v113, v114, v115
	global_store_dwordx4 v[116:117], v[110:113], off sc1
	s_waitcnt lgkmcnt(0)
	s_branch .LBB0_1156

; #define LAS __attribute__((address_space(3)))
; __device__ __forceinline__ unsigned cvt_pk_bf16(float lo, float hi) { unsigned r; asm volatile("v_cvt_pk_bf16_f32 %0, %1, %2" : "=v"(r) : "v"(lo), "v"(hi)); return r; }
; #define LDS_WAIT() asm volatile("s_waitcnt lgkmcnt(0)" ::: "memory")
; __device__ __forceinline__ unsigned cvt_pk_bf16(float lo, float hi) { unsigned r; asm volatile("v_cvt_pk_bf16_f32 %0, %1, %2" : "=v"(r) : "v"(lo), "v"(hi)); return r; }
; template <bool NT = true> __device__ __forceinline__ void tr_finish(const TrDesc& d, const f32x4 (&v)[8], LAS float* scr, int lane) {
;     const int c = lane & 7;
;     f32x4 g0 = {1.f, 1.f, 1.f, 1.f}, g1 = {1.f, 1.f, 1.f, 1.f};
;     if (d.gain) { g0 = *(const f32x4*)(d.gain + 8 * c); g1 = *(const f32x4*)(d.gain + 8 * c + 4); }
; #pragma unroll
;     for (int i = 0; i < 8; ++i) { LAS float* w = scr + (8 * i + (lane >> 3)) * 33 + 4 * c; w[0] = v[i].x; w[1] = v[i].y; w[2] = v[i].z; w[3] = v[i].w; }
;     LDS_WAIT(); asm volatile("" ::: "memory");
; #pragma unroll
;     for (int j = 0; j < 4; ++j) { const int n = (lane >> 3) + 8 * j; const LAS float* s = scr + (8 * c) * 33 + n;
;         u32x4 o; o.x = cvt_pk_bf16(s[0 * 33] * g0.x, s[1 * 33] * g0.y); o.y = cvt_pk_bf16(s[2 * 33] * g0.z, s[3 * 33] * g0.w); o.z = cvt_pk_bf16(s[4 * 33] * g1.x, s[5 * 33] * g1.y); o.w = cvt_pk_bf16(s[6 * 33] * g1.z, s[7 * 33] * g1.w);
;         if (NT) __builtin_nontemporal_store(o, (u32x4*)(d.dst + (size_t)n * d.K + 8 * c)); else *(u32x4*)(d.dst + (size_t)n * d.K + 8 * c) = o; }
;     LDS_WAIT(); asm volatile("" ::: "memory");
; }
; __device__ __forceinline__ void tail1_convert(const Params& p, LAS unsigned char* lds, int tw, int ntw, int wave, int lane) {
;     Tail1Item ti{p.ffn_w_down + (size_t)DFF * DM, (bf16_t*)(p.ws + WS_WDN1)};
;     tr_run(ti, tw, ntw, P0_I_DN1, (LAS float*)(lds + wave * 8704), lane);
.LBB0_1697:
	v_add_u32_e32 v111, 0x420, v110
	v_add_u32_e32 v112, 0x428, v110
	v_add_u32_e32 v113, 0x840, v110
	v_add_u32_e32 v114, 0x848, v110
	v_add_u32_e32 v115, 0xc60, v110
	v_add_u32_e32 v116, 0xc68, v110
	v_add_u32_e32 v117, 0x1080, v110
	v_add_u32_e32 v118, 0x1088, v110
	v_add_u32_e32 v119, 0x14a0, v110
	v_add_u32_e32 v120, 0x14a8, v110
	v_add_u32_e32 v121, 0x18c0, v110
	v_add_u32_e32 v122, 0x18c8, v110
	v_add_u32_e32 v123, 0x1ce0, v110
	v_add_u32_e32 v124, 0x1ce8, v110
	s_waitcnt vmcnt(7)
	ds_write2_b32 v110, v2, v3 offset1:1
	ds_write2_b32 v110, v4, v5 offset0:2 offset1:3
	s_waitcnt vmcnt(6)
	ds_write2_b32 v111, v6, v7 offset1:1
	ds_write2_b32 v112, v8, v9 offset1:1
	s_waitcnt vmcnt(5)
	ds_write2_b32 v113, v10, v11 offset1:1
	ds_write2_b32 v114, v12, v13 offset1:1
	s_waitcnt vmcnt(4)
	ds_write2_b32 v115, v14, v15 offset1:1
	ds_write2_b32 v116, v16, v17 offset1:1
	s_waitcnt vmcnt(3)
	ds_write2_b32 v117, v18, v19 offset1:1
	ds_write2_b32 v118, v20, v21 offset1:1
	s_waitcnt vmcnt(2)
	ds_write2_b32 v119, v22, v23 offset1:1
	ds_write2_b32 v120, v24, v25 offset1:1
	s_waitcnt vmcnt(1)
	ds_write2_b32 v121, v26, v27 offset1:1
	ds_write2_b32 v122, v28, v29 offset1:1
	s_waitcnt vmcnt(0)
	ds_write2_b32 v123, v30, v31 offset1:1
	ds_write2_b32 v124, v32, v33 offset1:1
	s_waitcnt lgkmcnt(0)
	ds_read2_b32 v[126:127], v105 offset1:33
	s_waitcnt lgkmcnt(0)
	v_cvt_pk_bf16_f32 v126, v126, v127
	ds_read2_b32 v[128:129], v105 offset0:66 offset1:99
	s_waitcnt lgkmcnt(0)
	v_cvt_pk_bf16_f32 v127, v128, v129
	ds_read2_b32 v[128:129], v105 offset0:132 offset1:165
	v_lshl_add_u64 v[132:133], s[4:5], 0, v[106:107]
	v_lshlrev_b32_e32 v98, 1, v104
	s_waitcnt lgkmcnt(0)
	v_cvt_pk_bf16_f32 v128, v128, v129
	ds_read2_b32 v[130:131], v105 offset0:198 offset1:231
	s_waitcnt lgkmcnt(0)
	v_cvt_pk_bf16_f32 v129, v130, v131
	v_lshl_add_u64 v[132:133], v[132:133], 0, v[98:99]
	ds_read2_b32 v[130:131], v105 offset0:8 offset1:41
	global_store_dwordx4 v[132:133], v[126:129], off sc1
	v_lshl_add_u64 v[132:133], s[4:5], 0, v[108:109]
	v_lshl_add_u64 v[132:133], v[132:133], 0, v[98:99]
	s_waitcnt lgkmcnt(0)
	v_cvt_pk_bf16_f32 v126, v130, v131
	ds_read2_b32 v[128:129], v105 offset0:74 offset1:107
	s_waitcnt lgkmcnt(0)
	v_cvt_pk_bf16_f32 v127, v128, v129
	ds_read2_b32 v[128:129], v105 offset0:140 offset1:173
	s_waitcnt lgkmcnt(0)
	v_cvt_pk_bf16_f32 v128, v128, v129
	ds_read2_b32 v[130:131], v105 offset0:206 offset1:239
	s_waitcnt lgkmcnt(0)
	v_cvt_pk_bf16_f32 v129, v130, v131
	ds_read2_b32 v[130:131], v105 offset0:16 offset1:49
	global_store_dwordx4 v[132:133], v[126:129], off sc1
	v_add_co_u32_e32 v134, vcc, s25, v132
	s_waitcnt lgkmcnt(0)
	v_cvt_pk_bf16_f32 v126, v130, v131
	ds_read2_b32 v[128:129], v105 offset0:82 offset1:115
	s_waitcnt lgkmcnt(0)
	v_cvt_pk_bf16_f32 v127, v128, v129
	ds_read2_b32 v[128:129], v105 offset0:148 offset1:181
	s_waitcnt lgkmcnt(0)
	v_cvt_pk_bf16_f32 v128, v128, v129
	ds_read2_b32 v[130:131], v105 offset0:214 offset1:247
	s_waitcnt lgkmcnt(0)
	v_cvt_pk_bf16_f32 v129, v130, v131
	v_addc_co_u32_e32 v135, vcc, 0, v133, vcc
	ds_read2_b32 v[130:131], v105 offset0:24 offset1:57
	global_store_dwordx4 v[134:135], v[126:129], off sc1
	v_add_co_u32_e32 v132, vcc, 0x56000, v132
	s_waitcnt lgkmcnt(0)
	v_cvt_pk_bf16_f32 v126, v130, v131
	ds_read2_b32 v[128:129], v105 offset0:90 offset1:123
	s_waitcnt lgkmcnt(0)
	v_cvt_pk_bf16_f32 v127, v128, v129
	ds_read2_b32 v[128:129], v105 offset0:156 offset1:189
	v_addc_co_u32_e32 v133, vcc, 0, v133, vcc
	s_waitcnt lgkmcnt(0)
	v_cvt_pk_bf16_f32 v128, v128, v129
	ds_read2_b32 v[130:131], v105 offset0:222 offset1:255
	s_waitcnt lgkmcnt(0)
	v_cvt_pk_bf16_f32 v129, v130, v131
	global_store_dwordx4 v[132:133], v[126:129], off sc1
	s_waitcnt lgkmcnt(0)
	s_add_i32 s27, s21, s26
	s_cmpk_gt_i32 s27, 0x15ff
	s_cbranch_scc0 .LBB0_1701
	s_add_i32 s27, s23, s26
	s_cmpk_gt_i32 s27, 0x15ff
	s_cbranch_scc0 .LBB0_1702

; #define LAS __attribute__((address_space(3)))
; __device__ __forceinline__ unsigned cvt_pk_bf16(float lo, float hi) { unsigned r; asm volatile("v_cvt_pk_bf16_f32 %0, %1, %2" : "=v"(r) : "v"(lo), "v"(hi)); return r; }
; #define LDS_WAIT() asm volatile("s_waitcnt lgkmcnt(0)" ::: "memory")
; __device__ __forceinline__ unsigned cvt_pk_bf16(float lo, float hi) { unsigned r; asm volatile("v_cvt_pk_bf16_f32 %0, %1, %2" : "=v"(r) : "v"(lo), "v"(hi)); return r; }
; template <bool NT = true> __device__ __forceinline__ void tr_finish(const TrDesc& d, const f32x4 (&v)[8], LAS float* scr, int lane) {
;     const int c = lane & 7;
;     f32x4 g0 = {1.f, 1.f, 1.f, 1.f}, g1 = {1.f, 1.f, 1.f, 1.f};
;     if (d.gain) { g0 = *(const f32x4*)(d.gain + 8 * c); g1 = *(const f32x4*)(d.gain + 8 * c + 4); }
; #pragma unroll
;     for (int i = 0; i < 8; ++i) { LAS float* w = scr + (8 * i + (lane >> 3)) * 33 + 4 * c; w[0] = v[i].x; w[1] = v[i].y; w[2] = v[i].z; w[3] = v[i].w; }
;     LDS_WAIT(); asm volatile("" ::: "memory");
; #pragma unroll
;     for (int j = 0; j < 4; ++j) { const int n = (lane >> 3) + 8 * j; const LAS float* s = scr + (8 * c) * 33 + n;
;         u32x4 o; o.x = cvt_pk_bf16(s[0 * 33] * g0.x, s[1 * 33] * g0.y); o.y = cvt_pk_bf16(s[2 * 33] * g0.z, s[3 * 33] * g0.w); o.z = cvt_pk_bf16(s[4 * 33] * g1.x, s[5 * 33] * g1.y); o.w = cvt_pk_bf16(s[6 * 33] * g1.z, s[7 * 33] * g1.w);
;         if (NT) __builtin_nontemporal_store(o, (u32x4*)(d.dst + (size_t)n * d.K + 8 * c)); else *(u32x4*)(d.dst + (size_t)n * d.K + 8 * c) = o; }
;     LDS_WAIT(); asm volatile("" ::: "memory");
; }
; __device__ __forceinline__ void tail1_convert(const Params& p, LAS unsigned char* lds, int tw, int ntw, int wave, int lane) {
;     Tail1Item ti{p.ffn_w_down + (size_t)DFF * DM, (bf16_t*)(p.ws + WS_WDN1)};
;     tr_run(ti, tw, ntw, P0_I_DN1, (LAS float*)(lds + wave * 8704), lane);
.LBB0_1702:
	ds_write2_b32 v110, v34, v35 offset1:1
	ds_write2_b32 v110, v36, v37 offset0:2 offset1:3
	ds_write2_b32 v111, v38, v39 offset1:1
	ds_write2_b32 v112, v40, v41 offset1:1
	ds_write2_b32 v113, v42, v43 offset1:1
	ds_write2_b32 v114, v44, v45 offset1:1
	ds_write2_b32 v115, v46, v47 offset1:1
	ds_write2_b32 v116, v48, v49 offset1:1
	ds_write2_b32 v117, v50, v51 offset1:1
	ds_write2_b32 v118, v52, v53 offset1:1
	ds_write2_b32 v119, v54, v55 offset1:1
	ds_write2_b32 v120, v56, v57 offset1:1
	ds_write2_b32 v121, v58, v59 offset1:1
	ds_write2_b32 v122, v60, v61 offset1:1
	ds_write2_b32 v123, v62, v63 offset1:1
	ds_write2_b32 v124, v64, v65 offset1:1
	s_waitcnt lgkmcnt(0)
	ds_read2_b32 v[126:127], v105 offset1:33
	s_waitcnt lgkmcnt(0)
	v_cvt_pk_bf16_f32 v126, v126, v127
	ds_read2_b32 v[128:129], v105 offset0:66 offset1:99
	s_waitcnt lgkmcnt(0)
	v_cvt_pk_bf16_f32 v127, v128, v129
	ds_read2_b32 v[128:129], v105 offset0:132 offset1:165
	v_lshl_add_u64 v[132:133], s[2:3], 0, v[106:107]
	s_waitcnt lgkmcnt(0)
	v_cvt_pk_bf16_f32 v128, v128, v129
	ds_read2_b32 v[130:131], v105 offset0:198 offset1:231
	s_waitcnt lgkmcnt(0)
	v_cvt_pk_bf16_f32 v129, v130, v131
	v_lshl_add_u64 v[132:133], v[132:133], 0, v[98:99]
	ds_read2_b32 v[130:131], v105 offset0:8 offset1:41
	global_store_dwordx4 v[132:133], v[126:129], off sc1
	v_lshl_add_u64 v[132:133], s[2:3], 0, v[108:109]
	v_lshl_add_u64 v[132:133], v[132:133], 0, v[98:99]
	s_waitcnt lgkmcnt(0)
	v_cvt_pk_bf16_f32 v126, v130, v131
	ds_read2_b32 v[128:129], v105 offset0:74 offset1:107
	s_waitcnt lgkmcnt(0)
	v_cvt_pk_bf16_f32 v127, v128, v129
	ds_read2_b32 v[128:129], v105 offset0:140 offset1:173
	s_waitcnt lgkmcnt(0)
	v_cvt_pk_bf16_f32 v128, v128, v129
	ds_read2_b32 v[130:131], v105 offset0:206 offset1:239
	s_waitcnt lgkmcnt(0)
	v_cvt_pk_bf16_f32 v129, v130, v131
	ds_read2_b32 v[130:131], v105 offset0:16 offset1:49
	global_store_dwordx4 v[132:133], v[126:129], off sc1
	v_add_co_u32_e32 v134, vcc, s25, v132
	s_waitcnt lgkmcnt(0)
	v_cvt_pk_bf16_f32 v126, v130, v131
	ds_read2_b32 v[128:129], v105 offset0:82 offset1:115
	s_waitcnt lgkmcnt(0)
	v_cvt_pk_bf16_f32 v127, v128, v129
	ds_read2_b32 v[128:129], v105 offset0:148 offset1:181
	s_waitcnt lgkmcnt(0)
	v_cvt_pk_bf16_f32 v128, v128, v129
	ds_read2_b32 v[130:131], v105 offset0:214 offset1:247
	s_waitcnt lgkmcnt(0)
	v_cvt_pk_bf16_f32 v129, v130, v131
	v_addc_co_u32_e32 v135, vcc, 0, v133, vcc
	ds_read2_b32 v[130:131], v105 offset0:24 offset1:57
	global_store_dwordx4 v[134:135], v[126:129], off sc1
	v_add_co_u32_e32 v132, vcc, 0x56000, v132
	s_waitcnt lgkmcnt(0)
	v_cvt_pk_bf16_f32 v126, v130, v131
	ds_read2_b32 v[128:129], v105 offset0:90 offset1:123
	s_waitcnt lgkmcnt(0)
	v_cvt_pk_bf16_f32 v127, v128, v129
	ds_read2_b32 v[128:129], v105 offset0:156 offset1:189
	v_addc_co_u32_e32 v133, vcc, 0, v133, vcc
	s_waitcnt lgkmcnt(0)
	v_cvt_pk_bf16_f32 v128, v128, v129
	ds_read2_b32 v[130:131], v105 offset0:222 offset1:255
	s_waitcnt lgkmcnt(0)
	v_cvt_pk_bf16_f32 v129, v130, v131
	global_store_dwordx4 v[132:133], v[126:129], off sc1
	s_waitcnt lgkmcnt(0)
	s_add_i32 s27, s22, s26
	s_cmpk_gt_i32 s27, 0x15ff
	s_cbranch_scc1 .LBB0_1700

; #define LAS __attribute__((address_space(3)))
; __device__ __forceinline__ unsigned cvt_pk_bf16(float lo, float hi) { unsigned r; asm volatile("v_cvt_pk_bf16_f32 %0, %1, %2" : "=v"(r) : "v"(lo), "v"(hi)); return r; }
; #define LDS_WAIT() asm volatile("s_waitcnt lgkmcnt(0)" ::: "memory")
; __device__ __forceinline__ unsigned cvt_pk_bf16(float lo, float hi) { unsigned r; asm volatile("v_cvt_pk_bf16_f32 %0, %1, %2" : "=v"(r) : "v"(lo), "v"(hi)); return r; }
; template <bool NT = true> __device__ __forceinline__ void tr_finish(const TrDesc& d, const f32x4 (&v)[8], LAS float* scr, int lane) {
;     const int c = lane & 7;
;     f32x4 g0 = {1.f, 1.f, 1.f, 1.f}, g1 = {1.f, 1.f, 1.f, 1.f};
;     if (d.gain) { g0 = *(const f32x4*)(d.gain + 8 * c); g1 = *(const f32x4*)(d.gain + 8 * c + 4); }
; #pragma unroll
;     for (int i = 0; i < 8; ++i) { LAS float* w = scr + (8 * i + (lane >> 3)) * 33 + 4 * c; w[0] = v[i].x; w[1] = v[i].y; w[2] = v[i].z; w[3] = v[i].w; }
;     LDS_WAIT(); asm volatile("" ::: "memory");
; #pragma unroll
;     for (int j = 0; j < 4; ++j) { const int n = (lane >> 3) + 8 * j; const LAS float* s = scr + (8 * c) * 33 + n;
;         u32x4 o; o.x = cvt_pk_bf16(s[0 * 33] * g0.x, s[1 * 33] * g0.y); o.y = cvt_pk_bf16(s[2 * 33] * g0.z, s[3 * 33] * g0.w); o.z = cvt_pk_bf16(s[4 * 33] * g1.x, s[5 * 33] * g1.y); o.w = cvt_pk_bf16(s[6 * 33] * g1.z, s[7 * 33] * g1.w);
;         if (NT) __builtin_nontemporal_store(o, (u32x4*)(d.dst + (size_t)n * d.K + 8 * c)); else *(u32x4*)(d.dst + (size_t)n * d.K + 8 * c) = o; }
;     LDS_WAIT(); asm volatile("" ::: "memory");
; }
; __device__ __forceinline__ void tail1_convert(const Params& p, LAS unsigned char* lds, int tw, int ntw, int wave, int lane) {
;     Tail1Item ti{p.ffn_w_down + (size_t)DFF * DM, (bf16_t*)(p.ws + WS_WDN1)};
;     tr_run(ti, tw, ntw, P0_I_DN1, (LAS float*)(lds + wave * 8704), lane);
.LBB0_1714:
	v_add_u32_e32 v110, 0x420, v105
	v_add_u32_e32 v111, 0x428, v105
	v_add_u32_e32 v112, 0x840, v105
	v_add_u32_e32 v113, 0x848, v105
	v_add_u32_e32 v114, 0xc60, v105
	v_add_u32_e32 v115, 0xc68, v105
	v_add_u32_e32 v116, 0x1080, v105
	v_add_u32_e32 v117, 0x1088, v105
	v_add_u32_e32 v118, 0x14a0, v105
	v_add_u32_e32 v119, 0x14a8, v105
	v_add_u32_e32 v120, 0x18c0, v105
	v_add_u32_e32 v121, 0x18c8, v105
	v_add_u32_e32 v122, 0x1ce0, v105
	v_add_u32_e32 v123, 0x1ce8, v105
	s_waitcnt vmcnt(7)
	ds_write2_b32 v105, v2, v3 offset1:1
	ds_write2_b32 v105, v4, v5 offset0:2 offset1:3
	s_waitcnt vmcnt(6)
	ds_write2_b32 v110, v6, v7 offset1:1
	ds_write2_b32 v111, v8, v9 offset1:1
	s_waitcnt vmcnt(5)
	ds_write2_b32 v112, v10, v11 offset1:1
	ds_write2_b32 v113, v12, v13 offset1:1
	s_waitcnt vmcnt(4)
	ds_write2_b32 v114, v14, v15 offset1:1
	ds_write2_b32 v115, v16, v17 offset1:1
	s_waitcnt vmcnt(3)
	ds_write2_b32 v116, v18, v19 offset1:1
	ds_write2_b32 v117, v20, v21 offset1:1
	s_waitcnt vmcnt(2)
	ds_write2_b32 v118, v22, v23 offset1:1
	ds_write2_b32 v119, v24, v25 offset1:1
	s_waitcnt vmcnt(1)
	ds_write2_b32 v120, v26, v27 offset1:1
	ds_write2_b32 v121, v28, v29 offset1:1
	s_waitcnt vmcnt(0)
	ds_write2_b32 v122, v30, v31 offset1:1
	ds_write2_b32 v123, v32, v33 offset1:1
	s_waitcnt lgkmcnt(0)
	ds_read2_b32 v[124:125], v1 offset1:33
	s_waitcnt lgkmcnt(0)
	v_cvt_pk_bf16_f32 v124, v124, v125
	ds_read2_b32 v[126:127], v1 offset0:66 offset1:99
	s_waitcnt lgkmcnt(0)
	v_cvt_pk_bf16_f32 v125, v126, v127
	ds_read2_b32 v[126:127], v1 offset0:132 offset1:165
	v_lshl_add_u64 v[130:131], s[4:5], 0, v[106:107]
	v_lshlrev_b32_e32 v98, 1, v104
	s_waitcnt lgkmcnt(0)
	v_cvt_pk_bf16_f32 v126, v126, v127
	ds_read2_b32 v[128:129], v1 offset0:198 offset1:231
	s_waitcnt lgkmcnt(0)
	v_cvt_pk_bf16_f32 v127, v128, v129
	v_lshl_add_u64 v[130:131], v[130:131], 0, v[98:99]
	ds_read2_b32 v[128:129], v1 offset0:8 offset1:41
	global_store_dwordx4 v[130:131], v[124:127], off sc1
	v_lshl_add_u64 v[130:131], s[4:5], 0, v[108:109]
	v_lshl_add_u64 v[130:131], v[130:131], 0, v[98:99]
	s_waitcnt lgkmcnt(0)
	v_cvt_pk_bf16_f32 v124, v128, v129
	ds_read2_b32 v[126:127], v1 offset0:74 offset1:107
	s_waitcnt lgkmcnt(0)
	v_cvt_pk_bf16_f32 v125, v126, v127
	ds_read2_b32 v[126:127], v1 offset0:140 offset1:173
	s_waitcnt lgkmcnt(0)
	v_cvt_pk_bf16_f32 v126, v126, v127
	ds_read2_b32 v[128:129], v1 offset0:206 offset1:239
	s_waitcnt lgkmcnt(0)
	v_cvt_pk_bf16_f32 v127, v128, v129
	ds_read2_b32 v[128:129], v1 offset0:16 offset1:49
	global_store_dwordx4 v[130:131], v[124:127], off sc1
	v_add_co_u32_e32 v132, vcc, s22, v130
	s_waitcnt lgkmcnt(0)
	v_cvt_pk_bf16_f32 v124, v128, v129
	ds_read2_b32 v[126:127], v1 offset0:82 offset1:115
	s_waitcnt lgkmcnt(0)
	v_cvt_pk_bf16_f32 v125, v126, v127
	ds_read2_b32 v[126:127], v1 offset0:148 offset1:181
	s_waitcnt lgkmcnt(0)
	v_cvt_pk_bf16_f32 v126, v126, v127
	ds_read2_b32 v[128:129], v1 offset0:214 offset1:247
	s_waitcnt lgkmcnt(0)
	v_cvt_pk_bf16_f32 v127, v128, v129
	v_addc_co_u32_e32 v133, vcc, 0, v131, vcc
	ds_read2_b32 v[128:129], v1 offset0:24 offset1:57
	global_store_dwordx4 v[132:133], v[124:127], off sc1
	v_add_co_u32_e32 v130, vcc, 0x56000, v130
	s_waitcnt lgkmcnt(0)
	v_cvt_pk_bf16_f32 v124, v128, v129
	ds_read2_b32 v[126:127], v1 offset0:90 offset1:123
	s_waitcnt lgkmcnt(0)
	v_cvt_pk_bf16_f32 v125, v126, v127
	ds_read2_b32 v[126:127], v1 offset0:156 offset1:189
	v_addc_co_u32_e32 v131, vcc, 0, v131, vcc
	s_waitcnt lgkmcnt(0)
	v_cvt_pk_bf16_f32 v126, v126, v127
	ds_read2_b32 v[128:129], v1 offset0:222 offset1:255
	s_waitcnt lgkmcnt(0)
	v_cvt_pk_bf16_f32 v127, v128, v129
	global_store_dwordx4 v[130:131], v[124:127], off sc1
	s_waitcnt lgkmcnt(0)
	s_add_i32 s24, s20, s23
	s_cmpk_gt_i32 s24, 0x15ff
	s_cbranch_scc0 .LBB0_1718
	s_add_i32 s24, s23, s74
	s_cmpk_gt_i32 s24, 0x15ff
	s_cbranch_scc0 .LBB0_1719

; #define LAS __attribute__((address_space(3)))
; __device__ __forceinline__ unsigned cvt_pk_bf16(float lo, float hi) { unsigned r; asm volatile("v_cvt_pk_bf16_f32 %0, %1, %2" : "=v"(r) : "v"(lo), "v"(hi)); return r; }
; #define LDS_WAIT() asm volatile("s_waitcnt lgkmcnt(0)" ::: "memory")
; __device__ __forceinline__ unsigned cvt_pk_bf16(float lo, float hi) { unsigned r; asm volatile("v_cvt_pk_bf16_f32 %0, %1, %2" : "=v"(r) : "v"(lo), "v"(hi)); return r; }
; template <bool NT = true> __device__ __forceinline__ void tr_finish(const TrDesc& d, const f32x4 (&v)[8], LAS float* scr, int lane) {
;     const int c = lane & 7;
;     f32x4 g0 = {1.f, 1.f, 1.f, 1.f}, g1 = {1.f, 1.f, 1.f, 1.f};
;     if (d.gain) { g0 = *(const f32x4*)(d.gain + 8 * c); g1 = *(const f32x4*)(d.gain + 8 * c + 4); }
; #pragma unroll
;     for (int i = 0; i < 8; ++i) { LAS float* w = scr + (8 * i + (lane >> 3)) * 33 + 4 * c; w[0] = v[i].x; w[1] = v[i].y; w[2] = v[i].z; w[3] = v[i].w; }
;     LDS_WAIT(); asm volatile("" ::: "memory");
; #pragma unroll
;     for (int j = 0; j < 4; ++j) { const int n = (lane >> 3) + 8 * j; const LAS float* s = scr + (8 * c) * 33 + n;
;         u32x4 o; o.x = cvt_pk_bf16(s[0 * 33] * g0.x, s[1 * 33] * g0.y); o.y = cvt_pk_bf16(s[2 * 33] * g0.z, s[3 * 33] * g0.w); o.z = cvt_pk_bf16(s[4 * 33] * g1.x, s[5 * 33] * g1.y); o.w = cvt_pk_bf16(s[6 * 33] * g1.z, s[7 * 33] * g1.w);
;         if (NT) __builtin_nontemporal_store(o, (u32x4*)(d.dst + (size_t)n * d.K + 8 * c)); else *(u32x4*)(d.dst + (size_t)n * d.K + 8 * c) = o; }
;     LDS_WAIT(); asm volatile("" ::: "memory");
; }
; __device__ __forceinline__ void tail1_convert(const Params& p, LAS unsigned char* lds, int tw, int ntw, int wave, int lane) {
;     Tail1Item ti{p.ffn_w_down + (size_t)DFF * DM, (bf16_t*)(p.ws + WS_WDN1)};
;     tr_run(ti, tw, ntw, P0_I_DN1, (LAS float*)(lds + wave * 8704), lane);
.LBB0_1719:
	ds_write2_b32 v105, v34, v35 offset1:1
	ds_write2_b32 v105, v36, v37 offset0:2 offset1:3
	ds_write2_b32 v110, v38, v39 offset1:1
	ds_write2_b32 v111, v40, v41 offset1:1
	ds_write2_b32 v112, v42, v43 offset1:1
	ds_write2_b32 v113, v44, v45 offset1:1
	ds_write2_b32 v114, v46, v47 offset1:1
	ds_write2_b32 v115, v48, v49 offset1:1
	ds_write2_b32 v116, v50, v51 offset1:1
	ds_write2_b32 v117, v52, v53 offset1:1
	ds_write2_b32 v118, v54, v55 offset1:1
	ds_write2_b32 v119, v56, v57 offset1:1
	ds_write2_b32 v120, v58, v59 offset1:1
	ds_write2_b32 v121, v60, v61 offset1:1
	ds_write2_b32 v122, v62, v63 offset1:1
	ds_write2_b32 v123, v64, v65 offset1:1
	s_waitcnt lgkmcnt(0)
	ds_read2_b32 v[124:125], v1 offset1:33
	s_waitcnt lgkmcnt(0)
	v_cvt_pk_bf16_f32 v124, v124, v125
	ds_read2_b32 v[126:127], v1 offset0:66 offset1:99
	s_waitcnt lgkmcnt(0)
	v_cvt_pk_bf16_f32 v125, v126, v127
	ds_read2_b32 v[126:127], v1 offset0:132 offset1:165
	v_lshl_add_u64 v[130:131], s[2:3], 0, v[106:107]
	s_waitcnt lgkmcnt(0)
	v_cvt_pk_bf16_f32 v126, v126, v127
	ds_read2_b32 v[128:129], v1 offset0:198 offset1:231
	s_waitcnt lgkmcnt(0)
	v_cvt_pk_bf16_f32 v127, v128, v129
	v_lshl_add_u64 v[130:131], v[130:131], 0, v[98:99]
	ds_read2_b32 v[128:129], v1 offset0:8 offset1:41
	global_store_dwordx4 v[130:131], v[124:127], off sc1
	v_lshl_add_u64 v[130:131], s[2:3], 0, v[108:109]
	v_lshl_add_u64 v[130:131], v[130:131], 0, v[98:99]
	s_waitcnt lgkmcnt(0)
	v_cvt_pk_bf16_f32 v124, v128, v129
	ds_read2_b32 v[126:127], v1 offset0:74 offset1:107
	s_waitcnt lgkmcnt(0)
	v_cvt_pk_bf16_f32 v125, v126, v127
	ds_read2_b32 v[126:127], v1 offset0:140 offset1:173
	s_waitcnt lgkmcnt(0)
	v_cvt_pk_bf16_f32 v126, v126, v127
	ds_read2_b32 v[128:129], v1 offset0:206 offset1:239
	s_waitcnt lgkmcnt(0)
	v_cvt_pk_bf16_f32 v127, v128, v129
	ds_read2_b32 v[128:129], v1 offset0:16 offset1:49
	global_store_dwordx4 v[130:131], v[124:127], off sc1
	v_add_co_u32_e32 v132, vcc, s22, v130
	s_waitcnt lgkmcnt(0)
	v_cvt_pk_bf16_f32 v124, v128, v129
	ds_read2_b32 v[126:127], v1 offset0:82 offset1:115
	s_waitcnt lgkmcnt(0)
	v_cvt_pk_bf16_f32 v125, v126, v127
	ds_read2_b32 v[126:127], v1 offset0:148 offset1:181
	s_waitcnt lgkmcnt(0)
	v_cvt_pk_bf16_f32 v126, v126, v127
	ds_read2_b32 v[128:129], v1 offset0:214 offset1:247
	s_waitcnt lgkmcnt(0)
	v_cvt_pk_bf16_f32 v127, v128, v129
	v_addc_co_u32_e32 v133, vcc, 0, v131, vcc
	ds_read2_b32 v[128:129], v1 offset0:24 offset1:57
	global_store_dwordx4 v[132:133], v[124:127], off sc1
	v_add_co_u32_e32 v130, vcc, 0x56000, v130
	s_waitcnt lgkmcnt(0)
	v_cvt_pk_bf16_f32 v124, v128, v129
	ds_read2_b32 v[126:127], v1 offset0:90 offset1:123
	s_waitcnt lgkmcnt(0)
	v_cvt_pk_bf16_f32 v125, v126, v127
	ds_read2_b32 v[126:127], v1 offset0:156 offset1:189
	v_addc_co_u32_e32 v131, vcc, 0, v131, vcc
	s_waitcnt lgkmcnt(0)
	v_cvt_pk_bf16_f32 v126, v126, v127
	ds_read2_b32 v[128:129], v1 offset0:222 offset1:255
	s_waitcnt lgkmcnt(0)
	v_cvt_pk_bf16_f32 v127, v128, v129
	global_store_dwordx4 v[130:131], v[124:127], off sc1
	s_waitcnt lgkmcnt(0)
	s_add_i32 s23, s21, s23
	s_cmpk_gt_i32 s23, 0x15ff
	s_cbranch_scc1 .LBB0_1717
